# GEMM k-loops: per-k-block 64-bit VALU address adds replaced by SGPR-base loads (wave-uniform base advanced by SALU + constant 32-bit lane offsets)
# baseline (speedup 1.0000x reference)
; DI int TID8() { int t = threadIdx.x; asm volatile("" : "+v"(t)); return t; }
; DI void gemm8_accum(f32x4 (&acc)[8][4], const bf16_t* a, size_t lda, const bf16_t* b, size_t ldb, int nkb, bf16_t* L,
;                     const bool pre, const bf16_t* an, size_t ldan, const bf16_t* bn, size_t ldbn) {
;   const int tid = TID8(), lane = tid & 63, w = tid >> 6;
;   const int wm = w >> 2, wn = w & 3;
;   const int lrow = tid >> 3, lch = tid & 7;
;   u32x4 ra[4], rb[4];
;   unsigned offa[4], offb[4];
; #pragma unroll
;   for (int i = 0; i < 4; ++i) {
;     offa[i] = (unsigned)(lrow + 64 * i) * (unsigned)lda + (unsigned)(lch * 8);
;     offb[i] = (unsigned)(lrow + 64 * i) * (unsigned)ldb + (unsigned)(lch * 8);
;   }
;   if (!pre) {
;     g8_load1o(ra, a, offa);
;     g8_load1o(rb, b, offb);
;     __syncthreads();
;     g8_store(L, ra, rb, lrow, lch);
;   }
;   g8_load1o(ra, a + 64, offa);
;   g8_load1o(rb, b + 64, offb);
; DI void zero_acc8(f32x4 (&acc)[8][4]) {
; #pragma unroll
;   for (int i = 0; i < 8; ++i)
; #pragma unroll
;     for (int j = 0; j < 4; ++j) acc[i][j] = f32x4{0.f, 0.f, 0.f, 0.f};
; }
.LBB0_133:
	v_lshlrev_b64 v[40:41], 1, v[168:169]
	v_lshlrev_b64 v[42:43], 1, v[166:167]
	v_lshl_add_u64 v[6:7], s[2:3], 0, v[40:41]
	v_lshl_add_u64 v[8:9], s[2:3], 0, v[42:43]
	v_lshlrev_b64 v[44:45], 1, v[0:1]
	global_load_dwordx4 v[18:21], v[6:7], off offset:128
	global_load_dwordx4 v[26:29], v[8:9], off offset:128
	v_lshl_add_u64 v[10:11], s[2:3], 0, v[44:45]
	global_load_dwordx4 v[22:25], v[4:5], off offset:128
	global_load_dwordx4 v[30:33], v[10:11], off offset:128
	global_load_dwordx4 v[6:9], v[2:3], off offset:128
	v_lshl_add_u64 v[2:3], s[0:1], 0, v[40:41]
	s_nop 1
	global_load_dwordx4 v[2:5], v[2:3], off offset:128
	v_lshl_add_u64 v[10:11], s[0:1], 0, v[42:43]
	v_lshl_add_u64 v[14:15], s[0:1], 0, v[44:45]
	global_load_dwordx4 v[10:13], v[10:11], off offset:128
	s_nop 0
	global_load_dwordx4 v[14:17], v[14:15], off offset:128
	v_bfe_u32 v39, v36, 4, 2
	v_lshrrev_b32_e32 v46, 1, v36
	v_bitop3_b32 v46, v46, v39, 7 bitop3:0x6c
	v_lshlrev_b32_e32 v191, 3, v46
	v_lshlrev_b32_e32 v46, 5, v36
	v_bfe_u32 v47, v36, 1, 3
	v_and_b32_e32 v46, 0xffffe000, v46
	v_lshlrev_b32_e32 v36, 6, v36
	s_movk_i32 s0, 0x3c0
	v_and_or_b32 v46, v36, s0, v46
	s_add_u32 s0, s39, s13
	v_add_u32_e32 v34, v35, v34
	v_mov_b32_e32 v35, v1
	s_addc_u32 s1, s40, 0
	v_lshlrev_b64 v[34:35], 1, v[34:35]
	v_lshl_add_u64 v[170:171], s[0:1], 0, v[44:45]
	v_lshl_add_u64 v[172:173], s[0:1], 0, v[42:43]
	v_lshl_add_u64 v[174:175], s[0:1], 0, v[40:41]
	v_lshl_add_u64 v[176:177], s[0:1], 0, v[34:35]
	s_add_i32 s0, s38, s11
	s_add_i32 s0, s0, s12
	s_lshl_b32 s0, s0, 19
	v_readlane_b32 s1, v253, 57
	s_add_u32 s0, s1, s0
	v_readlane_b32 s1, v253, 58
	s_addc_u32 s1, s1, 0
	v_and_b32_e32 v36, 0x33c0, v36
	v_bitop3_b32 v39, v39, v47, 4 bitop3:0x36
	v_lshlrev_b32_e32 v189, 1, v38
	v_lshlrev_b32_e32 v190, 1, v37
	v_lshl_add_u64 v[184:185], s[0:1], 0, v[34:35]
	v_mov_b32_e32 v34, 0
	v_lshlrev_b32_e32 v188, 3, v39
	v_add3_u32 v163, 0, v189, v190
	v_lshl_add_u64 v[178:179], s[0:1], 0, v[44:45]
	v_lshl_add_u64 v[180:181], s[0:1], 0, v[42:43]
	v_lshl_add_u64 v[182:183], s[0:1], 0, v[40:41]
	s_mov_b64 s[0:1], 0
	s_mov_b32 s2, 0
	v_lshlrev_b32_e32 v187, 1, v46
	v_lshlrev_b32_e32 v186, 1, v36
	v_mov_b32_e32 v35, v34
	v_mov_b32_e32 v36, v34
	v_mov_b32_e32 v37, v34
	v_mov_b32_e32 v38, v34
	v_mov_b32_e32 v39, v34
	v_mov_b32_e32 v40, v34
	v_mov_b32_e32 v41, v34
	v_mov_b32_e32 v42, v34
	v_mov_b32_e32 v43, v34
	v_mov_b32_e32 v44, v34
	v_mov_b32_e32 v45, v34
	v_mov_b32_e32 v46, v34
	v_mov_b32_e32 v47, v34
	v_mov_b32_e32 v48, v34
	v_mov_b32_e32 v49, v34
	v_mov_b32_e32 v50, v34
	v_mov_b32_e32 v51, v34
	v_mov_b32_e32 v52, v34
	v_mov_b32_e32 v53, v34
	v_mov_b32_e32 v54, v34
	v_mov_b32_e32 v55, v34
	v_mov_b32_e32 v56, v34
	v_mov_b32_e32 v57, v34
	v_mov_b32_e32 v58, v34
	v_mov_b32_e32 v59, v34
	v_mov_b32_e32 v60, v34
	v_mov_b32_e32 v61, v34
	v_mov_b32_e32 v62, v34
	v_mov_b32_e32 v63, v34
	v_mov_b32_e32 v64, v34
	v_mov_b32_e32 v65, v34
	v_mov_b32_e32 v66, v34
	v_mov_b32_e32 v67, v34
	v_mov_b32_e32 v68, v34
	v_mov_b32_e32 v69, v34
	v_mov_b32_e32 v70, v34
	v_mov_b32_e32 v71, v34
	v_mov_b32_e32 v72, v34
	v_mov_b32_e32 v73, v34
	v_mov_b32_e32 v74, v34
	v_mov_b32_e32 v75, v34
	v_mov_b32_e32 v76, v34
	v_mov_b32_e32 v77, v34
	v_mov_b32_e32 v78, v34
	v_mov_b32_e32 v79, v34
	v_mov_b32_e32 v80, v34
	v_mov_b32_e32 v81, v34
	v_mov_b32_e32 v82, v34
	v_mov_b32_e32 v83, v34
	v_mov_b32_e32 v84, v34
	v_mov_b32_e32 v85, v34
	v_mov_b32_e32 v86, v34
	v_mov_b32_e32 v87, v34
	v_mov_b32_e32 v88, v34
	v_mov_b32_e32 v89, v34
	v_mov_b32_e32 v90, v34
	v_mov_b32_e32 v91, v34
	v_mov_b32_e32 v92, v34
	v_mov_b32_e32 v93, v34
	v_mov_b32_e32 v94, v34
	v_mov_b32_e32 v95, v34
	v_mov_b32_e32 v96, v34
	v_mov_b32_e32 v97, v34
	v_mov_b32_e32 v98, v34
	v_mov_b32_e32 v99, v34
	v_mov_b32_e32 v100, v34
	v_mov_b32_e32 v101, v34
	v_mov_b32_e32 v102, v34
	v_mov_b32_e32 v103, v34
	v_mov_b32_e32 v104, v34
	v_mov_b32_e32 v105, v34
	v_mov_b32_e32 v106, v34
	v_mov_b32_e32 v107, v34
	v_mov_b32_e32 v108, v34
	v_mov_b32_e32 v109, v34
	v_mov_b32_e32 v110, v34
	v_mov_b32_e32 v111, v34
	v_mov_b32_e32 v112, v34
	v_mov_b32_e32 v113, v34
	v_mov_b32_e32 v114, v34
	v_mov_b32_e32 v115, v34
	v_mov_b32_e32 v116, v34
	v_mov_b32_e32 v117, v34
	v_mov_b32_e32 v118, v34
	v_mov_b32_e32 v119, v34
	v_mov_b32_e32 v120, v34
	v_mov_b32_e32 v121, v34
	v_mov_b32_e32 v122, v34
	v_mov_b32_e32 v123, v34
	v_mov_b32_e32 v124, v34
	v_mov_b32_e32 v125, v34
	v_mov_b32_e32 v126, v34
	v_mov_b32_e32 v127, v34
	v_mov_b32_e32 v128, v34
	v_mov_b32_e32 v129, v34
	v_mov_b32_e32 v130, v34
	v_mov_b32_e32 v131, v34
	v_mov_b32_e32 v132, v34
	v_mov_b32_e32 v133, v34
	v_mov_b32_e32 v134, v34
	v_mov_b32_e32 v135, v34
	v_mov_b32_e32 v136, v34
	v_mov_b32_e32 v137, v34
	v_mov_b32_e32 v138, v34
	v_mov_b32_e32 v139, v34
	v_mov_b32_e32 v140, v34
	v_mov_b32_e32 v141, v34
	v_mov_b32_e32 v142, v34
	v_mov_b32_e32 v143, v34
	v_mov_b32_e32 v144, v34
	v_mov_b32_e32 v145, v34
	v_mov_b32_e32 v146, v34
	v_mov_b32_e32 v147, v34
	v_mov_b32_e32 v148, v34
	v_mov_b32_e32 v149, v34
	v_mov_b32_e32 v150, v34
	v_mov_b32_e32 v151, v34
	v_mov_b32_e32 v152, v34
	v_mov_b32_e32 v153, v34
	v_mov_b32_e32 v154, v34
	v_mov_b32_e32 v155, v34
	v_mov_b32_e32 v156, v34
	v_mov_b32_e32 v157, v34
	v_mov_b32_e32 v158, v34
	v_mov_b32_e32 v159, v34
	v_mov_b32_e32 v160, v34
	v_mov_b32_e32 v161, v34
	v_readfirstlane_b32 s52, v184
	v_readfirstlane_b32 s53, v185
	s_sub_u32 s52, s52, 0x40000000
	s_subb_u32 s53, s53, 0
	v_readfirstlane_b32 s56, v176
	v_readfirstlane_b32 s57, v177
	s_sub_u32 s56, s56, 0x40000000
	s_subb_u32 s57, s57, 0
	v_subrev_u32_e32 v185, s52, v184
	v_subrev_u32_e32 v181, s52, v180
	v_subrev_u32_e32 v179, s52, v178
	v_subrev_u32_e32 v183, s52, v182
	v_subrev_u32_e32 v177, s56, v176
	v_subrev_u32_e32 v175, s56, v174
	v_subrev_u32_e32 v173, s56, v172
	v_subrev_u32_e32 v171, s56, v170

; DI void gemm8_accum(f32x4 (&acc)[8][4], const bf16_t* a, size_t lda, const bf16_t* b, size_t ldb, int nkb, bf16_t* L,
;                     const bool pre, const bf16_t* an, size_t ldan, const bf16_t* bn, size_t ldbn) {
;     ...
;   for (int kb = 0; kb + 2 < nkb; ++kb) {
;     __syncthreads();
;     g8_store1(L + ((kb + 1) & 1) * 32768, ra, lrow, lch);
;     g8_load1o(ra, a + (kb + 2) * 64, offa);
;     __builtin_amdgcn_sched_barrier(0);
;     g8_compute<0, 1>(acc, L + (kb & 1) * 32768, wm, wn, lane);
;     __builtin_amdgcn_sched_barrier(0);
;     g8_store1(L + ((kb + 1) & 1) * 32768 + 16384, rb, lrow, lch);
;     g8_load1o(rb, b + (kb + 2) * 64, offb);
;     __builtin_amdgcn_sched_barrier(0);
;     g8_compute<1, 2>(acc, L + (kb & 1) * 32768, wm, wn, lane);
.Lstg_134_a:
	s_waitcnt vmcnt(5)
	ds_write_b128 v167, v[22:25]
	ds_write_b128 v167, v[18:21] offset:8192
	ds_write_b128 v167, v[26:29] offset:16384
	s_waitcnt vmcnt(4)
	ds_write_b128 v167, v[30:33] offset:24576
	s_add_u32 s54, s52, s0
	s_addc_u32 s55, s53, s1
	global_load_dwordx4 v[22:25], v185, s[54:55]
	global_load_dwordx4 v[26:29], v181, s[54:55]
	global_load_dwordx4 v[18:21], v183, s[54:55]
	s_nop 0
	global_load_dwordx4 v[30:33], v179, s[54:55]
	s_and_b32 s2, s2, 0x8000
	s_lshl_b32 s2, s2, 1
	s_add_i32 s2, s2, 0
	v_lshl_add_u32 v169, v191, 1, s2
	v_add_u32_e32 v198, v169, v187
	ds_read_b128 v[192:195], v198
	ds_read_b128 v[206:209], v198 offset:2048
	ds_read_b128 v[210:213], v198 offset:4096
	ds_read_b128 v[214:217], v198 offset:6144
	ds_read_b128 v[218:221], v198 offset:8192
	ds_read_b128 v[222:225], v198 offset:10240
	ds_read_b128 v[226:229], v198 offset:12288
	ds_read_b128 v[230:233], v198 offset:14336
	v_add_u32_e32 v169, v169, v186
	ds_read_b128 v[234:237], v169 offset:32768
	ds_read_b128 v[238:241], v169 offset:34816
	ds_read_b128 v[242:245], v169 offset:36864
	ds_read_b128 v[246:249], v169 offset:38912
	s_setprio 1
	s_waitcnt lgkmcnt(3)
	v_mfma_f32_16x16x32_bf16 v[34:37], v[234:237], v[192:195], v[34:37]
	s_waitcnt lgkmcnt(2)
	v_mfma_f32_16x16x32_bf16 v[38:41], v[238:241], v[192:195], v[38:41]
	s_waitcnt lgkmcnt(1)
	v_mfma_f32_16x16x32_bf16 v[42:45], v[242:245], v[192:195], v[42:45]
	s_waitcnt lgkmcnt(0)
	v_mfma_f32_16x16x32_bf16 v[46:49], v[246:249], v[192:195], v[46:49]
	v_mfma_f32_16x16x32_bf16 v[50:53], v[234:237], v[206:209], v[50:53]
	v_mfma_f32_16x16x32_bf16 v[54:57], v[238:241], v[206:209], v[54:57]
	v_mfma_f32_16x16x32_bf16 v[58:61], v[242:245], v[206:209], v[58:61]
	v_mfma_f32_16x16x32_bf16 v[62:65], v[246:249], v[206:209], v[62:65]
	v_mfma_f32_16x16x32_bf16 v[66:69], v[234:237], v[210:213], v[66:69]
	v_mfma_f32_16x16x32_bf16 v[70:73], v[238:241], v[210:213], v[70:73]
	v_mfma_f32_16x16x32_bf16 v[74:77], v[242:245], v[210:213], v[74:77]
	v_mfma_f32_16x16x32_bf16 v[78:81], v[246:249], v[210:213], v[78:81]
	v_mfma_f32_16x16x32_bf16 v[82:85], v[234:237], v[214:217], v[82:85]
	v_mfma_f32_16x16x32_bf16 v[86:89], v[238:241], v[214:217], v[86:89]
	v_mfma_f32_16x16x32_bf16 v[90:93], v[242:245], v[214:217], v[90:93]
	v_mfma_f32_16x16x32_bf16 v[94:97], v[246:249], v[214:217], v[94:97]
	v_mfma_f32_16x16x32_bf16 v[98:101], v[234:237], v[218:221], v[98:101]
	v_mfma_f32_16x16x32_bf16 v[102:105], v[238:241], v[218:221], v[102:105]
	v_mfma_f32_16x16x32_bf16 v[106:109], v[242:245], v[218:221], v[106:109]
	v_mfma_f32_16x16x32_bf16 v[110:113], v[246:249], v[218:221], v[110:113]
	v_mfma_f32_16x16x32_bf16 v[114:117], v[234:237], v[222:225], v[114:117]
	v_mfma_f32_16x16x32_bf16 v[118:121], v[238:241], v[222:225], v[118:121]
	v_mfma_f32_16x16x32_bf16 v[122:125], v[242:245], v[222:225], v[122:125]
	v_mfma_f32_16x16x32_bf16 v[126:129], v[246:249], v[222:225], v[126:129]
	v_mfma_f32_16x16x32_bf16 v[130:133], v[234:237], v[226:229], v[130:133]
	v_mfma_f32_16x16x32_bf16 v[134:137], v[238:241], v[226:229], v[134:137]
	v_mfma_f32_16x16x32_bf16 v[138:141], v[242:245], v[226:229], v[138:141]
	v_mfma_f32_16x16x32_bf16 v[142:145], v[246:249], v[226:229], v[142:145]
	v_mfma_f32_16x16x32_bf16 v[146:149], v[234:237], v[230:233], v[146:149]
	v_mfma_f32_16x16x32_bf16 v[150:153], v[238:241], v[230:233], v[150:153]
	v_mfma_f32_16x16x32_bf16 v[154:157], v[242:245], v[230:233], v[154:157]
	v_mfma_f32_16x16x32_bf16 v[158:161], v[246:249], v[230:233], v[158:161]
	s_setprio 0
	s_waitcnt vmcnt(7)
	ds_write_b128 v167, v[6:9] offset:32768
	s_waitcnt vmcnt(6)
	ds_write_b128 v167, v[2:5] offset:40960
	s_waitcnt vmcnt(5)
	ds_write_b128 v167, v[10:13] offset:49152
	s_waitcnt vmcnt(4)
	ds_write_b128 v167, v[14:17] offset:57344
	s_add_u32 s58, s56, s0
	s_addc_u32 s59, s57, s1
	global_load_dwordx4 v[6:9], v177, s[58:59]
	s_nop 0
	global_load_dwordx4 v[2:5], v175, s[58:59]
	s_nop 0
	global_load_dwordx4 v[10:13], v173, s[58:59]
	s_nop 0
	global_load_dwordx4 v[14:17], v171, s[58:59]
	v_lshl_add_u32 v167, v188, 1, s2
	v_add_u32_e32 v169, v167, v187
	ds_read_b128 v[192:195], v169
	ds_read_b128 v[206:209], v169 offset:2048
	ds_read_b128 v[210:213], v169 offset:4096
	ds_read_b128 v[214:217], v169 offset:6144
	ds_read_b128 v[218:221], v169 offset:8192
	ds_read_b128 v[222:225], v169 offset:10240
	ds_read_b128 v[226:229], v169 offset:12288
	ds_read_b128 v[230:233], v169 offset:14336
	v_add_u32_e32 v167, v167, v186
	ds_read_b128 v[234:237], v167 offset:32768
	ds_read_b128 v[238:241], v167 offset:34816
	ds_read_b128 v[242:245], v167 offset:36864
	ds_read_b128 v[246:249], v167 offset:38912
	s_cmp_lg_u32 s101, 0
	s_cbranch_scc1 .Lstg_134_b
; DI f32x4 mfma16(bf16x8 a, bf16x8 b, f32x4 c) { return __builtin_amdgcn_mfma_f32_16x16x32_bf16(a, b, c, 0, 0, 0); }
; #pragma unroll
;   for (int ks = KS0; ks < KS1; ++ks) {
;     bf16x8 af[8], bfr[4];
; #pragma unroll
;     for (int i = 0; i < 8; ++i) {
;       const int r = wm * 128 + i * 16 + (lane & 15);
;       af[i] = *(const bf16x8*)(S + r * 64 + (((ks * 4 + (lane >> 4)) ^ ((r >> 1) & 7)) << 3));
;     }
; #pragma unroll
;     for (int j = 0; j < 4; ++j) {
;       const int r = wn * 64 + j * 16 + (lane & 15);
;       bfr[j] = *(const bf16x8*)(S + 16384 + r * 64 + (((ks * 4 + (lane >> 4)) ^ ((r >> 1) & 7)) << 3));
;     }
;     __builtin_amdgcn_s_setprio(1);
; #pragma unroll
;     for (int i = 0; i < 8; ++i)
; #pragma unroll
;       for (int j = 0; j < 4; ++j) acc[i][j] = mfma16(bfr[j], af[i], acc[i][j]);
;     __builtin_amdgcn_s_setprio(0);
;   }
; }
	s_setprio 1
	s_waitcnt lgkmcnt(3)
	v_mfma_f32_16x16x32_bf16 v[34:37], v[234:237], v[192:195], v[34:37]
	s_waitcnt lgkmcnt(2)
	v_mfma_f32_16x16x32_bf16 v[38:41], v[238:241], v[192:195], v[38:41]
	s_waitcnt lgkmcnt(1)
	v_mfma_f32_16x16x32_bf16 v[42:45], v[242:245], v[192:195], v[42:45]
	s_waitcnt lgkmcnt(0)
	v_mfma_f32_16x16x32_bf16 v[46:49], v[246:249], v[192:195], v[46:49]
	v_mfma_f32_16x16x32_bf16 v[50:53], v[234:237], v[206:209], v[50:53]
	v_mfma_f32_16x16x32_bf16 v[54:57], v[238:241], v[206:209], v[54:57]
	v_mfma_f32_16x16x32_bf16 v[58:61], v[242:245], v[206:209], v[58:61]
	v_mfma_f32_16x16x32_bf16 v[62:65], v[246:249], v[206:209], v[62:65]
	v_mfma_f32_16x16x32_bf16 v[66:69], v[234:237], v[210:213], v[66:69]
	v_mfma_f32_16x16x32_bf16 v[70:73], v[238:241], v[210:213], v[70:73]
	v_mfma_f32_16x16x32_bf16 v[74:77], v[242:245], v[210:213], v[74:77]
	v_mfma_f32_16x16x32_bf16 v[78:81], v[246:249], v[210:213], v[78:81]
	v_mfma_f32_16x16x32_bf16 v[82:85], v[234:237], v[214:217], v[82:85]
	v_mfma_f32_16x16x32_bf16 v[86:89], v[238:241], v[214:217], v[86:89]
	v_mfma_f32_16x16x32_bf16 v[90:93], v[242:245], v[214:217], v[90:93]
	v_mfma_f32_16x16x32_bf16 v[94:97], v[246:249], v[214:217], v[94:97]
	v_mfma_f32_16x16x32_bf16 v[98:101], v[234:237], v[218:221], v[98:101]
	v_mfma_f32_16x16x32_bf16 v[102:105], v[238:241], v[218:221], v[102:105]
	v_mfma_f32_16x16x32_bf16 v[106:109], v[242:245], v[218:221], v[106:109]
	v_mfma_f32_16x16x32_bf16 v[110:113], v[246:249], v[218:221], v[110:113]
	v_mfma_f32_16x16x32_bf16 v[114:117], v[234:237], v[222:225], v[114:117]
	v_mfma_f32_16x16x32_bf16 v[118:121], v[238:241], v[222:225], v[118:121]
	v_mfma_f32_16x16x32_bf16 v[122:125], v[242:245], v[222:225], v[122:125]
	v_mfma_f32_16x16x32_bf16 v[126:129], v[246:249], v[222:225], v[126:129]
	v_mfma_f32_16x16x32_bf16 v[130:133], v[234:237], v[226:229], v[130:133]
	v_mfma_f32_16x16x32_bf16 v[134:137], v[238:241], v[226:229], v[134:137]
	v_mfma_f32_16x16x32_bf16 v[138:141], v[242:245], v[226:229], v[138:141]
	v_mfma_f32_16x16x32_bf16 v[142:145], v[246:249], v[226:229], v[142:145]
	v_mfma_f32_16x16x32_bf16 v[146:149], v[234:237], v[230:233], v[146:149]
	v_mfma_f32_16x16x32_bf16 v[150:153], v[238:241], v[230:233], v[150:153]
	v_mfma_f32_16x16x32_bf16 v[154:157], v[242:245], v[230:233], v[154:157]
	v_mfma_f32_16x16x32_bf16 v[158:161], v[246:249], v[230:233], v[158:161]
	s_setprio 0

; DI int TID8() { int t = threadIdx.x; asm volatile("" : "+v"(t)); return t; }
; DI void gemm8_accum(f32x4 (&acc)[8][4], const bf16_t* a, size_t lda, const bf16_t* b, size_t ldb, int nkb, bf16_t* L,
;                     const bool pre, const bf16_t* an, size_t ldan, const bf16_t* bn, size_t ldbn) {
;   const int tid = TID8(), lane = tid & 63, w = tid >> 6;
;   const int wm = w >> 2, wn = w & 3;
;   const int lrow = tid >> 3, lch = tid & 7;
;   u32x4 ra[4], rb[4];
;   unsigned offa[4], offb[4];
; #pragma unroll
;   for (int i = 0; i < 4; ++i) {
;     offa[i] = (unsigned)(lrow + 64 * i) * (unsigned)lda + (unsigned)(lch * 8);
;     offb[i] = (unsigned)(lrow + 64 * i) * (unsigned)ldb + (unsigned)(lch * 8);
;   }
;   if (!pre) {
;     g8_load1o(ra, a, offa);
;     g8_load1o(rb, b, offb);
;     __syncthreads();
;     g8_store(L, ra, rb, lrow, lch);
;   }
;   g8_load1o(ra, a + 64, offa);
;   g8_load1o(rb, b + 64, offb);
; DI void zero_acc8(f32x4 (&acc)[8][4]) {
; #pragma unroll
;   for (int i = 0; i < 8; ++i)
; #pragma unroll
;     for (int j = 0; j < 4; ++j) acc[i][j] = f32x4{0.f, 0.f, 0.f, 0.f};
; }
.LBB0_777:
	v_lshlrev_b64 v[38:39], 1, v[168:169]
	v_lshl_add_u64 v[6:7], s[2:3], 0, v[38:39]
	v_lshlrev_b64 v[40:41], 1, v[166:167]
	v_lshlrev_b64 v[42:43], 1, v[164:165]
	v_lshl_add_u64 v[8:9], s[2:3], 0, v[40:41]
	global_load_dwordx4 v[18:21], v[6:7], off offset:128
	global_load_dwordx4 v[26:29], v[8:9], off offset:128
	v_lshl_add_u64 v[6:7], s[2:3], 0, v[42:43]
	global_load_dwordx4 v[22:25], v[4:5], off offset:128
	global_load_dwordx4 v[30:33], v[6:7], off offset:128
	global_load_dwordx4 v[14:17], v[2:3], off offset:128
	v_lshl_add_u64 v[2:3], s[0:1], 0, v[38:39]
	s_nop 1
	global_load_dwordx4 v[2:5], v[2:3], off offset:128
	v_lshl_add_u64 v[6:7], s[0:1], 0, v[40:41]
	v_lshl_add_u64 v[10:11], s[0:1], 0, v[42:43]
	global_load_dwordx4 v[6:9], v[6:7], off offset:128
	s_nop 0
	global_load_dwordx4 v[10:13], v[10:11], off offset:128
	s_lshl_b32 s7, s11, 10
	v_bfe_u32 v44, v35, 4, 2
	v_lshrrev_b32_e32 v45, 1, v35
	s_and_b32 s21, s7, 0xc0000
	s_and_b32 s7, s10, 0x60
	v_readlane_b32 s20, v252, 25
	v_bitop3_b32 v45, v45, v44, 7 bitop3:0x6c
	s_or_b32 s7, s20, s7
	s_and_b32 s20, s9, 3
	v_lshlrev_b32_e32 v169, 3, v45
	v_lshlrev_b32_e32 v45, 5, v35
	s_add_i32 s7, s7, s20
	v_bfe_u32 v46, v35, 1, 3
	v_and_b32_e32 v45, 0xffffe000, v45
	v_lshlrev_b32_e32 v35, 6, v35
	s_movk_i32 s0, 0x3c0
	s_lshl_b32 s13, s13, 8
	s_lshl_b32 s6, s12, 9
	s_lshl_b32 s20, s7, 18
	v_and_or_b32 v45, v35, s0, v45
	v_and_b32_e32 v47, 0x33c0, v35
	v_bitop3_b32 v35, v44, v46, 4 bitop3:0x36
	v_readlane_b32 s0, v254, 10
	v_lshlrev_b32_e32 v189, 3, v35
	s_add_u32 s0, s0, s21
	v_readlane_b32 s1, v254, 11
	v_add_u32_e32 v34, v34, v170
	v_mov_b32_e32 v35, v1
	s_addc_u32 s1, s1, 0
	v_lshlrev_b64 v[34:35], 1, v[34:35]
	v_lshl_add_u64 v[172:173], s[0:1], 0, v[42:43]
	v_lshl_add_u64 v[174:175], s[0:1], 0, v[40:41]
	v_lshl_add_u64 v[176:177], s[0:1], 0, v[38:39]
	v_lshl_add_u64 v[178:179], s[0:1], 0, v[34:35]
	v_readlane_b32 s0, v254, 14
	s_add_u32 s0, s0, s20
	v_readlane_b32 s1, v254, 15
	s_addc_u32 s1, s1, 0
	v_lshlrev_b32_e32 v165, 1, v37
	v_lshlrev_b32_e32 v167, 1, v36
	v_lshl_add_u64 v[186:187], s[0:1], 0, v[34:35]
	v_mov_b32_e32 v34, 0
	v_add3_u32 v163, 0, v165, v167
	v_lshl_add_u64 v[180:181], s[0:1], 0, v[42:43]
	v_lshl_add_u64 v[182:183], s[0:1], 0, v[40:41]
	v_lshl_add_u64 v[184:185], s[0:1], 0, v[38:39]
	s_mov_b64 s[0:1], 0
	s_mov_b32 s2, 0
	v_lshlrev_b32_e32 v188, 1, v45
	v_lshlrev_b32_e32 v171, 1, v47
	v_mov_b32_e32 v35, v34
	v_mov_b32_e32 v36, v34
	v_mov_b32_e32 v37, v34
	v_mov_b32_e32 v38, v34
	v_mov_b32_e32 v39, v34
	v_mov_b32_e32 v40, v34
	v_mov_b32_e32 v41, v34
	v_mov_b32_e32 v42, v34
	v_mov_b32_e32 v43, v34
	v_mov_b32_e32 v44, v34
	v_mov_b32_e32 v45, v34
	v_mov_b32_e32 v46, v34
	v_mov_b32_e32 v47, v34
	v_mov_b32_e32 v48, v34
	v_mov_b32_e32 v49, v34
	v_mov_b32_e32 v50, v34
	v_mov_b32_e32 v51, v34
	v_mov_b32_e32 v52, v34
	v_mov_b32_e32 v53, v34
	v_mov_b32_e32 v54, v34
	v_mov_b32_e32 v55, v34
	v_mov_b32_e32 v56, v34
	v_mov_b32_e32 v57, v34
	v_mov_b32_e32 v58, v34
	v_mov_b32_e32 v59, v34
	v_mov_b32_e32 v60, v34
	v_mov_b32_e32 v61, v34
	v_mov_b32_e32 v62, v34
	v_mov_b32_e32 v63, v34
	v_mov_b32_e32 v64, v34
	v_mov_b32_e32 v65, v34
	v_mov_b32_e32 v66, v34
	v_mov_b32_e32 v67, v34
	v_mov_b32_e32 v68, v34
	v_mov_b32_e32 v69, v34
	v_mov_b32_e32 v70, v34
	v_mov_b32_e32 v71, v34
	v_mov_b32_e32 v72, v34
	v_mov_b32_e32 v73, v34
	v_mov_b32_e32 v74, v34
	v_mov_b32_e32 v75, v34
	v_mov_b32_e32 v76, v34
	v_mov_b32_e32 v77, v34
	v_mov_b32_e32 v78, v34
	v_mov_b32_e32 v79, v34
	v_mov_b32_e32 v80, v34
	v_mov_b32_e32 v81, v34
	v_mov_b32_e32 v82, v34
	v_mov_b32_e32 v83, v34
	v_mov_b32_e32 v84, v34
	v_mov_b32_e32 v85, v34
	v_mov_b32_e32 v86, v34
	v_mov_b32_e32 v87, v34
	v_mov_b32_e32 v88, v34
	v_mov_b32_e32 v89, v34
	v_mov_b32_e32 v90, v34
	v_mov_b32_e32 v91, v34
	v_mov_b32_e32 v92, v34
	v_mov_b32_e32 v93, v34
	v_mov_b32_e32 v94, v34
	v_mov_b32_e32 v95, v34
	v_mov_b32_e32 v96, v34
	v_mov_b32_e32 v97, v34
	v_mov_b32_e32 v98, v34
	v_mov_b32_e32 v99, v34
	v_mov_b32_e32 v100, v34
	v_mov_b32_e32 v101, v34
	v_mov_b32_e32 v102, v34
	v_mov_b32_e32 v103, v34
	v_mov_b32_e32 v104, v34
	v_mov_b32_e32 v105, v34
	v_mov_b32_e32 v106, v34
	v_mov_b32_e32 v107, v34
	v_mov_b32_e32 v108, v34
	v_mov_b32_e32 v109, v34
	v_mov_b32_e32 v110, v34
	v_mov_b32_e32 v111, v34
	v_mov_b32_e32 v112, v34
	v_mov_b32_e32 v113, v34
	v_mov_b32_e32 v114, v34
	v_mov_b32_e32 v115, v34
	v_mov_b32_e32 v116, v34
	v_mov_b32_e32 v117, v34
	v_mov_b32_e32 v118, v34
	v_mov_b32_e32 v119, v34
	v_mov_b32_e32 v120, v34
	v_mov_b32_e32 v121, v34
	v_mov_b32_e32 v122, v34
	v_mov_b32_e32 v123, v34
	v_mov_b32_e32 v124, v34
	v_mov_b32_e32 v125, v34
	v_mov_b32_e32 v126, v34
	v_mov_b32_e32 v127, v34
	v_mov_b32_e32 v128, v34
	v_mov_b32_e32 v129, v34
	v_mov_b32_e32 v130, v34
	v_mov_b32_e32 v131, v34
	v_mov_b32_e32 v132, v34
	v_mov_b32_e32 v133, v34
	v_mov_b32_e32 v134, v34
	v_mov_b32_e32 v135, v34
	v_mov_b32_e32 v136, v34
	v_mov_b32_e32 v137, v34
	v_mov_b32_e32 v138, v34
	v_mov_b32_e32 v139, v34
	v_mov_b32_e32 v140, v34
	v_mov_b32_e32 v141, v34
	v_mov_b32_e32 v142, v34
	v_mov_b32_e32 v143, v34
	v_mov_b32_e32 v144, v34
	v_mov_b32_e32 v145, v34
	v_mov_b32_e32 v146, v34
	v_mov_b32_e32 v147, v34
	v_mov_b32_e32 v148, v34
	v_mov_b32_e32 v149, v34
	v_mov_b32_e32 v150, v34
	v_mov_b32_e32 v151, v34
	v_mov_b32_e32 v152, v34
	v_mov_b32_e32 v153, v34
	v_mov_b32_e32 v154, v34
	v_mov_b32_e32 v155, v34
	v_mov_b32_e32 v156, v34
	v_mov_b32_e32 v157, v34
	v_mov_b32_e32 v158, v34
	v_mov_b32_e32 v159, v34
	v_mov_b32_e32 v160, v34
	v_mov_b32_e32 v161, v34
	v_readfirstlane_b32 s52, v186
	v_readfirstlane_b32 s53, v187
	s_sub_u32 s52, s52, 0x40000000
	s_subb_u32 s53, s53, 0
	v_readfirstlane_b32 s56, v178
	v_readfirstlane_b32 s57, v179
	s_sub_u32 s56, s56, 0x40000000
	s_subb_u32 s57, s57, 0
	v_subrev_u32_e32 v187, s52, v186
	v_subrev_u32_e32 v183, s52, v182
	v_subrev_u32_e32 v181, s52, v180
	v_subrev_u32_e32 v185, s52, v184
	v_subrev_u32_e32 v179, s56, v178
	v_subrev_u32_e32 v177, s56, v176
	v_subrev_u32_e32 v175, s56, v174
	v_subrev_u32_e32 v173, s56, v172

; DI void gemm8_accum(f32x4 (&acc)[8][4], const bf16_t* a, size_t lda, const bf16_t* b, size_t ldb, int nkb, bf16_t* L,
;                     const bool pre, const bf16_t* an, size_t ldan, const bf16_t* bn, size_t ldbn) {
;     ...
;   for (int kb = 0; kb + 2 < nkb; ++kb) {
;     __syncthreads();
;     g8_store1(L + ((kb + 1) & 1) * 32768, ra, lrow, lch);
;     g8_load1o(ra, a + (kb + 2) * 64, offa);
;     __builtin_amdgcn_sched_barrier(0);
;     g8_compute<0, 1>(acc, L + (kb & 1) * 32768, wm, wn, lane);
;     __builtin_amdgcn_sched_barrier(0);
;     g8_store1(L + ((kb + 1) & 1) * 32768 + 16384, rb, lrow, lch);
;     g8_load1o(rb, b + (kb + 2) * 64, offb);
;     __builtin_amdgcn_sched_barrier(0);
;     g8_compute<1, 2>(acc, L + (kb & 1) * 32768, wm, wn, lane);
.Lstg_778_a:
	s_waitcnt vmcnt(5)
	ds_write_b128 v191, v[22:25]
	ds_write_b128 v191, v[18:21] offset:8192
	ds_write_b128 v191, v[26:29] offset:16384
	s_waitcnt vmcnt(4)
	ds_write_b128 v191, v[30:33] offset:24576
	s_add_u32 s54, s52, s0
	s_addc_u32 s55, s53, s1
	global_load_dwordx4 v[22:25], v187, s[54:55]
	global_load_dwordx4 v[26:29], v183, s[54:55]
	global_load_dwordx4 v[18:21], v185, s[54:55]
	s_nop 0
	global_load_dwordx4 v[30:33], v181, s[54:55]
	s_and_b32 s2, s2, 0x8000
	s_lshl_b32 s2, s2, 1
	s_add_i32 s2, s2, 0
	v_lshl_add_u32 v202, v169, 1, s2
	v_add_u32_e32 v203, v202, v188
	ds_read_b128 v[192:195], v203
	ds_read_b128 v[198:201], v203 offset:2048
	ds_read_b128 v[206:209], v203 offset:4096
	ds_read_b128 v[210:213], v203 offset:6144
	ds_read_b128 v[214:217], v203 offset:8192
	ds_read_b128 v[218:221], v203 offset:10240
	ds_read_b128 v[222:225], v203 offset:12288
	ds_read_b128 v[226:229], v203 offset:14336
	v_add_u32_e32 v202, v202, v171
	ds_read_b128 v[230:233], v202 offset:32768
	ds_read_b128 v[234:237], v202 offset:34816
	ds_read_b128 v[238:241], v202 offset:36864
	ds_read_b128 v[242:245], v202 offset:38912
	s_setprio 1
	s_waitcnt lgkmcnt(3)
	v_mfma_f32_16x16x32_bf16 v[158:161], v[230:233], v[192:195], v[158:161]
	s_waitcnt lgkmcnt(2)
	v_mfma_f32_16x16x32_bf16 v[154:157], v[234:237], v[192:195], v[154:157]
	s_waitcnt lgkmcnt(1)
	v_mfma_f32_16x16x32_bf16 v[150:153], v[238:241], v[192:195], v[150:153]
	s_waitcnt lgkmcnt(0)
	v_mfma_f32_16x16x32_bf16 v[146:149], v[242:245], v[192:195], v[146:149]
	v_mfma_f32_16x16x32_bf16 v[142:145], v[230:233], v[198:201], v[142:145]
	v_mfma_f32_16x16x32_bf16 v[138:141], v[234:237], v[198:201], v[138:141]
	v_mfma_f32_16x16x32_bf16 v[134:137], v[238:241], v[198:201], v[134:137]
	v_mfma_f32_16x16x32_bf16 v[130:133], v[242:245], v[198:201], v[130:133]
	v_mfma_f32_16x16x32_bf16 v[126:129], v[230:233], v[206:209], v[126:129]
	v_mfma_f32_16x16x32_bf16 v[122:125], v[234:237], v[206:209], v[122:125]
	v_mfma_f32_16x16x32_bf16 v[118:121], v[238:241], v[206:209], v[118:121]
	v_mfma_f32_16x16x32_bf16 v[114:117], v[242:245], v[206:209], v[114:117]
	v_mfma_f32_16x16x32_bf16 v[110:113], v[230:233], v[210:213], v[110:113]
	v_mfma_f32_16x16x32_bf16 v[106:109], v[234:237], v[210:213], v[106:109]
	v_mfma_f32_16x16x32_bf16 v[102:105], v[238:241], v[210:213], v[102:105]
	v_mfma_f32_16x16x32_bf16 v[98:101], v[242:245], v[210:213], v[98:101]
	v_mfma_f32_16x16x32_bf16 v[94:97], v[230:233], v[214:217], v[94:97]
	v_mfma_f32_16x16x32_bf16 v[90:93], v[234:237], v[214:217], v[90:93]
	v_mfma_f32_16x16x32_bf16 v[86:89], v[238:241], v[214:217], v[86:89]
	v_mfma_f32_16x16x32_bf16 v[82:85], v[242:245], v[214:217], v[82:85]
	v_mfma_f32_16x16x32_bf16 v[78:81], v[230:233], v[218:221], v[78:81]
	v_mfma_f32_16x16x32_bf16 v[74:77], v[234:237], v[218:221], v[74:77]
	v_mfma_f32_16x16x32_bf16 v[70:73], v[238:241], v[218:221], v[70:73]
	v_mfma_f32_16x16x32_bf16 v[66:69], v[242:245], v[218:221], v[66:69]
	v_mfma_f32_16x16x32_bf16 v[62:65], v[230:233], v[222:225], v[62:65]
	v_mfma_f32_16x16x32_bf16 v[58:61], v[234:237], v[222:225], v[58:61]
	v_mfma_f32_16x16x32_bf16 v[54:57], v[238:241], v[222:225], v[54:57]
	v_mfma_f32_16x16x32_bf16 v[50:53], v[242:245], v[222:225], v[50:53]
	v_mfma_f32_16x16x32_bf16 v[46:49], v[230:233], v[226:229], v[46:49]
	v_mfma_f32_16x16x32_bf16 v[42:45], v[234:237], v[226:229], v[42:45]
	v_mfma_f32_16x16x32_bf16 v[38:41], v[238:241], v[226:229], v[38:41]
	v_mfma_f32_16x16x32_bf16 v[34:37], v[242:245], v[226:229], v[34:37]
	s_setprio 0
	s_waitcnt vmcnt(7)
	ds_write_b128 v191, v[14:17] offset:32768
	s_waitcnt vmcnt(6)
	ds_write_b128 v191, v[2:5] offset:40960
	s_waitcnt vmcnt(5)
	ds_write_b128 v191, v[6:9] offset:49152
	s_waitcnt vmcnt(4)
	ds_write_b128 v191, v[10:13] offset:57344
	s_add_u32 s58, s56, s0
	s_addc_u32 s59, s57, s1
	global_load_dwordx4 v[14:17], v179, s[58:59]
	s_nop 0
	global_load_dwordx4 v[2:5], v177, s[58:59]
	s_nop 0
	global_load_dwordx4 v[6:9], v175, s[58:59]
	s_nop 0
	global_load_dwordx4 v[10:13], v173, s[58:59]
	v_lshl_add_u32 v191, v189, 1, s2
	v_add_u32_e32 v202, v191, v188
	ds_read_b128 v[192:195], v202
	ds_read_b128 v[198:201], v202 offset:2048
	ds_read_b128 v[206:209], v202 offset:4096
	ds_read_b128 v[210:213], v202 offset:6144
	ds_read_b128 v[214:217], v202 offset:8192
	ds_read_b128 v[218:221], v202 offset:10240
	ds_read_b128 v[222:225], v202 offset:12288
	ds_read_b128 v[226:229], v202 offset:14336
	v_add_u32_e32 v191, v191, v171
	ds_read_b128 v[230:233], v191 offset:32768
	ds_read_b128 v[234:237], v191 offset:34816
	ds_read_b128 v[238:241], v191 offset:36864
	ds_read_b128 v[242:245], v191 offset:38912
	s_cmp_lg_u32 s101, 0
	s_cbranch_scc1 .Lstg_778_b
; DI f32x4 mfma16(bf16x8 a, bf16x8 b, f32x4 c) { return __builtin_amdgcn_mfma_f32_16x16x32_bf16(a, b, c, 0, 0, 0); }
; #pragma unroll
;   for (int ks = KS0; ks < KS1; ++ks) {
;     bf16x8 af[8], bfr[4];
; #pragma unroll
;     for (int i = 0; i < 8; ++i) {
;       const int r = wm * 128 + i * 16 + (lane & 15);
;       af[i] = *(const bf16x8*)(S + r * 64 + (((ks * 4 + (lane >> 4)) ^ ((r >> 1) & 7)) << 3));
;     }
; #pragma unroll
;     for (int j = 0; j < 4; ++j) {
;       const int r = wn * 64 + j * 16 + (lane & 15);
;       bfr[j] = *(const bf16x8*)(S + 16384 + r * 64 + (((ks * 4 + (lane >> 4)) ^ ((r >> 1) & 7)) << 3));
;     }
;     __builtin_amdgcn_s_setprio(1);
; #pragma unroll
;     for (int i = 0; i < 8; ++i)
; #pragma unroll
;       for (int j = 0; j < 4; ++j) acc[i][j] = mfma16(bfr[j], af[i], acc[i][j]);
;     __builtin_amdgcn_s_setprio(0);
;   }
; }
	s_setprio 1
	s_waitcnt lgkmcnt(3)
	v_mfma_f32_16x16x32_bf16 v[158:161], v[230:233], v[192:195], v[158:161]
	s_waitcnt lgkmcnt(2)
	v_mfma_f32_16x16x32_bf16 v[154:157], v[234:237], v[192:195], v[154:157]
	s_waitcnt lgkmcnt(1)
	v_mfma_f32_16x16x32_bf16 v[150:153], v[238:241], v[192:195], v[150:153]
	s_waitcnt lgkmcnt(0)
	v_mfma_f32_16x16x32_bf16 v[146:149], v[242:245], v[192:195], v[146:149]
	v_mfma_f32_16x16x32_bf16 v[142:145], v[230:233], v[198:201], v[142:145]
	v_mfma_f32_16x16x32_bf16 v[138:141], v[234:237], v[198:201], v[138:141]
	v_mfma_f32_16x16x32_bf16 v[134:137], v[238:241], v[198:201], v[134:137]
	v_mfma_f32_16x16x32_bf16 v[130:133], v[242:245], v[198:201], v[130:133]
	v_mfma_f32_16x16x32_bf16 v[126:129], v[230:233], v[206:209], v[126:129]
	v_mfma_f32_16x16x32_bf16 v[122:125], v[234:237], v[206:209], v[122:125]
	v_mfma_f32_16x16x32_bf16 v[118:121], v[238:241], v[206:209], v[118:121]
	v_mfma_f32_16x16x32_bf16 v[114:117], v[242:245], v[206:209], v[114:117]
	v_mfma_f32_16x16x32_bf16 v[110:113], v[230:233], v[210:213], v[110:113]
	v_mfma_f32_16x16x32_bf16 v[106:109], v[234:237], v[210:213], v[106:109]
	v_mfma_f32_16x16x32_bf16 v[102:105], v[238:241], v[210:213], v[102:105]
	v_mfma_f32_16x16x32_bf16 v[98:101], v[242:245], v[210:213], v[98:101]
	v_mfma_f32_16x16x32_bf16 v[94:97], v[230:233], v[214:217], v[94:97]
	v_mfma_f32_16x16x32_bf16 v[90:93], v[234:237], v[214:217], v[90:93]
	v_mfma_f32_16x16x32_bf16 v[86:89], v[238:241], v[214:217], v[86:89]
	v_mfma_f32_16x16x32_bf16 v[82:85], v[242:245], v[214:217], v[82:85]
	v_mfma_f32_16x16x32_bf16 v[78:81], v[230:233], v[218:221], v[78:81]
	v_mfma_f32_16x16x32_bf16 v[74:77], v[234:237], v[218:221], v[74:77]
	v_mfma_f32_16x16x32_bf16 v[70:73], v[238:241], v[218:221], v[70:73]
	v_mfma_f32_16x16x32_bf16 v[66:69], v[242:245], v[218:221], v[66:69]
	v_mfma_f32_16x16x32_bf16 v[62:65], v[230:233], v[222:225], v[62:65]
	v_mfma_f32_16x16x32_bf16 v[58:61], v[234:237], v[222:225], v[58:61]
	v_mfma_f32_16x16x32_bf16 v[54:57], v[238:241], v[222:225], v[54:57]
	v_mfma_f32_16x16x32_bf16 v[50:53], v[242:245], v[222:225], v[50:53]
	v_mfma_f32_16x16x32_bf16 v[46:49], v[230:233], v[226:229], v[46:49]
	v_mfma_f32_16x16x32_bf16 v[42:45], v[234:237], v[226:229], v[42:45]
	v_mfma_f32_16x16x32_bf16 v[38:41], v[238:241], v[226:229], v[38:41]
	v_mfma_f32_16x16x32_bf16 v[34:37], v[242:245], v[226:229], v[34:37]
	s_setprio 0

; DI void gemm8_accum(f32x4 (&acc)[8][4], const bf16_t* a, size_t lda, const bf16_t* b, size_t ldb, int nkb, bf16_t* L,
;                     const bool pre, const bf16_t* an, size_t ldan, const bf16_t* bn, size_t ldbn) {
;     ...
;   __syncthreads();
;   g8_store1(L + 32768, ra, lrow, lch);
;   g8_load1(ra, an, ldan, 0, lrow, lch);
;   __builtin_amdgcn_sched_barrier(0);
;   g8_compute<0, 1>(acc, L, wm, wn, lane);
;   __builtin_amdgcn_sched_barrier(0);
;   g8_store1(L + 32768 + 16384, rb, lrow, lch);
;   g8_load1(rb, bn, ldbn, 0, lrow, lch);
;   __builtin_amdgcn_sched_barrier(0);
;   g8_compute<1, 2>(acc, L, wm, wn, lane);
.Lstg_778_c:
	s_mul_i32 s0, s13, 0x2a30
	s_movk_i32 s25, 0x1518
	s_add_u32 s2, s16, s0
	v_mad_u64_u32 v[180:181], s[0:1], v190, s25, v[170:171]
	s_addc_u32 s3, s17, 0
	v_mov_b32_e32 v181, v1
	v_lshl_add_u64 v[172:173], v[180:181], 1, s[2:3]
	v_add_u32_e32 v174, 0x54600, v180
	v_mov_b32_e32 v175, v1
	v_add_u32_e32 v182, 0xa8c00, v180
	v_mov_b32_e32 v183, v1
	v_add_u32_e32 v180, 0xfd200, v180
	v_lshl_add_u64 v[176:177], v[174:175], 1, s[2:3]
	v_lshl_add_u64 v[182:183], v[182:183], 1, s[2:3]
	v_lshl_add_u64 v[184:185], v[180:181], 1, s[2:3]
	s_barrier
	global_load_dwordx4 v[172:175], v[172:173], off offset:2608
	s_nop 0
	global_load_dwordx4 v[176:179], v[176:177], off offset:2608
	s_nop 0
	global_load_dwordx4 v[180:183], v[182:183], off offset:2608
	s_nop 0
	global_load_dwordx4 v[184:187], v[184:185], off offset:2608
	s_mul_i32 s0, s7, 0x2a3000
	s_lshl_b32 s1, s6, 1
	v_readlane_b32 s6, v252, 1
	v_readlane_b32 s7, v252, 2
	s_add_u32 s6, s6, s1
	s_addc_u32 s7, s7, 0
	s_add_i32 s20, 0, 0x10000
	v_add3_u32 v170, s20, v165, v167
	s_waitcnt vmcnt(11)
	ds_write_b128 v170, v[22:25]
	s_waitcnt vmcnt(9)
	ds_write_b128 v170, v[18:21] offset:8192
	ds_write_b128 v170, v[26:29] offset:16384
	s_waitcnt vmcnt(8)
	ds_write_b128 v170, v[30:33] offset:24576
	v_lshlrev_b32_e32 v170, 1, v169
	v_add_u32_e32 v169, 0, v170
	v_add_u32_e32 v194, v169, v188
	ds_read_b128 v[18:21], v194
	ds_read_b128 v[22:25], v194 offset:2048
	ds_read_b128 v[26:29], v194 offset:4096
	ds_read_b128 v[30:33], v194 offset:6144
	ds_read_b128 v[190:193], v194 offset:8192
	ds_read_b128 v[198:201], v194 offset:10240
	ds_read_b128 v[206:209], v194 offset:12288
	ds_read_b128 v[210:213], v194 offset:14336
	v_add_u32_e32 v169, v169, v171
	ds_read_b128 v[214:217], v169 offset:32768
	ds_read_b128 v[218:221], v169 offset:34816
	ds_read_b128 v[222:225], v169 offset:36864
	ds_read_b128 v[226:229], v169 offset:38912
	s_setprio 1
	s_waitcnt lgkmcnt(3)
	v_mfma_f32_16x16x32_bf16 v[158:161], v[214:217], v[18:21], v[158:161]
	s_waitcnt lgkmcnt(2)
	v_mfma_f32_16x16x32_bf16 v[154:157], v[218:221], v[18:21], v[154:157]
	s_waitcnt lgkmcnt(1)
	v_mfma_f32_16x16x32_bf16 v[150:153], v[222:225], v[18:21], v[150:153]
	s_waitcnt lgkmcnt(0)
	v_mfma_f32_16x16x32_bf16 v[18:21], v[226:229], v[18:21], v[146:149]
	v_mfma_f32_16x16x32_bf16 v[142:145], v[214:217], v[22:25], v[142:145]
	v_mfma_f32_16x16x32_bf16 v[138:141], v[218:221], v[22:25], v[138:141]
	v_mfma_f32_16x16x32_bf16 v[134:137], v[222:225], v[22:25], v[134:137]
	v_mfma_f32_16x16x32_bf16 v[22:25], v[226:229], v[22:25], v[130:133]
	v_mfma_f32_16x16x32_bf16 v[126:129], v[214:217], v[26:29], v[126:129]
	v_mfma_f32_16x16x32_bf16 v[122:125], v[218:221], v[26:29], v[122:125]
	v_mfma_f32_16x16x32_bf16 v[118:121], v[222:225], v[26:29], v[118:121]
	v_mfma_f32_16x16x32_bf16 v[26:29], v[226:229], v[26:29], v[114:117]
	v_mfma_f32_16x16x32_bf16 v[110:113], v[214:217], v[30:33], v[110:113]
	v_mfma_f32_16x16x32_bf16 v[106:109], v[218:221], v[30:33], v[106:109]
	v_mfma_f32_16x16x32_bf16 v[102:105], v[222:225], v[30:33], v[102:105]
	v_mfma_f32_16x16x32_bf16 v[30:33], v[226:229], v[30:33], v[98:101]
	v_mfma_f32_16x16x32_bf16 v[94:97], v[214:217], v[190:193], v[94:97]
	v_mfma_f32_16x16x32_bf16 v[90:93], v[218:221], v[190:193], v[90:93]
	v_mfma_f32_16x16x32_bf16 v[86:89], v[222:225], v[190:193], v[86:89]
	v_mfma_f32_16x16x32_bf16 v[82:85], v[226:229], v[190:193], v[82:85]
	v_mfma_f32_16x16x32_bf16 v[78:81], v[214:217], v[198:201], v[78:81]
	v_mfma_f32_16x16x32_bf16 v[74:77], v[218:221], v[198:201], v[74:77]
	v_mfma_f32_16x16x32_bf16 v[70:73], v[222:225], v[198:201], v[70:73]
	v_mfma_f32_16x16x32_bf16 v[66:69], v[226:229], v[198:201], v[66:69]
	v_mfma_f32_16x16x32_bf16 v[62:65], v[214:217], v[206:209], v[62:65]
	v_mfma_f32_16x16x32_bf16 v[58:61], v[218:221], v[206:209], v[58:61]
	v_mfma_f32_16x16x32_bf16 v[54:57], v[222:225], v[206:209], v[54:57]
	v_mfma_f32_16x16x32_bf16 v[50:53], v[226:229], v[206:209], v[50:53]
	v_mfma_f32_16x16x32_bf16 v[46:49], v[214:217], v[210:213], v[46:49]
	v_mfma_f32_16x16x32_bf16 v[42:45], v[218:221], v[210:213], v[42:45]
	v_mfma_f32_16x16x32_bf16 v[38:41], v[222:225], v[210:213], v[38:41]
	v_mfma_f32_16x16x32_bf16 v[34:37], v[226:229], v[210:213], v[34:37]
	s_setprio 0
	v_readlane_b32 s1, v254, 36
	v_mov_b32_e32 v169, v1
	s_nop 0
	v_add3_u32 v98, s1, v165, v167
	v_mov_b32_e32 v167, v1
	v_mov_b32_e32 v165, v1
	s_waitcnt vmcnt(7)
	ds_write_b128 v98, v[14:17]
	s_waitcnt vmcnt(6)
	ds_write_b128 v98, v[2:5] offset:8192
	s_waitcnt vmcnt(5)
	ds_write_b128 v98, v[6:9] offset:16384
	s_waitcnt vmcnt(4)
	ds_write_b128 v98, v[10:13] offset:24576
	v_lshl_add_u64 v[2:3], v[0:1], 1, s[6:7]
	v_lshl_add_u64 v[6:7], v[168:169], 1, s[6:7]
	v_lshl_add_u64 v[10:11], v[166:167], 1, s[6:7]
	v_lshl_add_u64 v[14:15], v[164:165], 1, s[6:7]
	global_load_dwordx4 v[2:5], v[2:3], off
	s_nop 0
	global_load_dwordx4 v[6:9], v[6:7], off
	s_nop 0
	global_load_dwordx4 v[10:13], v[10:11], off
	s_nop 0
	global_load_dwordx4 v[14:17], v[14:15], off
	v_lshlrev_b32_e32 v0, 1, v189
	v_add_u32_e32 v168, 0, v0
	v_add_u32_e32 v169, v168, v188
	ds_read_b128 v[98:101], v169
	ds_read_b128 v[114:117], v169 offset:2048
	ds_read_b128 v[130:133], v169 offset:4096
	ds_read_b128 v[146:149], v169 offset:6144
	ds_read_b128 v[164:167], v169 offset:8192
	ds_read_b128 v[190:193], v169 offset:10240
	ds_read_b128 v[198:201], v169 offset:12288
	ds_read_b128 v[206:209], v169 offset:14336
	v_add_u32_e32 v168, v168, v171
	ds_read_b128 v[210:213], v168 offset:32768
	ds_read_b128 v[214:217], v168 offset:34816
	ds_read_b128 v[218:221], v168 offset:36864
	ds_read_b128 v[222:225], v168 offset:38912
	s_setprio 1
	s_waitcnt lgkmcnt(3)
; DI void gemm8_accum(f32x4 (&acc)[8][4], const bf16_t* a, size_t lda, const bf16_t* b, size_t ldb, int nkb, bf16_t* L,
;                     const bool pre, const bf16_t* an, size_t ldan, const bf16_t* bn, size_t ldbn) {
;     ...
;   __syncthreads();
;   g8_store1(L, ra, lrow, lch);
;   __builtin_amdgcn_sched_barrier(0);
;   g8_compute<0, 1>(acc, L + 32768, wm, wn, lane);
;   __builtin_amdgcn_sched_barrier(0);
;   g8_store1(L + 16384, rb, lrow, lch);
;   __builtin_amdgcn_sched_barrier(0);
;   g8_compute<1, 2>(acc, L + 32768, wm, wn, lane);
	v_mfma_f32_16x16x32_bf16 v[158:161], v[210:213], v[98:101], v[158:161]
	s_waitcnt lgkmcnt(2)
	v_mfma_f32_16x16x32_bf16 v[154:157], v[214:217], v[98:101], v[154:157]
	s_waitcnt lgkmcnt(1)
	v_mfma_f32_16x16x32_bf16 v[150:153], v[218:221], v[98:101], v[150:153]
	s_waitcnt lgkmcnt(0)
	v_mfma_f32_16x16x32_bf16 v[18:21], v[222:225], v[98:101], v[18:21]
	v_mfma_f32_16x16x32_bf16 v[98:101], v[210:213], v[114:117], v[142:145]
	v_mfma_f32_16x16x32_bf16 v[138:141], v[214:217], v[114:117], v[138:141]
	v_mfma_f32_16x16x32_bf16 v[134:137], v[218:221], v[114:117], v[134:137]
	v_mfma_f32_16x16x32_bf16 v[22:25], v[222:225], v[114:117], v[22:25]
	v_mfma_f32_16x16x32_bf16 v[114:117], v[210:213], v[130:133], v[126:129]
	v_mfma_f32_16x16x32_bf16 v[122:125], v[214:217], v[130:133], v[122:125]
	v_mfma_f32_16x16x32_bf16 v[118:121], v[218:221], v[130:133], v[118:121]
	v_mfma_f32_16x16x32_bf16 v[26:29], v[222:225], v[130:133], v[26:29]
	v_mfma_f32_16x16x32_bf16 v[110:113], v[210:213], v[146:149], v[110:113]
	v_mfma_f32_16x16x32_bf16 v[106:109], v[214:217], v[146:149], v[106:109]
	v_mfma_f32_16x16x32_bf16 v[102:105], v[218:221], v[146:149], v[102:105]
	v_mfma_f32_16x16x32_bf16 v[30:33], v[222:225], v[146:149], v[30:33]
	v_mfma_f32_16x16x32_bf16 v[94:97], v[210:213], v[164:167], v[94:97]
	v_mfma_f32_16x16x32_bf16 v[90:93], v[214:217], v[164:167], v[90:93]
	v_mfma_f32_16x16x32_bf16 v[86:89], v[218:221], v[164:167], v[86:89]
	v_mfma_f32_16x16x32_bf16 v[82:85], v[222:225], v[164:167], v[82:85]
	v_mfma_f32_16x16x32_bf16 v[78:81], v[210:213], v[190:193], v[78:81]
	v_mfma_f32_16x16x32_bf16 v[74:77], v[214:217], v[190:193], v[74:77]
	v_mfma_f32_16x16x32_bf16 v[70:73], v[218:221], v[190:193], v[70:73]
	v_mfma_f32_16x16x32_bf16 v[66:69], v[222:225], v[190:193], v[66:69]
	v_mfma_f32_16x16x32_bf16 v[62:65], v[210:213], v[198:201], v[62:65]
	v_mfma_f32_16x16x32_bf16 v[58:61], v[214:217], v[198:201], v[58:61]
	v_mfma_f32_16x16x32_bf16 v[54:57], v[218:221], v[198:201], v[54:57]
	v_mfma_f32_16x16x32_bf16 v[50:53], v[222:225], v[198:201], v[50:53]
	v_mfma_f32_16x16x32_bf16 v[46:49], v[210:213], v[206:209], v[46:49]
	v_mfma_f32_16x16x32_bf16 v[42:45], v[214:217], v[206:209], v[42:45]
	v_mfma_f32_16x16x32_bf16 v[38:41], v[218:221], v[206:209], v[38:41]
	v_mfma_f32_16x16x32_bf16 v[34:37], v[222:225], v[206:209], v[34:37]
	s_setprio 0
	s_barrier
	s_waitcnt vmcnt(7)
	ds_write_b128 v163, v[172:175]
	s_waitcnt vmcnt(6)
	ds_write_b128 v163, v[176:179] offset:8192
	s_waitcnt vmcnt(5)
	ds_write_b128 v163, v[180:183] offset:16384
	s_waitcnt vmcnt(4)
	ds_write_b128 v163, v[184:187] offset:24576
	v_add3_u32 v168, s20, v170, v188
	ds_read_b128 v[126:129], v168
	ds_read_b128 v[130:133], v168 offset:2048
	ds_read_b128 v[142:145], v168 offset:4096
	ds_read_b128 v[146:149], v168 offset:6144
	ds_read_b128 v[164:167], v168 offset:8192
	ds_read_b128 v[172:175], v168 offset:10240
	ds_read_b128 v[176:179], v168 offset:12288
	ds_read_b128 v[180:183], v168 offset:14336
	v_add3_u32 v168, s1, v170, v171
	ds_read_b128 v[184:187], v168
	ds_read_b128 v[190:193], v168 offset:2048
	ds_read_b128 v[198:201], v168 offset:4096
	ds_read_b128 v[206:209], v168 offset:6144
	s_setprio 1
	s_waitcnt lgkmcnt(3)
	v_mfma_f32_16x16x32_bf16 v[158:161], v[184:187], v[126:129], v[158:161]
	s_waitcnt lgkmcnt(2)
	v_mfma_f32_16x16x32_bf16 v[154:157], v[190:193], v[126:129], v[154:157]
	s_waitcnt lgkmcnt(1)
	v_mfma_f32_16x16x32_bf16 v[150:153], v[198:201], v[126:129], v[150:153]
	s_waitcnt lgkmcnt(0)
	v_mfma_f32_16x16x32_bf16 v[18:21], v[206:209], v[126:129], v[18:21]
	v_mfma_f32_16x16x32_bf16 v[98:101], v[184:187], v[130:133], v[98:101]
	v_mfma_f32_16x16x32_bf16 v[126:129], v[190:193], v[130:133], v[138:141]
	v_mfma_f32_16x16x32_bf16 v[134:137], v[198:201], v[130:133], v[134:137]
	v_mfma_f32_16x16x32_bf16 v[130:133], v[206:209], v[130:133], v[22:25]
	v_mfma_f32_16x16x32_bf16 v[114:117], v[184:187], v[142:145], v[114:117]
	v_mfma_f32_16x16x32_bf16 v[122:125], v[190:193], v[142:145], v[122:125]
	v_mfma_f32_16x16x32_bf16 v[118:121], v[198:201], v[142:145], v[118:121]
	v_mfma_f32_16x16x32_bf16 v[26:29], v[206:209], v[142:145], v[26:29]
	v_mfma_f32_16x16x32_bf16 v[110:113], v[184:187], v[146:149], v[110:113]
	v_mfma_f32_16x16x32_bf16 v[106:109], v[190:193], v[146:149], v[106:109]
	v_mfma_f32_16x16x32_bf16 v[102:105], v[198:201], v[146:149], v[102:105]
	v_mfma_f32_16x16x32_bf16 v[138:141], v[206:209], v[146:149], v[30:33]
	v_mfma_f32_16x16x32_bf16 v[142:145], v[184:187], v[164:167], v[94:97]
	v_mfma_f32_16x16x32_bf16 v[90:93], v[190:193], v[164:167], v[90:93]
	v_mfma_f32_16x16x32_bf16 v[146:149], v[198:201], v[164:167], v[86:89]
	v_mfma_f32_16x16x32_bf16 v[82:85], v[206:209], v[164:167], v[82:85]
	v_mfma_f32_16x16x32_bf16 v[164:167], v[184:187], v[172:175], v[78:81]
	v_mfma_f32_16x16x32_bf16 v[74:77], v[190:193], v[172:175], v[74:77]
	v_mfma_f32_16x16x32_bf16 v[210:213], v[198:201], v[172:175], v[70:73]
	v_mfma_f32_16x16x32_bf16 v[66:69], v[206:209], v[172:175], v[66:69]
	v_mfma_f32_16x16x32_bf16 v[172:175], v[184:187], v[176:179], v[62:65]
	v_mfma_f32_16x16x32_bf16 v[58:61], v[190:193], v[176:179], v[58:61]
	v_mfma_f32_16x16x32_bf16 v[214:217], v[198:201], v[176:179], v[54:57]
	v_mfma_f32_16x16x32_bf16 v[50:53], v[206:209], v[176:179], v[50:53]
	v_mfma_f32_16x16x32_bf16 v[176:179], v[184:187], v[180:183], v[46:49]
	v_mfma_f32_16x16x32_bf16 v[184:187], v[190:193], v[180:183], v[42:45]
	v_mfma_f32_16x16x32_bf16 v[190:193], v[198:201], v[180:183], v[38:41]
	v_mfma_f32_16x16x32_bf16 v[180:183], v[206:209], v[180:183], v[34:37]
	s_setprio 0
	s_waitcnt vmcnt(3)
	ds_write_b128 v163, v[2:5] offset:32768
	s_waitcnt vmcnt(2)
; DI float bflo(unsigned u) { return __uint_as_float(u << 16); }
; DI float bfhi(unsigned u) { return __uint_as_float(u & 0xffff0000u); }
; DI float sigmoidf(float x) { return __builtin_amdgcn_rcpf(1.f + __expf(-x)); }
; DI float inv_sigmoidf(float x) { return 1.f + __expf(-x); }
; DI void gemm8_accum(f32x4 (&acc)[8][4], const bf16_t* a, size_t lda, const bf16_t* b, size_t ldb, int nkb, bf16_t* L,
;                     const bool pre, const bf16_t* an, size_t ldan, const bf16_t* bn, size_t ldbn) {
;     ...
;   g8_store1(L + 16384, rb, lrow, lch);
;   __builtin_amdgcn_sched_barrier(0);
;   g8_compute<1, 2>(acc, L + 32768, wm, wn, lane);
;   __syncthreads();
; __global__ void __launch_bounds__(512, 2) mega(Params p) {
;     ...
;       gemm8_epi(acc8, m0, n0, [&](int m, int n, f32x4& a) {
;         uint2 ua = *(const uint2*)(z + (size_t)m * ZS + C_MA + n);
;         uint2 ub = *(const uint2*)(z + (size_t)m * ZS + C_MB + n);
;         a[0] *= sigmoidf(bflo(ua.x)) * inv_sigmoidf(bflo(ub.x));
;         a[1] *= sigmoidf(bfhi(ua.x)) * inv_sigmoidf(bfhi(ub.x));
;         a[2] *= sigmoidf(bflo(ua.y)) * inv_sigmoidf(bflo(ub.y));
;         a[3] *= sigmoidf(bfhi(ua.y)) * inv_sigmoidf(bfhi(ub.y));
;       });
	ds_write_b128 v163, v[6:9] offset:40960
	s_waitcnt vmcnt(1)
	ds_write_b128 v163, v[10:13] offset:49152
	s_waitcnt vmcnt(0)
	ds_write_b128 v163, v[14:17] offset:57344
	v_add3_u32 v6, s20, v0, v188
	ds_read_b128 v[2:5], v6
	ds_read_b128 v[34:37], v6 offset:2048
	ds_read_b128 v[42:45], v6 offset:4096
	ds_read_b128 v[198:201], v6 offset:6144
	ds_read_b128 v[206:209], v6 offset:8192
	ds_read_b128 v[218:221], v6 offset:10240
	ds_read_b128 v[222:225], v6 offset:12288
	ds_read_b128 v[226:229], v6 offset:14336
	v_add3_u32 v0, s1, v0, v171
	ds_read_b128 v[168:171], v0
	ds_read_b128 v[230:233], v0 offset:2048
	ds_read_b128 v[234:237], v0 offset:4096
	ds_read_b128 v[238:241], v0 offset:6144
	s_setprio 1
	s_waitcnt lgkmcnt(3)
	v_mfma_f32_16x16x32_bf16 v[158:161], v[168:171], v[2:5], v[158:161]
	s_waitcnt lgkmcnt(2)
	v_mfma_f32_16x16x32_bf16 v[6:9], v[230:233], v[2:5], v[154:157]
	s_waitcnt lgkmcnt(1)
	v_mfma_f32_16x16x32_bf16 v[10:13], v[234:237], v[2:5], v[150:153]
	s_waitcnt lgkmcnt(0)
	v_mfma_f32_16x16x32_bf16 v[14:17], v[238:241], v[2:5], v[18:21]
	v_mfma_f32_16x16x32_bf16 v[22:25], v[168:171], v[34:37], v[98:101]
	v_mfma_f32_16x16x32_bf16 v[30:33], v[230:233], v[34:37], v[126:129]
	v_mfma_f32_16x16x32_bf16 v[38:41], v[234:237], v[34:37], v[134:137]
	v_mfma_f32_16x16x32_bf16 v[46:49], v[238:241], v[34:37], v[130:133]
	v_mfma_f32_16x16x32_bf16 v[54:57], v[168:171], v[42:45], v[114:117]
	v_mfma_f32_16x16x32_bf16 v[62:65], v[230:233], v[42:45], v[122:125]
	v_mfma_f32_16x16x32_bf16 v[70:73], v[234:237], v[42:45], v[118:121]
	v_mfma_f32_16x16x32_bf16 v[78:81], v[238:241], v[42:45], v[26:29]
	v_mfma_f32_16x16x32_bf16 v[86:89], v[168:171], v[198:201], v[110:113]
	v_mfma_f32_16x16x32_bf16 v[94:97], v[230:233], v[198:201], v[106:109]
	v_mfma_f32_16x16x32_bf16 v[102:105], v[234:237], v[198:201], v[102:105]
	v_mfma_f32_16x16x32_bf16 v[110:113], v[238:241], v[198:201], v[138:141]
	v_mfma_f32_16x16x32_bf16 v[118:121], v[168:171], v[206:209], v[142:145]
	v_mfma_f32_16x16x32_bf16 v[126:129], v[230:233], v[206:209], v[90:93]
	v_mfma_f32_16x16x32_bf16 v[122:125], v[234:237], v[206:209], v[146:149]
	v_mfma_f32_16x16x32_bf16 v[114:117], v[238:241], v[206:209], v[82:85]
	v_mfma_f32_16x16x32_bf16 v[106:109], v[168:171], v[218:221], v[164:167]
	v_mfma_f32_16x16x32_bf16 v[98:101], v[230:233], v[218:221], v[74:77]
	v_mfma_f32_16x16x32_bf16 v[90:93], v[234:237], v[218:221], v[210:213]
	v_mfma_f32_16x16x32_bf16 v[82:85], v[238:241], v[218:221], v[66:69]
	v_mfma_f32_16x16x32_bf16 v[74:77], v[168:171], v[222:225], v[172:175]
	v_mfma_f32_16x16x32_bf16 v[66:69], v[230:233], v[222:225], v[58:61]
	v_mfma_f32_16x16x32_bf16 v[58:61], v[234:237], v[222:225], v[214:217]
	v_mfma_f32_16x16x32_bf16 v[50:53], v[238:241], v[222:225], v[50:53]
	v_mfma_f32_16x16x32_bf16 v[42:45], v[168:171], v[226:229], v[176:179]
	v_mfma_f32_16x16x32_bf16 v[34:37], v[230:233], v[226:229], v[184:187]
	v_mfma_f32_16x16x32_bf16 v[26:29], v[234:237], v[226:229], v[190:193]
	v_mfma_f32_16x16x32_bf16 v[18:21], v[238:241], v[226:229], v[180:183]
	s_setprio 0
	v_mov_b32_e32 v0, v196
	s_barrier
	v_mov_b64_e32 v[136:137], s[16:17]
	v_ashrrev_i32_e32 v3, 1, v0
	v_and_b32_e32 v2, 0xc0, v0
	v_and_b32_e32 v3, 0xffffff80, v3
	v_and_or_b32 v4, v0, 15, s13
	v_lshrrev_b32_e32 v0, 2, v0
	v_add_u32_e32 v142, v4, v3
	v_and_b32_e32 v0, 12, v0
	v_or3_b32 v0, v2, v0, s12
	v_mad_i64_i32 v[2:3], s[26:27], v142, s35, v[136:137]
	s_mov_b64 s[30:31], 0x1a30
	s_mov_b64 s[42:43], 0x2230
	v_lshl_add_u64 v[138:139], v[2:3], 0, s[30:31]
	v_lshlrev_b32_e32 v0, 1, v0
	v_lshl_add_u64 v[140:141], v[2:3], 0, s[42:43]
	v_lshl_add_u64 v[4:5], v[138:139], 0, v[0:1]
	v_lshl_add_u64 v[2:3], v[140:141], 0, v[0:1]
	global_load_dwordx2 v[4:5], v[4:5], off
	v_or_b32_e32 v134, 32, v0
	global_load_dwordx2 v[2:3], v[2:3], off
	v_mov_b32_e32 v135, v1
	v_mov_b32_e32 v172, v196
	s_movk_i32 s1, 0x3c0
	s_movk_i32 s96, 0x1518
	s_waitcnt vmcnt(1)
	v_lshlrev_b32_e32 v130, 16, v4
	v_and_b32_e32 v4, 0xffff0000, v4
	s_waitcnt vmcnt(0)
	v_lshlrev_b32_e32 v131, 16, v2
	v_and_b32_e32 v2, 0xffff0000, v2
	v_mul_f32_e32 v2, 0xbfb8aa3b, v2
	v_exp_f32_e32 v133, v2
	v_lshlrev_b32_e32 v2, 16, v5
	v_mul_f32_e32 v4, 0xbfb8aa3b, v4
	v_mul_f32_e32 v2, 0xbfb8aa3b, v2
	v_exp_f32_e32 v4, v4
	v_exp_f32_e32 v2, v2
	v_and_b32_e32 v5, 0xffff0000, v5
	v_mul_f32_e32 v130, 0xbfb8aa3b, v130
	v_mul_f32_e32 v5, 0xbfb8aa3b, v5
	v_exp_f32_e32 v130, v130
	v_exp_f32_e32 v5, v5
	v_mul_f32_e32 v131, 0xbfb8aa3b, v131
	v_add_f32_e32 v4, 1.0, v4
	v_add_f32_e32 v2, 1.0, v2
	v_exp_f32_e32 v132, v131
	v_rcp_f32_e32 v131, v4
	v_rcp_f32_e32 v4, v2
	v_lshlrev_b32_e32 v2, 16, v3
	v_and_b32_e32 v3, 0xffff0000, v3
	v_mul_f32_e32 v2, 0xbfb8aa3b, v2
	v_mul_f32_e32 v3, 0xbfb8aa3b, v3
	v_add_f32_e32 v130, 1.0, v130
	v_exp_f32_e32 v2, v2
	v_add_f32_e32 v5, 1.0, v5
	v_exp_f32_e32 v3, v3
	v_rcp_f32_e32 v130, v130
	v_rcp_f32_e32 v5, v5
	v_pk_add_f32 v[132:133], v[132:133], 1.0 op_sel_hi:[1,0]
	v_pk_add_f32 v[2:3], v[2:3], 1.0 op_sel_hi:[1,0]
	v_pk_mul_f32 v[130:131], v[130:131], v[132:133]
	v_pk_mul_f32 v[2:3], v[4:5], v[2:3]
	v_lshl_add_u64 v[132:133], v[140:141], 0, v[134:135]
	v_pk_mul_f32 v[4:5], v[160:161], v[2:3]
	v_pk_mul_f32 v[2:3], v[158:159], v[130:131]
	v_lshl_add_u64 v[130:131], v[138:139], 0, v[134:135]
	global_load_dwordx2 v[130:131], v[130:131], off
	s_nop 0
	global_load_dwordx2 v[132:133], v[132:133], off
	s_waitcnt vmcnt(1)
	v_lshlrev_b32_e32 v143, 16, v130
	v_and_b32_e32 v130, 0xffff0000, v130
	v_mul_f32_e32 v130, 0xbfb8aa3b, v130
	v_exp_f32_e32 v130, v130
	v_mul_f32_e32 v143, 0xbfb8aa3b, v143
	v_exp_f32_e32 v143, v143
	v_add_f32_e32 v130, 1.0, v130
	v_rcp_f32_e32 v145, v130
	s_waitcnt vmcnt(0)
; DI float bflo(unsigned u) { return __uint_as_float(u << 16); }
; DI float bfhi(unsigned u) { return __uint_as_float(u & 0xffff0000u); }
; DI float sigmoidf(float x) { return __builtin_amdgcn_rcpf(1.f + __expf(-x)); }
; DI float inv_sigmoidf(float x) { return 1.f + __expf(-x); }
; DI int TID8() { int t = threadIdx.x; asm volatile("" : "+v"(t)); return t; }
; template <class E>
; DI void gemm8_epi(f32x4 (&acc)[8][4], int m0, int n0, E e) {
;   const int tid = TID8(), lane = tid & 63, w = tid >> 6;
;   const int wm = w >> 2, wn = w & 3;
; #pragma unroll
;   for (int i = 0; i < 8; ++i)
; #pragma unroll
;     for (int j = 0; j < 4; ++j) {
;       const int m = m0 + wm * 128 + i * 16 + (lane & 15);
;       const int n = n0 + wn * 64 + j * 16 + (lane >> 4) * 4;
;       e(m, n, acc[i][j]);
;     }
; }
; __global__ void __launch_bounds__(512, 2) mega(Params p) {
;     ...
;       gemm8_epi(acc8, m0, n0, [&](int m, int n, f32x4& a) {
;         uint2 ua = *(const uint2*)(z + (size_t)m * ZS + C_MA + n);
;         uint2 ub = *(const uint2*)(z + (size_t)m * ZS + C_MB + n);
;         a[0] *= sigmoidf(bflo(ua.x)) * inv_sigmoidf(bflo(ub.x));
;         a[1] *= sigmoidf(bfhi(ua.x)) * inv_sigmoidf(bfhi(ub.x));
;         a[2] *= sigmoidf(bflo(ua.y)) * inv_sigmoidf(bflo(ub.y));
;         a[3] *= sigmoidf(bfhi(ua.y)) * inv_sigmoidf(bfhi(ub.y));
;       });
	v_and_b32_e32 v130, 0xffff0000, v132
	v_mul_f32_e32 v130, 0xbfb8aa3b, v130
	v_exp_f32_e32 v147, v130
	v_lshlrev_b32_e32 v130, 16, v131
	v_and_b32_e32 v131, 0xffff0000, v131
	v_mul_f32_e32 v130, 0xbfb8aa3b, v130
	v_mul_f32_e32 v131, 0xbfb8aa3b, v131
	v_exp_f32_e32 v130, v130
	v_exp_f32_e32 v131, v131
	v_add_f32_e32 v143, 1.0, v143
	v_rcp_f32_e32 v144, v143
	v_lshlrev_b32_e32 v143, 16, v132
	v_lshlrev_b32_e32 v132, 16, v133
	v_and_b32_e32 v133, 0xffff0000, v133
	v_mul_f32_e32 v132, 0xbfb8aa3b, v132
	v_mul_f32_e32 v133, 0xbfb8aa3b, v133
	v_add_f32_e32 v130, 1.0, v130
	v_exp_f32_e32 v132, v132
	v_add_f32_e32 v131, 1.0, v131
	v_exp_f32_e32 v133, v133
	v_rcp_f32_e32 v130, v130
	v_rcp_f32_e32 v131, v131
	v_mul_f32_e32 v143, 0xbfb8aa3b, v143
	v_pk_add_f32 v[132:133], v[132:133], 1.0 op_sel_hi:[1,0]
	v_exp_f32_e32 v146, v143
	v_pk_mul_f32 v[130:131], v[130:131], v[132:133]
	v_or_b32_e32 v132, 64, v0
	v_mov_b32_e32 v133, v1
	v_pk_mul_f32 v[8:9], v[8:9], v[130:131]
	v_lshl_add_u64 v[130:131], v[138:139], 0, v[132:133]
	global_load_dwordx2 v[130:131], v[130:131], off
	v_pk_add_f32 v[146:147], v[146:147], 1.0 op_sel_hi:[1,0]
	s_nop 0
	v_pk_mul_f32 v[144:145], v[144:145], v[146:147]
	s_nop 0
	v_pk_mul_f32 v[6:7], v[6:7], v[144:145]
	v_lshl_add_u64 v[144:145], v[140:141], 0, v[132:133]
	global_load_dwordx2 v[144:145], v[144:145], off
	s_waitcnt vmcnt(1)
	v_lshlrev_b32_e32 v143, 16, v130
	v_and_b32_e32 v130, 0xffff0000, v130
	v_mul_f32_e32 v130, 0xbfb8aa3b, v130
	v_exp_f32_e32 v130, v130
	v_mul_f32_e32 v143, 0xbfb8aa3b, v143
	v_exp_f32_e32 v143, v143
	v_add_f32_e32 v130, 1.0, v130
	v_rcp_f32_e32 v147, v130
	s_waitcnt vmcnt(0)
	v_and_b32_e32 v130, 0xffff0000, v144
	v_add_f32_e32 v143, 1.0, v143
	v_mul_f32_e32 v130, 0xbfb8aa3b, v130
	v_rcp_f32_e32 v146, v143
	v_lshlrev_b32_e32 v143, 16, v144
	v_exp_f32_e32 v149, v130
	v_lshlrev_b32_e32 v130, 16, v131
	v_and_b32_e32 v131, 0xffff0000, v131
	v_mul_f32_e32 v143, 0xbfb8aa3b, v143
	v_mul_f32_e32 v130, 0xbfb8aa3b, v130
	v_mul_f32_e32 v131, 0xbfb8aa3b, v131
	v_exp_f32_e32 v148, v143
	v_exp_f32_e32 v130, v130
	v_lshlrev_b32_e32 v143, 16, v145
	v_exp_f32_e32 v131, v131
	v_mul_f32_e32 v143, 0xbfb8aa3b, v143
	v_exp_f32_e32 v144, v143
	v_and_b32_e32 v143, 0xffff0000, v145
	v_mul_f32_e32 v143, 0xbfb8aa3b, v143
	v_add_f32_e32 v130, 1.0, v130
	v_add_f32_e32 v131, 1.0, v131
	v_exp_f32_e32 v145, v143
	v_rcp_f32_e32 v130, v130
	v_rcp_f32_e32 v131, v131
	v_pk_add_f32 v[148:149], v[148:149], 1.0 op_sel_hi:[1,0]
	v_pk_add_f32 v[144:145], v[144:145], 1.0 op_sel_hi:[1,0]
	v_pk_mul_f32 v[146:147], v[146:147], v[148:149]
	v_pk_mul_f32 v[130:131], v[130:131], v[144:145]
	v_pk_mul_f32 v[10:11], v[10:11], v[146:147]
	v_pk_mul_f32 v[12:13], v[12:13], v[130:131]
	v_or_b32_e32 v130, 0x60, v0
	v_mov_b32_e32 v131, v1
	v_lshl_add_u64 v[138:139], v[138:139], 0, v[130:131]
	global_load_dwordx2 v[138:139], v[138:139], off
	v_lshl_add_u64 v[140:141], v[140:141], 0, v[130:131]
	global_load_dwordx2 v[140:141], v[140:141], off
	s_waitcnt vmcnt(1)
	v_lshlrev_b32_e32 v143, 16, v138
	v_and_b32_e32 v138, 0xffff0000, v138
	v_mul_f32_e32 v138, 0xbfb8aa3b, v138
	v_exp_f32_e32 v138, v138
	v_mul_f32_e32 v143, 0xbfb8aa3b, v143
	v_exp_f32_e32 v143, v143
	v_add_f32_e32 v138, 1.0, v138
	v_rcp_f32_e32 v145, v138
	s_waitcnt vmcnt(0)
	v_and_b32_e32 v138, 0xffff0000, v140
	v_mul_f32_e32 v138, 0xbfb8aa3b, v138
	v_exp_f32_e32 v147, v138
	v_lshlrev_b32_e32 v138, 16, v139
	v_and_b32_e32 v139, 0xffff0000, v139
	v_mul_f32_e32 v138, 0xbfb8aa3b, v138
	v_mul_f32_e32 v139, 0xbfb8aa3b, v139
	v_exp_f32_e32 v138, v138
	v_exp_f32_e32 v139, v139
	v_add_f32_e32 v143, 1.0, v143
	v_rcp_f32_e32 v144, v143
	v_lshlrev_b32_e32 v143, 16, v140
	v_lshlrev_b32_e32 v140, 16, v141
	v_and_b32_e32 v141, 0xffff0000, v141
	v_mul_f32_e32 v140, 0xbfb8aa3b, v140
	v_mul_f32_e32 v141, 0xbfb8aa3b, v141
	v_add_f32_e32 v138, 1.0, v138
	v_exp_f32_e32 v140, v140
	v_add_f32_e32 v139, 1.0, v139
	v_exp_f32_e32 v141, v141
	v_rcp_f32_e32 v138, v138
	v_rcp_f32_e32 v139, v139
	v_mul_f32_e32 v143, 0xbfb8aa3b, v143
	v_exp_f32_e32 v146, v143
	v_pk_add_f32 v[140:141], v[140:141], 1.0 op_sel_hi:[1,0]
	v_pk_add_f32 v[146:147], v[146:147], 1.0 op_sel_hi:[1,0]
	v_pk_mul_f32 v[138:139], v[138:139], v[140:141]
	v_pk_mul_f32 v[144:145], v[144:145], v[146:147]
	v_pk_mul_f32 v[16:17], v[16:17], v[138:139]
	v_or_b32_e32 v138, 16, v142
	v_mad_i64_i32 v[140:141], s[26:27], v138, s35, v[136:137]
	v_lshl_add_u64 v[138:139], v[140:141], 0, s[30:31]
	v_pk_mul_f32 v[14:15], v[14:15], v[144:145]
	v_lshl_add_u64 v[144:145], v[138:139], 0, v[0:1]
	global_load_dwordx2 v[144:145], v[144:145], off
	v_lshl_add_u64 v[140:141], v[140:141], 0, s[42:43]
	v_lshl_add_u64 v[146:147], v[140:141], 0, v[0:1]
	global_load_dwordx2 v[146:147], v[146:147], off
	s_waitcnt vmcnt(1)
	v_lshlrev_b32_e32 v143, 16, v144
	v_mul_f32_e32 v143, 0xbfb8aa3b, v143
	v_exp_f32_e32 v143, v143
	s_nop 0
	v_add_f32_e32 v143, 1.0, v143
	v_rcp_f32_e32 v148, v143
	s_waitcnt vmcnt(0)
; DI float bflo(unsigned u) { return __uint_as_float(u << 16); }
; DI float bfhi(unsigned u) { return __uint_as_float(u & 0xffff0000u); }
; DI float sigmoidf(float x) { return __builtin_amdgcn_rcpf(1.f + __expf(-x)); }
; DI float inv_sigmoidf(float x) { return 1.f + __expf(-x); }
; DI int TID8() { int t = threadIdx.x; asm volatile("" : "+v"(t)); return t; }
; template <class E>
; DI void gemm8_epi(f32x4 (&acc)[8][4], int m0, int n0, E e) {
;   const int tid = TID8(), lane = tid & 63, w = tid >> 6;
;   const int wm = w >> 2, wn = w & 3;
; #pragma unroll
;   for (int i = 0; i < 8; ++i)
; #pragma unroll
;     for (int j = 0; j < 4; ++j) {
;       const int m = m0 + wm * 128 + i * 16 + (lane & 15);
;       const int n = n0 + wn * 64 + j * 16 + (lane >> 4) * 4;
;       e(m, n, acc[i][j]);
;     }
; }
; __global__ void __launch_bounds__(512, 2) mega(Params p) {
;     ...
;       gemm8_epi(acc8, m0, n0, [&](int m, int n, f32x4& a) {
;         uint2 ua = *(const uint2*)(z + (size_t)m * ZS + C_MA + n);
;         uint2 ub = *(const uint2*)(z + (size_t)m * ZS + C_MB + n);
;         a[0] *= sigmoidf(bflo(ua.x)) * inv_sigmoidf(bflo(ub.x));
;         a[1] *= sigmoidf(bfhi(ua.x)) * inv_sigmoidf(bfhi(ub.x));
;         a[2] *= sigmoidf(bflo(ua.y)) * inv_sigmoidf(bflo(ub.y));
;         a[3] *= sigmoidf(bfhi(ua.y)) * inv_sigmoidf(bfhi(ub.y));
;       });
	v_lshlrev_b32_e32 v143, 16, v146
	v_mul_f32_e32 v143, 0xbfb8aa3b, v143
	v_exp_f32_e32 v150, v143
	v_and_b32_e32 v143, 0xffff0000, v144
	v_mul_f32_e32 v143, 0xbfb8aa3b, v143
	v_exp_f32_e32 v143, v143
	s_nop 0
	v_add_f32_e32 v143, 1.0, v143
	v_rcp_f32_e32 v149, v143
	v_and_b32_e32 v143, 0xffff0000, v146
	v_mul_f32_e32 v143, 0xbfb8aa3b, v143
	v_exp_f32_e32 v151, v143
	v_lshlrev_b32_e32 v143, 16, v145
	v_mul_f32_e32 v143, 0xbfb8aa3b, v143
	v_exp_f32_e32 v143, v143
	v_pk_add_f32 v[150:151], v[150:151], 1.0 op_sel_hi:[1,0]
	v_add_f32_e32 v143, 1.0, v143
	v_rcp_f32_e32 v144, v143
	v_lshlrev_b32_e32 v143, 16, v147
	v_mul_f32_e32 v143, 0xbfb8aa3b, v143
	v_exp_f32_e32 v146, v143
	v_and_b32_e32 v143, 0xffff0000, v145
	v_mul_f32_e32 v143, 0xbfb8aa3b, v143
	v_exp_f32_e32 v143, v143
	v_pk_mul_f32 v[148:149], v[148:149], v[150:151]
	v_add_f32_e32 v143, 1.0, v143
	v_rcp_f32_e32 v145, v143
	v_and_b32_e32 v143, 0xffff0000, v147
	v_mul_f32_e32 v143, 0xbfb8aa3b, v143
	v_exp_f32_e32 v147, v143
	v_pk_mul_f32 v[22:23], v[22:23], v[148:149]
	v_pk_add_f32 v[146:147], v[146:147], 1.0 op_sel_hi:[1,0]
	s_nop 0
	v_pk_mul_f32 v[144:145], v[144:145], v[146:147]
	v_lshl_add_u64 v[146:147], v[140:141], 0, v[134:135]
	v_pk_mul_f32 v[24:25], v[24:25], v[144:145]
	v_lshl_add_u64 v[144:145], v[138:139], 0, v[134:135]
	global_load_dwordx2 v[144:145], v[144:145], off
	s_nop 0
	global_load_dwordx2 v[146:147], v[146:147], off
	s_waitcnt vmcnt(1)
	v_lshlrev_b32_e32 v143, 16, v144
	v_mul_f32_e32 v143, 0xbfb8aa3b, v143
	v_exp_f32_e32 v143, v143
	s_nop 0
	v_add_f32_e32 v143, 1.0, v143
	v_rcp_f32_e32 v148, v143
	s_waitcnt vmcnt(0)
	v_lshlrev_b32_e32 v143, 16, v146
	v_mul_f32_e32 v143, 0xbfb8aa3b, v143
	v_exp_f32_e32 v150, v143
	v_and_b32_e32 v143, 0xffff0000, v144
	v_mul_f32_e32 v143, 0xbfb8aa3b, v143
	v_exp_f32_e32 v143, v143
	s_nop 0
	v_add_f32_e32 v143, 1.0, v143
	v_rcp_f32_e32 v149, v143
	v_and_b32_e32 v143, 0xffff0000, v146
	v_mul_f32_e32 v143, 0xbfb8aa3b, v143
	v_exp_f32_e32 v151, v143
	v_lshlrev_b32_e32 v143, 16, v145
	v_mul_f32_e32 v143, 0xbfb8aa3b, v143
	v_exp_f32_e32 v143, v143
	v_pk_add_f32 v[150:151], v[150:151], 1.0 op_sel_hi:[1,0]
	v_add_f32_e32 v143, 1.0, v143
	v_rcp_f32_e32 v144, v143
	v_lshlrev_b32_e32 v143, 16, v147
	v_mul_f32_e32 v143, 0xbfb8aa3b, v143
	v_exp_f32_e32 v146, v143
	v_and_b32_e32 v143, 0xffff0000, v145
	v_mul_f32_e32 v143, 0xbfb8aa3b, v143
	v_exp_f32_e32 v143, v143
	v_pk_mul_f32 v[148:149], v[148:149], v[150:151]
	v_add_f32_e32 v143, 1.0, v143
	v_rcp_f32_e32 v145, v143
	v_and_b32_e32 v143, 0xffff0000, v147
	v_mul_f32_e32 v143, 0xbfb8aa3b, v143
	v_exp_f32_e32 v147, v143
	v_pk_mul_f32 v[30:31], v[30:31], v[148:149]
	v_pk_add_f32 v[146:147], v[146:147], 1.0 op_sel_hi:[1,0]
	s_nop 0
	v_pk_mul_f32 v[144:145], v[144:145], v[146:147]
	v_lshl_add_u64 v[146:147], v[140:141], 0, v[132:133]
	v_pk_mul_f32 v[32:33], v[32:33], v[144:145]
	v_lshl_add_u64 v[144:145], v[138:139], 0, v[132:133]
	global_load_dwordx2 v[144:145], v[144:145], off
	v_lshl_add_u64 v[138:139], v[138:139], 0, v[130:131]
	global_load_dwordx2 v[146:147], v[146:147], off
	v_lshl_add_u64 v[140:141], v[140:141], 0, v[130:131]
	global_load_dwordx2 v[138:139], v[138:139], off
	s_nop 0
	global_load_dwordx2 v[140:141], v[140:141], off
	s_waitcnt vmcnt(3)
	v_lshlrev_b32_e32 v143, 16, v144
	v_mul_f32_e32 v143, 0xbfb8aa3b, v143
	v_exp_f32_e32 v143, v143
	s_nop 0
	v_add_f32_e32 v143, 1.0, v143
	v_rcp_f32_e32 v148, v143
	s_waitcnt vmcnt(2)
	v_lshlrev_b32_e32 v143, 16, v146
	v_mul_f32_e32 v143, 0xbfb8aa3b, v143
	v_exp_f32_e32 v150, v143
	v_and_b32_e32 v143, 0xffff0000, v144
	v_mul_f32_e32 v143, 0xbfb8aa3b, v143
	v_exp_f32_e32 v143, v143
	s_nop 0
	v_add_f32_e32 v143, 1.0, v143
	v_rcp_f32_e32 v149, v143
	v_and_b32_e32 v143, 0xffff0000, v146
	v_mul_f32_e32 v143, 0xbfb8aa3b, v143
	v_exp_f32_e32 v151, v143
	v_lshlrev_b32_e32 v143, 16, v145
	v_mul_f32_e32 v143, 0xbfb8aa3b, v143
	v_exp_f32_e32 v143, v143
	v_pk_add_f32 v[150:151], v[150:151], 1.0 op_sel_hi:[1,0]
	v_add_f32_e32 v143, 1.0, v143
	v_rcp_f32_e32 v144, v143
	v_lshlrev_b32_e32 v143, 16, v147
	v_mul_f32_e32 v143, 0xbfb8aa3b, v143
	v_exp_f32_e32 v146, v143
	v_and_b32_e32 v143, 0xffff0000, v145
	v_mul_f32_e32 v143, 0xbfb8aa3b, v143
	v_exp_f32_e32 v143, v143
	v_pk_mul_f32 v[148:149], v[148:149], v[150:151]
	v_add_f32_e32 v143, 1.0, v143
	v_rcp_f32_e32 v145, v143
	v_and_b32_e32 v143, 0xffff0000, v147
	v_mul_f32_e32 v143, 0xbfb8aa3b, v143
	v_exp_f32_e32 v147, v143
	s_waitcnt vmcnt(1)
	v_lshlrev_b32_e32 v143, 16, v138
	v_and_b32_e32 v138, 0xffff0000, v138
	v_mul_f32_e32 v138, 0xbfb8aa3b, v138
	v_exp_f32_e32 v138, v138
	v_pk_add_f32 v[146:147], v[146:147], 1.0 op_sel_hi:[1,0]
	v_mul_f32_e32 v143, 0xbfb8aa3b, v143
	v_pk_mul_f32 v[144:145], v[144:145], v[146:147]
	v_add_f32_e32 v138, 1.0, v138
	v_pk_mul_f32 v[40:41], v[40:41], v[144:145]
	v_rcp_f32_e32 v145, v138
	s_waitcnt vmcnt(0)
	v_and_b32_e32 v138, 0xffff0000, v140
	v_exp_f32_e32 v143, v143
	v_mul_f32_e32 v138, 0xbfb8aa3b, v138
	v_exp_f32_e32 v147, v138
	v_lshlrev_b32_e32 v138, 16, v139
	v_and_b32_e32 v139, 0xffff0000, v139
	v_mul_f32_e32 v138, 0xbfb8aa3b, v138
	v_mul_f32_e32 v139, 0xbfb8aa3b, v139
	v_exp_f32_e32 v138, v138
	v_exp_f32_e32 v139, v139
	v_add_f32_e32 v143, 1.0, v143
	v_rcp_f32_e32 v144, v143
	v_lshlrev_b32_e32 v143, 16, v140
	v_lshlrev_b32_e32 v140, 16, v141
	v_and_b32_e32 v141, 0xffff0000, v141
	v_mul_f32_e32 v140, 0xbfb8aa3b, v140
	v_mul_f32_e32 v141, 0xbfb8aa3b, v141
	v_add_f32_e32 v138, 1.0, v138
	v_exp_f32_e32 v140, v140
	v_add_f32_e32 v139, 1.0, v139
	v_exp_f32_e32 v141, v141
	v_rcp_f32_e32 v138, v138
	v_rcp_f32_e32 v139, v139
	v_mul_f32_e32 v143, 0xbfb8aa3b, v143
	v_exp_f32_e32 v146, v143
	v_pk_add_f32 v[140:141], v[140:141], 1.0 op_sel_hi:[1,0]
	v_pk_mul_f32 v[38:39], v[38:39], v[148:149]
	v_pk_mul_f32 v[138:139], v[138:139], v[140:141]
	v_pk_add_f32 v[146:147], v[146:147], 1.0 op_sel_hi:[1,0]
	v_pk_mul_f32 v[48:49], v[48:49], v[138:139]
	v_or_b32_e32 v138, 32, v142
	v_mad_i64_i32 v[140:141], s[26:27], v138, s35, v[136:137]
	v_pk_mul_f32 v[144:145], v[144:145], v[146:147]
	v_lshl_add_u64 v[138:139], v[140:141], 0, s[30:31]
	v_pk_mul_f32 v[46:47], v[46:47], v[144:145]
	v_lshl_add_u64 v[144:145], v[138:139], 0, v[0:1]
	global_load_dwordx2 v[144:145], v[144:145], off
	v_lshl_add_u64 v[140:141], v[140:141], 0, s[42:43]
	v_lshl_add_u64 v[146:147], v[140:141], 0, v[0:1]
	global_load_dwordx2 v[146:147], v[146:147], off
	s_waitcnt vmcnt(1)
; DI float bflo(unsigned u) { return __uint_as_float(u << 16); }
; DI float bfhi(unsigned u) { return __uint_as_float(u & 0xffff0000u); }
; DI float sigmoidf(float x) { return __builtin_amdgcn_rcpf(1.f + __expf(-x)); }
; DI float inv_sigmoidf(float x) { return 1.f + __expf(-x); }
; DI int TID8() { int t = threadIdx.x; asm volatile("" : "+v"(t)); return t; }
; template <class E>
; DI void gemm8_epi(f32x4 (&acc)[8][4], int m0, int n0, E e) {
;   const int tid = TID8(), lane = tid & 63, w = tid >> 6;
;   const int wm = w >> 2, wn = w & 3;
; #pragma unroll
;   for (int i = 0; i < 8; ++i)
; #pragma unroll
;     for (int j = 0; j < 4; ++j) {
;       const int m = m0 + wm * 128 + i * 16 + (lane & 15);
;       const int n = n0 + wn * 64 + j * 16 + (lane >> 4) * 4;
;       e(m, n, acc[i][j]);
;     }
; }
; __global__ void __launch_bounds__(512, 2) mega(Params p) {
;     ...
;       gemm8_epi(acc8, m0, n0, [&](int m, int n, f32x4& a) {
;         uint2 ua = *(const uint2*)(z + (size_t)m * ZS + C_MA + n);
;         uint2 ub = *(const uint2*)(z + (size_t)m * ZS + C_MB + n);
;         a[0] *= sigmoidf(bflo(ua.x)) * inv_sigmoidf(bflo(ub.x));
;         a[1] *= sigmoidf(bfhi(ua.x)) * inv_sigmoidf(bfhi(ub.x));
;         a[2] *= sigmoidf(bflo(ua.y)) * inv_sigmoidf(bflo(ub.y));
;         a[3] *= sigmoidf(bfhi(ua.y)) * inv_sigmoidf(bfhi(ub.y));
;       });
	v_lshlrev_b32_e32 v143, 16, v144
	v_mul_f32_e32 v143, 0xbfb8aa3b, v143
	v_exp_f32_e32 v143, v143
	s_nop 0
	v_add_f32_e32 v143, 1.0, v143
	v_rcp_f32_e32 v148, v143
	s_waitcnt vmcnt(0)
	v_lshlrev_b32_e32 v143, 16, v146
	v_mul_f32_e32 v143, 0xbfb8aa3b, v143
	v_exp_f32_e32 v150, v143
	v_and_b32_e32 v143, 0xffff0000, v144
	v_mul_f32_e32 v143, 0xbfb8aa3b, v143
	v_exp_f32_e32 v143, v143
	s_nop 0
	v_add_f32_e32 v143, 1.0, v143
	v_rcp_f32_e32 v149, v143
	v_and_b32_e32 v143, 0xffff0000, v146
	v_mul_f32_e32 v143, 0xbfb8aa3b, v143
	v_exp_f32_e32 v151, v143
	v_lshlrev_b32_e32 v143, 16, v145
	v_mul_f32_e32 v143, 0xbfb8aa3b, v143
	v_exp_f32_e32 v143, v143
	v_pk_add_f32 v[150:151], v[150:151], 1.0 op_sel_hi:[1,0]
	v_add_f32_e32 v143, 1.0, v143
	v_rcp_f32_e32 v144, v143
	v_lshlrev_b32_e32 v143, 16, v147
	v_mul_f32_e32 v143, 0xbfb8aa3b, v143
	v_exp_f32_e32 v146, v143
	v_and_b32_e32 v143, 0xffff0000, v145
	v_mul_f32_e32 v143, 0xbfb8aa3b, v143
	v_exp_f32_e32 v143, v143
	v_pk_mul_f32 v[148:149], v[148:149], v[150:151]
	v_add_f32_e32 v143, 1.0, v143
	v_rcp_f32_e32 v145, v143
	v_and_b32_e32 v143, 0xffff0000, v147
	v_mul_f32_e32 v143, 0xbfb8aa3b, v143
	v_exp_f32_e32 v147, v143
	v_pk_mul_f32 v[54:55], v[54:55], v[148:149]
	v_pk_add_f32 v[146:147], v[146:147], 1.0 op_sel_hi:[1,0]
	s_nop 0
	v_pk_mul_f32 v[144:145], v[144:145], v[146:147]
	v_lshl_add_u64 v[146:147], v[140:141], 0, v[134:135]
	v_pk_mul_f32 v[56:57], v[56:57], v[144:145]
	v_lshl_add_u64 v[144:145], v[138:139], 0, v[134:135]
	global_load_dwordx2 v[144:145], v[144:145], off
	s_nop 0
	global_load_dwordx2 v[146:147], v[146:147], off
	s_waitcnt vmcnt(1)
	v_lshlrev_b32_e32 v143, 16, v144
	v_mul_f32_e32 v143, 0xbfb8aa3b, v143
	v_exp_f32_e32 v143, v143
	s_nop 0
	v_add_f32_e32 v143, 1.0, v143
	v_rcp_f32_e32 v148, v143
	s_waitcnt vmcnt(0)
	v_lshlrev_b32_e32 v143, 16, v146
	v_mul_f32_e32 v143, 0xbfb8aa3b, v143
	v_exp_f32_e32 v150, v143
	v_and_b32_e32 v143, 0xffff0000, v144
	v_mul_f32_e32 v143, 0xbfb8aa3b, v143
	v_exp_f32_e32 v143, v143
	s_nop 0
	v_add_f32_e32 v143, 1.0, v143
	v_rcp_f32_e32 v149, v143
	v_and_b32_e32 v143, 0xffff0000, v146
	v_mul_f32_e32 v143, 0xbfb8aa3b, v143
	v_exp_f32_e32 v151, v143
	v_lshlrev_b32_e32 v143, 16, v145
	v_mul_f32_e32 v143, 0xbfb8aa3b, v143
	v_exp_f32_e32 v143, v143
	v_pk_add_f32 v[150:151], v[150:151], 1.0 op_sel_hi:[1,0]
	v_add_f32_e32 v143, 1.0, v143
	v_rcp_f32_e32 v144, v143
	v_lshlrev_b32_e32 v143, 16, v147
	v_mul_f32_e32 v143, 0xbfb8aa3b, v143
	v_exp_f32_e32 v146, v143
	v_and_b32_e32 v143, 0xffff0000, v145
	v_mul_f32_e32 v143, 0xbfb8aa3b, v143
	v_exp_f32_e32 v143, v143
	v_pk_mul_f32 v[148:149], v[148:149], v[150:151]
	v_add_f32_e32 v143, 1.0, v143
	v_rcp_f32_e32 v145, v143
	v_and_b32_e32 v143, 0xffff0000, v147
	v_mul_f32_e32 v143, 0xbfb8aa3b, v143
	v_exp_f32_e32 v147, v143
	v_pk_mul_f32 v[62:63], v[62:63], v[148:149]
	v_pk_add_f32 v[146:147], v[146:147], 1.0 op_sel_hi:[1,0]
	s_nop 0
	v_pk_mul_f32 v[144:145], v[144:145], v[146:147]
	v_lshl_add_u64 v[146:147], v[140:141], 0, v[132:133]
	v_pk_mul_f32 v[64:65], v[64:65], v[144:145]
	v_lshl_add_u64 v[144:145], v[138:139], 0, v[132:133]
	global_load_dwordx2 v[144:145], v[144:145], off
	v_lshl_add_u64 v[138:139], v[138:139], 0, v[130:131]
	global_load_dwordx2 v[146:147], v[146:147], off
	v_lshl_add_u64 v[140:141], v[140:141], 0, v[130:131]
	global_load_dwordx2 v[138:139], v[138:139], off
	s_nop 0
	global_load_dwordx2 v[140:141], v[140:141], off
	s_waitcnt vmcnt(3)
	v_lshlrev_b32_e32 v143, 16, v144
	v_mul_f32_e32 v143, 0xbfb8aa3b, v143
	v_exp_f32_e32 v143, v143
	s_nop 0
	v_add_f32_e32 v143, 1.0, v143
	v_rcp_f32_e32 v148, v143
	s_waitcnt vmcnt(2)
	v_lshlrev_b32_e32 v143, 16, v146
	v_mul_f32_e32 v143, 0xbfb8aa3b, v143
	v_exp_f32_e32 v150, v143
	v_and_b32_e32 v143, 0xffff0000, v144
	v_mul_f32_e32 v143, 0xbfb8aa3b, v143
	v_exp_f32_e32 v143, v143
	s_nop 0
	v_add_f32_e32 v143, 1.0, v143
	v_rcp_f32_e32 v149, v143
	v_and_b32_e32 v143, 0xffff0000, v146
	v_mul_f32_e32 v143, 0xbfb8aa3b, v143
	v_exp_f32_e32 v151, v143
	v_lshlrev_b32_e32 v143, 16, v145
	v_mul_f32_e32 v143, 0xbfb8aa3b, v143
	v_exp_f32_e32 v143, v143
	v_pk_add_f32 v[150:151], v[150:151], 1.0 op_sel_hi:[1,0]
	v_add_f32_e32 v143, 1.0, v143
	v_rcp_f32_e32 v144, v143
	v_lshlrev_b32_e32 v143, 16, v147
	v_mul_f32_e32 v143, 0xbfb8aa3b, v143
	v_exp_f32_e32 v146, v143
	v_and_b32_e32 v143, 0xffff0000, v145
	v_mul_f32_e32 v143, 0xbfb8aa3b, v143
	v_exp_f32_e32 v143, v143
	v_pk_mul_f32 v[148:149], v[148:149], v[150:151]
	v_add_f32_e32 v143, 1.0, v143
	v_rcp_f32_e32 v145, v143
	v_and_b32_e32 v143, 0xffff0000, v147
	v_mul_f32_e32 v143, 0xbfb8aa3b, v143
	v_exp_f32_e32 v147, v143
	s_waitcnt vmcnt(1)
	v_lshlrev_b32_e32 v143, 16, v138
	v_and_b32_e32 v138, 0xffff0000, v138
	v_mul_f32_e32 v138, 0xbfb8aa3b, v138
	v_exp_f32_e32 v138, v138
	v_pk_add_f32 v[146:147], v[146:147], 1.0 op_sel_hi:[1,0]
	v_mul_f32_e32 v143, 0xbfb8aa3b, v143
	v_pk_mul_f32 v[144:145], v[144:145], v[146:147]
	v_add_f32_e32 v138, 1.0, v138
	v_pk_mul_f32 v[72:73], v[72:73], v[144:145]
	v_rcp_f32_e32 v145, v138
	s_waitcnt vmcnt(0)
; DI float bflo(unsigned u) { return __uint_as_float(u << 16); }
; DI float bfhi(unsigned u) { return __uint_as_float(u & 0xffff0000u); }
; DI float sigmoidf(float x) { return __builtin_amdgcn_rcpf(1.f + __expf(-x)); }
; DI float inv_sigmoidf(float x) { return 1.f + __expf(-x); }
; DI int TID8() { int t = threadIdx.x; asm volatile("" : "+v"(t)); return t; }
; template <class E>
; DI void gemm8_epi(f32x4 (&acc)[8][4], int m0, int n0, E e) {
;   const int tid = TID8(), lane = tid & 63, w = tid >> 6;
;   const int wm = w >> 2, wn = w & 3;
; #pragma unroll
;   for (int i = 0; i < 8; ++i)
; #pragma unroll
;     for (int j = 0; j < 4; ++j) {
;       const int m = m0 + wm * 128 + i * 16 + (lane & 15);
;       const int n = n0 + wn * 64 + j * 16 + (lane >> 4) * 4;
;       e(m, n, acc[i][j]);
;     }
; }
; __global__ void __launch_bounds__(512, 2) mega(Params p) {
;     ...
;       gemm8_epi(acc8, m0, n0, [&](int m, int n, f32x4& a) {
;         uint2 ua = *(const uint2*)(z + (size_t)m * ZS + C_MA + n);
;         uint2 ub = *(const uint2*)(z + (size_t)m * ZS + C_MB + n);
;         a[0] *= sigmoidf(bflo(ua.x)) * inv_sigmoidf(bflo(ub.x));
;         a[1] *= sigmoidf(bfhi(ua.x)) * inv_sigmoidf(bfhi(ub.x));
;         a[2] *= sigmoidf(bflo(ua.y)) * inv_sigmoidf(bflo(ub.y));
;         a[3] *= sigmoidf(bfhi(ua.y)) * inv_sigmoidf(bfhi(ub.y));
;       });
	v_and_b32_e32 v138, 0xffff0000, v140
	v_exp_f32_e32 v143, v143
	v_mul_f32_e32 v138, 0xbfb8aa3b, v138
	v_exp_f32_e32 v147, v138
	v_lshlrev_b32_e32 v138, 16, v139
	v_and_b32_e32 v139, 0xffff0000, v139
	v_mul_f32_e32 v138, 0xbfb8aa3b, v138
	v_mul_f32_e32 v139, 0xbfb8aa3b, v139
	v_exp_f32_e32 v138, v138
	v_exp_f32_e32 v139, v139
	v_add_f32_e32 v143, 1.0, v143
	v_rcp_f32_e32 v144, v143
	v_lshlrev_b32_e32 v143, 16, v140
	v_lshlrev_b32_e32 v140, 16, v141
	v_and_b32_e32 v141, 0xffff0000, v141
	v_mul_f32_e32 v140, 0xbfb8aa3b, v140
	v_mul_f32_e32 v141, 0xbfb8aa3b, v141
	v_add_f32_e32 v138, 1.0, v138
	v_exp_f32_e32 v140, v140
	v_add_f32_e32 v139, 1.0, v139
	v_exp_f32_e32 v141, v141
	v_rcp_f32_e32 v138, v138
	v_rcp_f32_e32 v139, v139
	v_mul_f32_e32 v143, 0xbfb8aa3b, v143
	v_exp_f32_e32 v146, v143
	v_pk_add_f32 v[140:141], v[140:141], 1.0 op_sel_hi:[1,0]
	v_pk_mul_f32 v[70:71], v[70:71], v[148:149]
	v_pk_mul_f32 v[138:139], v[138:139], v[140:141]
	v_pk_add_f32 v[146:147], v[146:147], 1.0 op_sel_hi:[1,0]
	v_pk_mul_f32 v[80:81], v[80:81], v[138:139]
	v_or_b32_e32 v138, 48, v142
	v_mad_i64_i32 v[140:141], s[26:27], v138, s35, v[136:137]
	v_pk_mul_f32 v[144:145], v[144:145], v[146:147]
	v_lshl_add_u64 v[138:139], v[140:141], 0, s[30:31]
	v_pk_mul_f32 v[78:79], v[78:79], v[144:145]
	v_lshl_add_u64 v[144:145], v[138:139], 0, v[0:1]
	global_load_dwordx2 v[144:145], v[144:145], off
	v_lshl_add_u64 v[140:141], v[140:141], 0, s[42:43]
	v_lshl_add_u64 v[146:147], v[140:141], 0, v[0:1]
	global_load_dwordx2 v[146:147], v[146:147], off
	s_waitcnt vmcnt(1)
	v_lshlrev_b32_e32 v143, 16, v144
	v_mul_f32_e32 v143, 0xbfb8aa3b, v143
	v_exp_f32_e32 v143, v143
	s_nop 0
	v_add_f32_e32 v143, 1.0, v143
	v_rcp_f32_e32 v148, v143
	s_waitcnt vmcnt(0)
	v_lshlrev_b32_e32 v143, 16, v146
	v_mul_f32_e32 v143, 0xbfb8aa3b, v143
	v_exp_f32_e32 v150, v143
	v_and_b32_e32 v143, 0xffff0000, v144
	v_mul_f32_e32 v143, 0xbfb8aa3b, v143
	v_exp_f32_e32 v143, v143
	s_nop 0
	v_add_f32_e32 v143, 1.0, v143
	v_rcp_f32_e32 v149, v143
	v_and_b32_e32 v143, 0xffff0000, v146
	v_mul_f32_e32 v143, 0xbfb8aa3b, v143
	v_exp_f32_e32 v151, v143
	v_lshlrev_b32_e32 v143, 16, v145
	v_mul_f32_e32 v143, 0xbfb8aa3b, v143
	v_exp_f32_e32 v143, v143
	v_pk_add_f32 v[150:151], v[150:151], 1.0 op_sel_hi:[1,0]
	v_add_f32_e32 v143, 1.0, v143
	v_rcp_f32_e32 v144, v143
	v_lshlrev_b32_e32 v143, 16, v147
	v_mul_f32_e32 v143, 0xbfb8aa3b, v143
	v_exp_f32_e32 v146, v143
	v_and_b32_e32 v143, 0xffff0000, v145
	v_mul_f32_e32 v143, 0xbfb8aa3b, v143
	v_exp_f32_e32 v143, v143
	v_pk_mul_f32 v[148:149], v[148:149], v[150:151]
	v_add_f32_e32 v143, 1.0, v143
	v_rcp_f32_e32 v145, v143
	v_and_b32_e32 v143, 0xffff0000, v147
	v_mul_f32_e32 v143, 0xbfb8aa3b, v143
	v_exp_f32_e32 v147, v143
	v_pk_mul_f32 v[86:87], v[86:87], v[148:149]
	v_pk_add_f32 v[146:147], v[146:147], 1.0 op_sel_hi:[1,0]
	s_nop 0
	v_pk_mul_f32 v[144:145], v[144:145], v[146:147]
	v_lshl_add_u64 v[146:147], v[140:141], 0, v[134:135]
	v_pk_mul_f32 v[88:89], v[88:89], v[144:145]
	v_lshl_add_u64 v[144:145], v[138:139], 0, v[134:135]
	global_load_dwordx2 v[144:145], v[144:145], off
	s_nop 0
	global_load_dwordx2 v[146:147], v[146:147], off
	s_waitcnt vmcnt(1)
	v_lshlrev_b32_e32 v143, 16, v144
	v_mul_f32_e32 v143, 0xbfb8aa3b, v143
	v_exp_f32_e32 v143, v143
	s_nop 0
	v_add_f32_e32 v143, 1.0, v143
	v_rcp_f32_e32 v148, v143
	s_waitcnt vmcnt(0)
	v_lshlrev_b32_e32 v143, 16, v146
	v_mul_f32_e32 v143, 0xbfb8aa3b, v143
	v_exp_f32_e32 v150, v143
	v_and_b32_e32 v143, 0xffff0000, v144
	v_mul_f32_e32 v143, 0xbfb8aa3b, v143
	v_exp_f32_e32 v143, v143
	s_nop 0
	v_add_f32_e32 v143, 1.0, v143
	v_rcp_f32_e32 v149, v143
	v_and_b32_e32 v143, 0xffff0000, v146
	v_mul_f32_e32 v143, 0xbfb8aa3b, v143
	v_exp_f32_e32 v151, v143
	v_lshlrev_b32_e32 v143, 16, v145
	v_mul_f32_e32 v143, 0xbfb8aa3b, v143
	v_exp_f32_e32 v143, v143
	v_pk_add_f32 v[150:151], v[150:151], 1.0 op_sel_hi:[1,0]
	v_add_f32_e32 v143, 1.0, v143
	v_rcp_f32_e32 v144, v143
	v_lshlrev_b32_e32 v143, 16, v147
	v_mul_f32_e32 v143, 0xbfb8aa3b, v143
	v_exp_f32_e32 v146, v143
	v_and_b32_e32 v143, 0xffff0000, v145
	v_mul_f32_e32 v143, 0xbfb8aa3b, v143
	v_exp_f32_e32 v143, v143
	v_pk_mul_f32 v[148:149], v[148:149], v[150:151]
	v_add_f32_e32 v143, 1.0, v143
	v_rcp_f32_e32 v145, v143
	v_and_b32_e32 v143, 0xffff0000, v147
	v_mul_f32_e32 v143, 0xbfb8aa3b, v143
	v_exp_f32_e32 v147, v143
	v_pk_mul_f32 v[94:95], v[94:95], v[148:149]
	v_pk_add_f32 v[146:147], v[146:147], 1.0 op_sel_hi:[1,0]
	s_nop 0
	v_pk_mul_f32 v[144:145], v[144:145], v[146:147]
	v_lshl_add_u64 v[146:147], v[140:141], 0, v[132:133]
	v_pk_mul_f32 v[96:97], v[96:97], v[144:145]
	v_lshl_add_u64 v[144:145], v[138:139], 0, v[132:133]
	global_load_dwordx2 v[144:145], v[144:145], off
	v_lshl_add_u64 v[138:139], v[138:139], 0, v[130:131]
	global_load_dwordx2 v[146:147], v[146:147], off
	v_lshl_add_u64 v[140:141], v[140:141], 0, v[130:131]
	global_load_dwordx2 v[138:139], v[138:139], off
	s_nop 0
	global_load_dwordx2 v[140:141], v[140:141], off
	s_waitcnt vmcnt(3)
	v_lshlrev_b32_e32 v143, 16, v144
	v_mul_f32_e32 v143, 0xbfb8aa3b, v143
	v_exp_f32_e32 v143, v143
	s_nop 0
	v_add_f32_e32 v143, 1.0, v143
	v_rcp_f32_e32 v148, v143
	s_waitcnt vmcnt(2)
; DI float bflo(unsigned u) { return __uint_as_float(u << 16); }
; DI float bfhi(unsigned u) { return __uint_as_float(u & 0xffff0000u); }
; DI float sigmoidf(float x) { return __builtin_amdgcn_rcpf(1.f + __expf(-x)); }
; DI float inv_sigmoidf(float x) { return 1.f + __expf(-x); }
; DI int TID8() { int t = threadIdx.x; asm volatile("" : "+v"(t)); return t; }
; template <class E>
; DI void gemm8_epi(f32x4 (&acc)[8][4], int m0, int n0, E e) {
;   const int tid = TID8(), lane = tid & 63, w = tid >> 6;
;   const int wm = w >> 2, wn = w & 3;
; #pragma unroll
;   for (int i = 0; i < 8; ++i)
; #pragma unroll
;     for (int j = 0; j < 4; ++j) {
;       const int m = m0 + wm * 128 + i * 16 + (lane & 15);
;       const int n = n0 + wn * 64 + j * 16 + (lane >> 4) * 4;
;       e(m, n, acc[i][j]);
;     }
; }
; __global__ void __launch_bounds__(512, 2) mega(Params p) {
;     ...
;       gemm8_epi(acc8, m0, n0, [&](int m, int n, f32x4& a) {
;         uint2 ua = *(const uint2*)(z + (size_t)m * ZS + C_MA + n);
;         uint2 ub = *(const uint2*)(z + (size_t)m * ZS + C_MB + n);
;         a[0] *= sigmoidf(bflo(ua.x)) * inv_sigmoidf(bflo(ub.x));
;         a[1] *= sigmoidf(bfhi(ua.x)) * inv_sigmoidf(bfhi(ub.x));
;         a[2] *= sigmoidf(bflo(ua.y)) * inv_sigmoidf(bflo(ub.y));
;         a[3] *= sigmoidf(bfhi(ua.y)) * inv_sigmoidf(bfhi(ub.y));
;       });
	v_lshlrev_b32_e32 v143, 16, v146
	v_mul_f32_e32 v143, 0xbfb8aa3b, v143
	v_exp_f32_e32 v150, v143
	v_and_b32_e32 v143, 0xffff0000, v144
	v_mul_f32_e32 v143, 0xbfb8aa3b, v143
	v_exp_f32_e32 v143, v143
	s_nop 0
	v_add_f32_e32 v143, 1.0, v143
	v_rcp_f32_e32 v149, v143
	v_and_b32_e32 v143, 0xffff0000, v146
	v_mul_f32_e32 v143, 0xbfb8aa3b, v143
	v_exp_f32_e32 v151, v143
	v_lshlrev_b32_e32 v143, 16, v145
	v_mul_f32_e32 v143, 0xbfb8aa3b, v143
	v_exp_f32_e32 v143, v143
	v_pk_add_f32 v[150:151], v[150:151], 1.0 op_sel_hi:[1,0]
	v_add_f32_e32 v143, 1.0, v143
	v_rcp_f32_e32 v144, v143
	v_lshlrev_b32_e32 v143, 16, v147
	v_mul_f32_e32 v143, 0xbfb8aa3b, v143
	v_exp_f32_e32 v146, v143
	v_and_b32_e32 v143, 0xffff0000, v145
	v_mul_f32_e32 v143, 0xbfb8aa3b, v143
	v_exp_f32_e32 v143, v143
	v_pk_mul_f32 v[148:149], v[148:149], v[150:151]
	v_add_f32_e32 v143, 1.0, v143
	v_rcp_f32_e32 v145, v143
	v_and_b32_e32 v143, 0xffff0000, v147
	v_mul_f32_e32 v143, 0xbfb8aa3b, v143
	v_exp_f32_e32 v147, v143
	s_waitcnt vmcnt(1)
	v_lshlrev_b32_e32 v143, 16, v138
	v_and_b32_e32 v138, 0xffff0000, v138
	v_mul_f32_e32 v138, 0xbfb8aa3b, v138
	v_exp_f32_e32 v138, v138
	v_pk_add_f32 v[146:147], v[146:147], 1.0 op_sel_hi:[1,0]
	v_mul_f32_e32 v143, 0xbfb8aa3b, v143
	v_pk_mul_f32 v[144:145], v[144:145], v[146:147]
	v_add_f32_e32 v138, 1.0, v138
	v_pk_mul_f32 v[104:105], v[104:105], v[144:145]
	v_rcp_f32_e32 v145, v138
	s_waitcnt vmcnt(0)
	v_and_b32_e32 v138, 0xffff0000, v140
	v_exp_f32_e32 v143, v143
	v_mul_f32_e32 v138, 0xbfb8aa3b, v138
	v_exp_f32_e32 v147, v138
	v_lshlrev_b32_e32 v138, 16, v139
	v_and_b32_e32 v139, 0xffff0000, v139
	v_mul_f32_e32 v138, 0xbfb8aa3b, v138
	v_mul_f32_e32 v139, 0xbfb8aa3b, v139
	v_exp_f32_e32 v138, v138
	v_exp_f32_e32 v139, v139
	v_add_f32_e32 v143, 1.0, v143
	v_rcp_f32_e32 v144, v143
	v_lshlrev_b32_e32 v143, 16, v140
	v_lshlrev_b32_e32 v140, 16, v141
	v_and_b32_e32 v141, 0xffff0000, v141
	v_mul_f32_e32 v140, 0xbfb8aa3b, v140
	v_mul_f32_e32 v141, 0xbfb8aa3b, v141
	v_add_f32_e32 v138, 1.0, v138
	v_exp_f32_e32 v140, v140
	v_add_f32_e32 v139, 1.0, v139
	v_exp_f32_e32 v141, v141
	v_rcp_f32_e32 v138, v138
	v_rcp_f32_e32 v139, v139
	v_mul_f32_e32 v143, 0xbfb8aa3b, v143
	v_exp_f32_e32 v146, v143
	v_pk_add_f32 v[140:141], v[140:141], 1.0 op_sel_hi:[1,0]
	v_pk_mul_f32 v[102:103], v[102:103], v[148:149]
	v_pk_mul_f32 v[138:139], v[138:139], v[140:141]
	v_pk_add_f32 v[146:147], v[146:147], 1.0 op_sel_hi:[1,0]
	v_pk_mul_f32 v[112:113], v[112:113], v[138:139]
	v_or_b32_e32 v138, 64, v142
	v_mad_i64_i32 v[140:141], s[26:27], v138, s35, v[136:137]
	v_pk_mul_f32 v[144:145], v[144:145], v[146:147]
	v_lshl_add_u64 v[138:139], v[140:141], 0, s[30:31]
	v_pk_mul_f32 v[110:111], v[110:111], v[144:145]
	v_lshl_add_u64 v[144:145], v[138:139], 0, v[0:1]
	global_load_dwordx2 v[144:145], v[144:145], off
	v_lshl_add_u64 v[140:141], v[140:141], 0, s[42:43]
	v_lshl_add_u64 v[146:147], v[140:141], 0, v[0:1]
	global_load_dwordx2 v[146:147], v[146:147], off
	s_waitcnt vmcnt(1)
	v_lshlrev_b32_e32 v143, 16, v144
	v_mul_f32_e32 v143, 0xbfb8aa3b, v143
	v_exp_f32_e32 v143, v143
	s_nop 0
	v_add_f32_e32 v143, 1.0, v143
	v_rcp_f32_e32 v148, v143
	s_waitcnt vmcnt(0)
	v_lshlrev_b32_e32 v143, 16, v146
	v_mul_f32_e32 v143, 0xbfb8aa3b, v143
	v_exp_f32_e32 v150, v143
	v_and_b32_e32 v143, 0xffff0000, v144
	v_mul_f32_e32 v143, 0xbfb8aa3b, v143
	v_exp_f32_e32 v143, v143
	s_nop 0
	v_add_f32_e32 v143, 1.0, v143
	v_rcp_f32_e32 v149, v143
	v_and_b32_e32 v143, 0xffff0000, v146
	v_mul_f32_e32 v143, 0xbfb8aa3b, v143
	v_exp_f32_e32 v151, v143
	v_lshlrev_b32_e32 v143, 16, v145
	v_mul_f32_e32 v143, 0xbfb8aa3b, v143
	v_exp_f32_e32 v143, v143
	v_pk_add_f32 v[150:151], v[150:151], 1.0 op_sel_hi:[1,0]
	v_add_f32_e32 v143, 1.0, v143
	v_rcp_f32_e32 v144, v143
	v_lshlrev_b32_e32 v143, 16, v147
	v_mul_f32_e32 v143, 0xbfb8aa3b, v143
	v_exp_f32_e32 v146, v143
	v_and_b32_e32 v143, 0xffff0000, v145
	v_mul_f32_e32 v143, 0xbfb8aa3b, v143
	v_exp_f32_e32 v143, v143
	v_pk_mul_f32 v[148:149], v[148:149], v[150:151]
	v_add_f32_e32 v143, 1.0, v143
	v_rcp_f32_e32 v145, v143
	v_and_b32_e32 v143, 0xffff0000, v147
	v_mul_f32_e32 v143, 0xbfb8aa3b, v143
	v_exp_f32_e32 v147, v143
	v_pk_mul_f32 v[118:119], v[118:119], v[148:149]
	v_pk_add_f32 v[146:147], v[146:147], 1.0 op_sel_hi:[1,0]
	s_nop 0
	v_pk_mul_f32 v[144:145], v[144:145], v[146:147]
	v_lshl_add_u64 v[146:147], v[140:141], 0, v[134:135]
	v_pk_mul_f32 v[120:121], v[120:121], v[144:145]
	v_lshl_add_u64 v[144:145], v[138:139], 0, v[134:135]
	global_load_dwordx2 v[144:145], v[144:145], off
	s_nop 0
	global_load_dwordx2 v[146:147], v[146:147], off
	s_waitcnt vmcnt(1)
	v_lshlrev_b32_e32 v143, 16, v144
	v_mul_f32_e32 v143, 0xbfb8aa3b, v143
	v_exp_f32_e32 v143, v143
	s_nop 0
	v_add_f32_e32 v143, 1.0, v143
	v_rcp_f32_e32 v148, v143
	s_waitcnt vmcnt(0)
	v_lshlrev_b32_e32 v143, 16, v146
	v_mul_f32_e32 v143, 0xbfb8aa3b, v143
	v_exp_f32_e32 v150, v143
	v_and_b32_e32 v143, 0xffff0000, v144
	v_mul_f32_e32 v143, 0xbfb8aa3b, v143
	v_exp_f32_e32 v143, v143
	s_nop 0
	v_add_f32_e32 v143, 1.0, v143
	v_rcp_f32_e32 v149, v143
	v_and_b32_e32 v143, 0xffff0000, v146
	v_mul_f32_e32 v143, 0xbfb8aa3b, v143
	v_exp_f32_e32 v151, v143
	v_lshlrev_b32_e32 v143, 16, v145
	v_mul_f32_e32 v143, 0xbfb8aa3b, v143
	v_exp_f32_e32 v143, v143
	v_pk_add_f32 v[150:151], v[150:151], 1.0 op_sel_hi:[1,0]
	v_add_f32_e32 v143, 1.0, v143
	v_rcp_f32_e32 v144, v143
	v_lshlrev_b32_e32 v143, 16, v147
	v_mul_f32_e32 v143, 0xbfb8aa3b, v143
	v_exp_f32_e32 v146, v143
	v_and_b32_e32 v143, 0xffff0000, v145
	v_mul_f32_e32 v143, 0xbfb8aa3b, v143
	v_exp_f32_e32 v143, v143
	v_pk_mul_f32 v[148:149], v[148:149], v[150:151]
	v_add_f32_e32 v143, 1.0, v143
	v_rcp_f32_e32 v145, v143
	v_and_b32_e32 v143, 0xffff0000, v147
	v_mul_f32_e32 v143, 0xbfb8aa3b, v143
	v_exp_f32_e32 v147, v143
	v_pk_mul_f32 v[126:127], v[126:127], v[148:149]
	v_pk_add_f32 v[146:147], v[146:147], 1.0 op_sel_hi:[1,0]
	s_nop 0
	v_pk_mul_f32 v[144:145], v[144:145], v[146:147]
	v_lshl_add_u64 v[146:147], v[140:141], 0, v[132:133]
	v_pk_mul_f32 v[128:129], v[128:129], v[144:145]
	v_lshl_add_u64 v[144:145], v[138:139], 0, v[132:133]
	global_load_dwordx2 v[144:145], v[144:145], off
	v_lshl_add_u64 v[138:139], v[138:139], 0, v[130:131]
	global_load_dwordx2 v[146:147], v[146:147], off
	v_lshl_add_u64 v[140:141], v[140:141], 0, v[130:131]
	global_load_dwordx2 v[138:139], v[138:139], off
	s_nop 0
	global_load_dwordx2 v[140:141], v[140:141], off
	s_waitcnt vmcnt(3)
; DI float bflo(unsigned u) { return __uint_as_float(u << 16); }
; DI float bfhi(unsigned u) { return __uint_as_float(u & 0xffff0000u); }
; DI float sigmoidf(float x) { return __builtin_amdgcn_rcpf(1.f + __expf(-x)); }
; DI float inv_sigmoidf(float x) { return 1.f + __expf(-x); }
; DI int TID8() { int t = threadIdx.x; asm volatile("" : "+v"(t)); return t; }
; template <class E>
; DI void gemm8_epi(f32x4 (&acc)[8][4], int m0, int n0, E e) {
;   const int tid = TID8(), lane = tid & 63, w = tid >> 6;
;   const int wm = w >> 2, wn = w & 3;
; #pragma unroll
;   for (int i = 0; i < 8; ++i)
; #pragma unroll
;     for (int j = 0; j < 4; ++j) {
;       const int m = m0 + wm * 128 + i * 16 + (lane & 15);
;       const int n = n0 + wn * 64 + j * 16 + (lane >> 4) * 4;
;       e(m, n, acc[i][j]);
;     }
; }
; __global__ void __launch_bounds__(512, 2) mega(Params p) {
;     ...
;       gemm8_epi(acc8, m0, n0, [&](int m, int n, f32x4& a) {
;         uint2 ua = *(const uint2*)(z + (size_t)m * ZS + C_MA + n);
;         uint2 ub = *(const uint2*)(z + (size_t)m * ZS + C_MB + n);
;         a[0] *= sigmoidf(bflo(ua.x)) * inv_sigmoidf(bflo(ub.x));
;         a[1] *= sigmoidf(bfhi(ua.x)) * inv_sigmoidf(bfhi(ub.x));
;         a[2] *= sigmoidf(bflo(ua.y)) * inv_sigmoidf(bflo(ub.y));
;         a[3] *= sigmoidf(bfhi(ua.y)) * inv_sigmoidf(bfhi(ub.y));
;       });
	v_lshlrev_b32_e32 v143, 16, v144
	v_mul_f32_e32 v143, 0xbfb8aa3b, v143
	v_exp_f32_e32 v143, v143
	s_nop 0
	v_add_f32_e32 v143, 1.0, v143
	v_rcp_f32_e32 v148, v143
	s_waitcnt vmcnt(2)
	v_lshlrev_b32_e32 v143, 16, v146
	v_mul_f32_e32 v143, 0xbfb8aa3b, v143
	v_exp_f32_e32 v150, v143
	v_and_b32_e32 v143, 0xffff0000, v144
	v_mul_f32_e32 v143, 0xbfb8aa3b, v143
	v_exp_f32_e32 v143, v143
	s_nop 0
	v_add_f32_e32 v143, 1.0, v143
	v_rcp_f32_e32 v149, v143
	v_and_b32_e32 v143, 0xffff0000, v146
	v_mul_f32_e32 v143, 0xbfb8aa3b, v143
	v_exp_f32_e32 v151, v143
	v_lshlrev_b32_e32 v143, 16, v145
	v_mul_f32_e32 v143, 0xbfb8aa3b, v143
	v_exp_f32_e32 v143, v143
	v_pk_add_f32 v[150:151], v[150:151], 1.0 op_sel_hi:[1,0]
	v_add_f32_e32 v143, 1.0, v143
	v_rcp_f32_e32 v144, v143
	v_lshlrev_b32_e32 v143, 16, v147
	v_mul_f32_e32 v143, 0xbfb8aa3b, v143
	v_exp_f32_e32 v146, v143
	v_and_b32_e32 v143, 0xffff0000, v145
	v_mul_f32_e32 v143, 0xbfb8aa3b, v143
	v_exp_f32_e32 v143, v143
	v_pk_mul_f32 v[148:149], v[148:149], v[150:151]
	v_add_f32_e32 v143, 1.0, v143
	v_rcp_f32_e32 v145, v143
	v_and_b32_e32 v143, 0xffff0000, v147
	v_mul_f32_e32 v143, 0xbfb8aa3b, v143
	v_exp_f32_e32 v147, v143
	s_waitcnt vmcnt(1)
	v_lshlrev_b32_e32 v143, 16, v138
	v_and_b32_e32 v138, 0xffff0000, v138
	v_mul_f32_e32 v138, 0xbfb8aa3b, v138
	v_exp_f32_e32 v138, v138
	v_pk_add_f32 v[146:147], v[146:147], 1.0 op_sel_hi:[1,0]
	v_mul_f32_e32 v143, 0xbfb8aa3b, v143
	v_pk_mul_f32 v[144:145], v[144:145], v[146:147]
	v_add_f32_e32 v138, 1.0, v138
	v_pk_mul_f32 v[124:125], v[124:125], v[144:145]
	v_rcp_f32_e32 v145, v138
	s_waitcnt vmcnt(0)
	v_and_b32_e32 v138, 0xffff0000, v140
	v_exp_f32_e32 v143, v143
	v_mul_f32_e32 v138, 0xbfb8aa3b, v138
	v_exp_f32_e32 v147, v138
	v_lshlrev_b32_e32 v138, 16, v139
	v_and_b32_e32 v139, 0xffff0000, v139
	v_mul_f32_e32 v138, 0xbfb8aa3b, v138
	v_mul_f32_e32 v139, 0xbfb8aa3b, v139
	v_exp_f32_e32 v138, v138
	v_exp_f32_e32 v139, v139
	v_add_f32_e32 v143, 1.0, v143
	v_rcp_f32_e32 v144, v143
	v_lshlrev_b32_e32 v143, 16, v140
	v_lshlrev_b32_e32 v140, 16, v141
	v_and_b32_e32 v141, 0xffff0000, v141
	v_mul_f32_e32 v140, 0xbfb8aa3b, v140
	v_mul_f32_e32 v141, 0xbfb8aa3b, v141
	v_add_f32_e32 v138, 1.0, v138
	v_exp_f32_e32 v140, v140
	v_add_f32_e32 v139, 1.0, v139
	v_exp_f32_e32 v141, v141
	v_rcp_f32_e32 v138, v138
	v_rcp_f32_e32 v139, v139
	v_mul_f32_e32 v143, 0xbfb8aa3b, v143
	v_exp_f32_e32 v146, v143
	v_pk_add_f32 v[140:141], v[140:141], 1.0 op_sel_hi:[1,0]
	v_pk_mul_f32 v[122:123], v[122:123], v[148:149]
	v_pk_mul_f32 v[138:139], v[138:139], v[140:141]
	v_pk_add_f32 v[146:147], v[146:147], 1.0 op_sel_hi:[1,0]
	v_pk_mul_f32 v[116:117], v[116:117], v[138:139]
	v_or_b32_e32 v138, 0x50, v142
	v_mad_i64_i32 v[140:141], s[26:27], v138, s35, v[136:137]
	v_pk_mul_f32 v[144:145], v[144:145], v[146:147]
	v_lshl_add_u64 v[138:139], v[140:141], 0, s[30:31]
	v_pk_mul_f32 v[114:115], v[114:115], v[144:145]
	v_lshl_add_u64 v[144:145], v[138:139], 0, v[0:1]
	global_load_dwordx2 v[144:145], v[144:145], off
	v_lshl_add_u64 v[140:141], v[140:141], 0, s[42:43]
	v_lshl_add_u64 v[146:147], v[140:141], 0, v[0:1]
	global_load_dwordx2 v[146:147], v[146:147], off
	s_waitcnt vmcnt(1)
	v_lshlrev_b32_e32 v143, 16, v144
	v_mul_f32_e32 v143, 0xbfb8aa3b, v143
	v_exp_f32_e32 v143, v143
	s_nop 0
	v_add_f32_e32 v143, 1.0, v143
	v_rcp_f32_e32 v148, v143
	s_waitcnt vmcnt(0)
	v_lshlrev_b32_e32 v143, 16, v146
	v_mul_f32_e32 v143, 0xbfb8aa3b, v143
	v_exp_f32_e32 v150, v143
	v_and_b32_e32 v143, 0xffff0000, v144
	v_mul_f32_e32 v143, 0xbfb8aa3b, v143
	v_exp_f32_e32 v143, v143
	s_nop 0
	v_add_f32_e32 v143, 1.0, v143
	v_rcp_f32_e32 v149, v143
	v_and_b32_e32 v143, 0xffff0000, v146
	v_mul_f32_e32 v143, 0xbfb8aa3b, v143
	v_exp_f32_e32 v151, v143
	v_lshlrev_b32_e32 v143, 16, v145
	v_mul_f32_e32 v143, 0xbfb8aa3b, v143
	v_exp_f32_e32 v143, v143
	v_pk_add_f32 v[150:151], v[150:151], 1.0 op_sel_hi:[1,0]
	v_add_f32_e32 v143, 1.0, v143
	v_rcp_f32_e32 v144, v143
	v_lshlrev_b32_e32 v143, 16, v147
	v_mul_f32_e32 v143, 0xbfb8aa3b, v143
	v_exp_f32_e32 v146, v143
	v_and_b32_e32 v143, 0xffff0000, v145
	v_mul_f32_e32 v143, 0xbfb8aa3b, v143
	v_exp_f32_e32 v143, v143
	v_pk_mul_f32 v[148:149], v[148:149], v[150:151]
	v_add_f32_e32 v143, 1.0, v143
	v_rcp_f32_e32 v145, v143
	v_and_b32_e32 v143, 0xffff0000, v147
	v_mul_f32_e32 v143, 0xbfb8aa3b, v143
	v_exp_f32_e32 v147, v143
	v_pk_mul_f32 v[106:107], v[106:107], v[148:149]
	v_pk_add_f32 v[146:147], v[146:147], 1.0 op_sel_hi:[1,0]
	s_nop 0
	v_pk_mul_f32 v[144:145], v[144:145], v[146:147]
	v_lshl_add_u64 v[146:147], v[140:141], 0, v[134:135]
	v_pk_mul_f32 v[108:109], v[108:109], v[144:145]
	v_lshl_add_u64 v[144:145], v[138:139], 0, v[134:135]
	global_load_dwordx2 v[144:145], v[144:145], off
	s_nop 0
	global_load_dwordx2 v[146:147], v[146:147], off
	s_waitcnt vmcnt(1)
	v_lshlrev_b32_e32 v143, 16, v144
	v_mul_f32_e32 v143, 0xbfb8aa3b, v143
	v_exp_f32_e32 v143, v143
	s_nop 0
	v_add_f32_e32 v143, 1.0, v143
	v_rcp_f32_e32 v148, v143
	s_waitcnt vmcnt(0)
; DI float bflo(unsigned u) { return __uint_as_float(u << 16); }
; DI float bfhi(unsigned u) { return __uint_as_float(u & 0xffff0000u); }
; DI float sigmoidf(float x) { return __builtin_amdgcn_rcpf(1.f + __expf(-x)); }
; DI float inv_sigmoidf(float x) { return 1.f + __expf(-x); }
; DI int TID8() { int t = threadIdx.x; asm volatile("" : "+v"(t)); return t; }
; template <class E>
; DI void gemm8_epi(f32x4 (&acc)[8][4], int m0, int n0, E e) {
;   const int tid = TID8(), lane = tid & 63, w = tid >> 6;
;   const int wm = w >> 2, wn = w & 3;
; #pragma unroll
;   for (int i = 0; i < 8; ++i)
; #pragma unroll
;     for (int j = 0; j < 4; ++j) {
;       const int m = m0 + wm * 128 + i * 16 + (lane & 15);
;       const int n = n0 + wn * 64 + j * 16 + (lane >> 4) * 4;
;       e(m, n, acc[i][j]);
;     }
; }
; __global__ void __launch_bounds__(512, 2) mega(Params p) {
;     ...
;       gemm8_epi(acc8, m0, n0, [&](int m, int n, f32x4& a) {
;         uint2 ua = *(const uint2*)(z + (size_t)m * ZS + C_MA + n);
;         uint2 ub = *(const uint2*)(z + (size_t)m * ZS + C_MB + n);
;         a[0] *= sigmoidf(bflo(ua.x)) * inv_sigmoidf(bflo(ub.x));
;         a[1] *= sigmoidf(bfhi(ua.x)) * inv_sigmoidf(bfhi(ub.x));
;         a[2] *= sigmoidf(bflo(ua.y)) * inv_sigmoidf(bflo(ub.y));
;         a[3] *= sigmoidf(bfhi(ua.y)) * inv_sigmoidf(bfhi(ub.y));
;       });
	v_lshlrev_b32_e32 v143, 16, v146
	v_mul_f32_e32 v143, 0xbfb8aa3b, v143
	v_exp_f32_e32 v150, v143
	v_and_b32_e32 v143, 0xffff0000, v144
	v_mul_f32_e32 v143, 0xbfb8aa3b, v143
	v_exp_f32_e32 v143, v143
	s_nop 0
	v_add_f32_e32 v143, 1.0, v143
	v_rcp_f32_e32 v149, v143
	v_and_b32_e32 v143, 0xffff0000, v146
	v_mul_f32_e32 v143, 0xbfb8aa3b, v143
	v_exp_f32_e32 v151, v143
	v_lshlrev_b32_e32 v143, 16, v145
	v_mul_f32_e32 v143, 0xbfb8aa3b, v143
	v_exp_f32_e32 v143, v143
	v_pk_add_f32 v[150:151], v[150:151], 1.0 op_sel_hi:[1,0]
	v_add_f32_e32 v143, 1.0, v143
	v_rcp_f32_e32 v144, v143
	v_lshlrev_b32_e32 v143, 16, v147
	v_mul_f32_e32 v143, 0xbfb8aa3b, v143
	v_exp_f32_e32 v146, v143
	v_and_b32_e32 v143, 0xffff0000, v145
	v_mul_f32_e32 v143, 0xbfb8aa3b, v143
	v_exp_f32_e32 v143, v143
	v_pk_mul_f32 v[148:149], v[148:149], v[150:151]
	v_add_f32_e32 v143, 1.0, v143
	v_rcp_f32_e32 v145, v143
	v_and_b32_e32 v143, 0xffff0000, v147
	v_mul_f32_e32 v143, 0xbfb8aa3b, v143
	v_exp_f32_e32 v147, v143
	v_pk_mul_f32 v[98:99], v[98:99], v[148:149]
	v_pk_add_f32 v[146:147], v[146:147], 1.0 op_sel_hi:[1,0]
	s_nop 0
	v_pk_mul_f32 v[144:145], v[144:145], v[146:147]
	v_lshl_add_u64 v[146:147], v[140:141], 0, v[132:133]
	v_pk_mul_f32 v[100:101], v[100:101], v[144:145]
	v_lshl_add_u64 v[144:145], v[138:139], 0, v[132:133]
	global_load_dwordx2 v[144:145], v[144:145], off
	v_lshl_add_u64 v[138:139], v[138:139], 0, v[130:131]
	global_load_dwordx2 v[146:147], v[146:147], off
	v_lshl_add_u64 v[140:141], v[140:141], 0, v[130:131]
	global_load_dwordx2 v[138:139], v[138:139], off
	s_nop 0
	global_load_dwordx2 v[140:141], v[140:141], off
	s_waitcnt vmcnt(3)
	v_lshlrev_b32_e32 v143, 16, v144
	v_mul_f32_e32 v143, 0xbfb8aa3b, v143
	v_exp_f32_e32 v143, v143
	s_nop 0
	v_add_f32_e32 v143, 1.0, v143
	v_rcp_f32_e32 v148, v143
	s_waitcnt vmcnt(2)
	v_lshlrev_b32_e32 v143, 16, v146
	v_mul_f32_e32 v143, 0xbfb8aa3b, v143
	v_exp_f32_e32 v150, v143
	v_and_b32_e32 v143, 0xffff0000, v144
	v_mul_f32_e32 v143, 0xbfb8aa3b, v143
	v_exp_f32_e32 v143, v143
	s_nop 0
	v_add_f32_e32 v143, 1.0, v143
	v_rcp_f32_e32 v149, v143
	v_and_b32_e32 v143, 0xffff0000, v146
	v_mul_f32_e32 v143, 0xbfb8aa3b, v143
	v_exp_f32_e32 v151, v143
	v_lshlrev_b32_e32 v143, 16, v145
	v_mul_f32_e32 v143, 0xbfb8aa3b, v143
	v_exp_f32_e32 v143, v143
	v_pk_add_f32 v[150:151], v[150:151], 1.0 op_sel_hi:[1,0]
	v_add_f32_e32 v143, 1.0, v143
	v_rcp_f32_e32 v144, v143
	v_lshlrev_b32_e32 v143, 16, v147
	v_mul_f32_e32 v143, 0xbfb8aa3b, v143
	v_exp_f32_e32 v146, v143
	v_and_b32_e32 v143, 0xffff0000, v145
	v_mul_f32_e32 v143, 0xbfb8aa3b, v143
	v_exp_f32_e32 v143, v143
	v_pk_mul_f32 v[148:149], v[148:149], v[150:151]
	v_add_f32_e32 v143, 1.0, v143
	v_rcp_f32_e32 v145, v143
	v_and_b32_e32 v143, 0xffff0000, v147
	v_mul_f32_e32 v143, 0xbfb8aa3b, v143
	v_exp_f32_e32 v147, v143
	s_waitcnt vmcnt(1)
	v_lshlrev_b32_e32 v143, 16, v138
	v_and_b32_e32 v138, 0xffff0000, v138
	v_mul_f32_e32 v138, 0xbfb8aa3b, v138
	v_exp_f32_e32 v138, v138
	v_pk_add_f32 v[146:147], v[146:147], 1.0 op_sel_hi:[1,0]
	v_mul_f32_e32 v143, 0xbfb8aa3b, v143
	v_pk_mul_f32 v[144:145], v[144:145], v[146:147]
	v_add_f32_e32 v138, 1.0, v138
	v_pk_mul_f32 v[92:93], v[92:93], v[144:145]
	v_rcp_f32_e32 v145, v138
	s_waitcnt vmcnt(0)
	v_and_b32_e32 v138, 0xffff0000, v140
	v_exp_f32_e32 v143, v143
	v_mul_f32_e32 v138, 0xbfb8aa3b, v138
	v_exp_f32_e32 v147, v138
	v_lshlrev_b32_e32 v138, 16, v139
	v_and_b32_e32 v139, 0xffff0000, v139
	v_mul_f32_e32 v138, 0xbfb8aa3b, v138
	v_mul_f32_e32 v139, 0xbfb8aa3b, v139
	v_exp_f32_e32 v138, v138
	v_exp_f32_e32 v139, v139
	v_add_f32_e32 v143, 1.0, v143
	v_rcp_f32_e32 v144, v143
	v_lshlrev_b32_e32 v143, 16, v140
	v_lshlrev_b32_e32 v140, 16, v141
	v_and_b32_e32 v141, 0xffff0000, v141
	v_mul_f32_e32 v140, 0xbfb8aa3b, v140
	v_mul_f32_e32 v141, 0xbfb8aa3b, v141
	v_add_f32_e32 v138, 1.0, v138
	v_exp_f32_e32 v140, v140
	v_add_f32_e32 v139, 1.0, v139
	v_exp_f32_e32 v141, v141
	v_rcp_f32_e32 v138, v138
	v_rcp_f32_e32 v139, v139
	v_mul_f32_e32 v143, 0xbfb8aa3b, v143
	v_exp_f32_e32 v146, v143
	v_pk_add_f32 v[140:141], v[140:141], 1.0 op_sel_hi:[1,0]
	v_pk_mul_f32 v[90:91], v[90:91], v[148:149]
	v_pk_mul_f32 v[138:139], v[138:139], v[140:141]
	v_pk_add_f32 v[146:147], v[146:147], 1.0 op_sel_hi:[1,0]
	v_pk_mul_f32 v[84:85], v[84:85], v[138:139]
	v_or_b32_e32 v138, 0x60, v142
	v_mad_i64_i32 v[140:141], s[26:27], v138, s35, v[136:137]
	v_pk_mul_f32 v[144:145], v[144:145], v[146:147]
	v_lshl_add_u64 v[138:139], v[140:141], 0, s[30:31]
	v_pk_mul_f32 v[82:83], v[82:83], v[144:145]
	v_lshl_add_u64 v[144:145], v[138:139], 0, v[0:1]
	global_load_dwordx2 v[144:145], v[144:145], off
	v_lshl_add_u64 v[140:141], v[140:141], 0, s[42:43]
	v_lshl_add_u64 v[146:147], v[140:141], 0, v[0:1]
	global_load_dwordx2 v[146:147], v[146:147], off
	s_waitcnt vmcnt(1)
	v_lshlrev_b32_e32 v143, 16, v144
	v_mul_f32_e32 v143, 0xbfb8aa3b, v143
	v_exp_f32_e32 v143, v143
	s_nop 0
	v_add_f32_e32 v143, 1.0, v143
	v_rcp_f32_e32 v148, v143
	s_waitcnt vmcnt(0)
; DI float bflo(unsigned u) { return __uint_as_float(u << 16); }
; DI float bfhi(unsigned u) { return __uint_as_float(u & 0xffff0000u); }
; DI float sigmoidf(float x) { return __builtin_amdgcn_rcpf(1.f + __expf(-x)); }
; DI float inv_sigmoidf(float x) { return 1.f + __expf(-x); }
; DI int TID8() { int t = threadIdx.x; asm volatile("" : "+v"(t)); return t; }
; template <class E>
; DI void gemm8_epi(f32x4 (&acc)[8][4], int m0, int n0, E e) {
;   const int tid = TID8(), lane = tid & 63, w = tid >> 6;
;   const int wm = w >> 2, wn = w & 3;
; #pragma unroll
;   for (int i = 0; i < 8; ++i)
; #pragma unroll
;     for (int j = 0; j < 4; ++j) {
;       const int m = m0 + wm * 128 + i * 16 + (lane & 15);
;       const int n = n0 + wn * 64 + j * 16 + (lane >> 4) * 4;
;       e(m, n, acc[i][j]);
;     }
; }
; __global__ void __launch_bounds__(512, 2) mega(Params p) {
;     ...
;       gemm8_epi(acc8, m0, n0, [&](int m, int n, f32x4& a) {
;         uint2 ua = *(const uint2*)(z + (size_t)m * ZS + C_MA + n);
;         uint2 ub = *(const uint2*)(z + (size_t)m * ZS + C_MB + n);
;         a[0] *= sigmoidf(bflo(ua.x)) * inv_sigmoidf(bflo(ub.x));
;         a[1] *= sigmoidf(bfhi(ua.x)) * inv_sigmoidf(bfhi(ub.x));
;         a[2] *= sigmoidf(bflo(ua.y)) * inv_sigmoidf(bflo(ub.y));
;         a[3] *= sigmoidf(bfhi(ua.y)) * inv_sigmoidf(bfhi(ub.y));
;       });
	v_lshlrev_b32_e32 v143, 16, v146
	v_mul_f32_e32 v143, 0xbfb8aa3b, v143
	v_exp_f32_e32 v150, v143
	v_and_b32_e32 v143, 0xffff0000, v144
	v_mul_f32_e32 v143, 0xbfb8aa3b, v143
	v_exp_f32_e32 v143, v143
	s_nop 0
	v_add_f32_e32 v143, 1.0, v143
	v_rcp_f32_e32 v149, v143
	v_and_b32_e32 v143, 0xffff0000, v146
	v_mul_f32_e32 v143, 0xbfb8aa3b, v143
	v_exp_f32_e32 v151, v143
	v_lshlrev_b32_e32 v143, 16, v145
	v_mul_f32_e32 v143, 0xbfb8aa3b, v143
	v_exp_f32_e32 v143, v143
	v_pk_add_f32 v[150:151], v[150:151], 1.0 op_sel_hi:[1,0]
	v_add_f32_e32 v143, 1.0, v143
	v_rcp_f32_e32 v144, v143
	v_lshlrev_b32_e32 v143, 16, v147
	v_mul_f32_e32 v143, 0xbfb8aa3b, v143
	v_exp_f32_e32 v146, v143
	v_and_b32_e32 v143, 0xffff0000, v145
	v_mul_f32_e32 v143, 0xbfb8aa3b, v143
	v_exp_f32_e32 v143, v143
	v_pk_mul_f32 v[148:149], v[148:149], v[150:151]
	v_add_f32_e32 v143, 1.0, v143
	v_rcp_f32_e32 v145, v143
	v_and_b32_e32 v143, 0xffff0000, v147
	v_mul_f32_e32 v143, 0xbfb8aa3b, v143
	v_exp_f32_e32 v147, v143
	v_pk_mul_f32 v[74:75], v[74:75], v[148:149]
	v_pk_add_f32 v[146:147], v[146:147], 1.0 op_sel_hi:[1,0]
	s_nop 0
	v_pk_mul_f32 v[144:145], v[144:145], v[146:147]
	v_lshl_add_u64 v[146:147], v[140:141], 0, v[134:135]
	v_pk_mul_f32 v[76:77], v[76:77], v[144:145]
	v_lshl_add_u64 v[144:145], v[138:139], 0, v[134:135]
	global_load_dwordx2 v[144:145], v[144:145], off
	s_nop 0
	global_load_dwordx2 v[146:147], v[146:147], off
	s_waitcnt vmcnt(1)
	v_lshlrev_b32_e32 v143, 16, v144
	v_mul_f32_e32 v143, 0xbfb8aa3b, v143
	v_exp_f32_e32 v143, v143
	s_nop 0
	v_add_f32_e32 v143, 1.0, v143
	v_rcp_f32_e32 v148, v143
	s_waitcnt vmcnt(0)
	v_lshlrev_b32_e32 v143, 16, v146
	v_mul_f32_e32 v143, 0xbfb8aa3b, v143
	v_exp_f32_e32 v150, v143
	v_and_b32_e32 v143, 0xffff0000, v144
	v_mul_f32_e32 v143, 0xbfb8aa3b, v143
	v_exp_f32_e32 v143, v143
	s_nop 0
	v_add_f32_e32 v143, 1.0, v143
	v_rcp_f32_e32 v149, v143
	v_and_b32_e32 v143, 0xffff0000, v146
	v_mul_f32_e32 v143, 0xbfb8aa3b, v143
	v_exp_f32_e32 v151, v143
	v_lshlrev_b32_e32 v143, 16, v145
	v_mul_f32_e32 v143, 0xbfb8aa3b, v143
	v_exp_f32_e32 v143, v143
	v_pk_add_f32 v[150:151], v[150:151], 1.0 op_sel_hi:[1,0]
	v_add_f32_e32 v143, 1.0, v143
	v_rcp_f32_e32 v144, v143
	v_lshlrev_b32_e32 v143, 16, v147
	v_mul_f32_e32 v143, 0xbfb8aa3b, v143
	v_exp_f32_e32 v146, v143
	v_and_b32_e32 v143, 0xffff0000, v145
	v_mul_f32_e32 v143, 0xbfb8aa3b, v143
	v_exp_f32_e32 v143, v143
	v_pk_mul_f32 v[148:149], v[148:149], v[150:151]
	v_add_f32_e32 v143, 1.0, v143
	v_rcp_f32_e32 v145, v143
	v_and_b32_e32 v143, 0xffff0000, v147
	v_mul_f32_e32 v143, 0xbfb8aa3b, v143
	v_exp_f32_e32 v147, v143
	v_pk_mul_f32 v[66:67], v[66:67], v[148:149]
	v_pk_add_f32 v[146:147], v[146:147], 1.0 op_sel_hi:[1,0]
	s_nop 0
	v_pk_mul_f32 v[144:145], v[144:145], v[146:147]
	v_lshl_add_u64 v[146:147], v[140:141], 0, v[132:133]
	v_pk_mul_f32 v[68:69], v[68:69], v[144:145]
	v_lshl_add_u64 v[144:145], v[138:139], 0, v[132:133]
	global_load_dwordx2 v[144:145], v[144:145], off
	v_lshl_add_u64 v[138:139], v[138:139], 0, v[130:131]
	global_load_dwordx2 v[146:147], v[146:147], off
	v_lshl_add_u64 v[140:141], v[140:141], 0, v[130:131]
	global_load_dwordx2 v[138:139], v[138:139], off
	s_nop 0
	global_load_dwordx2 v[140:141], v[140:141], off
	s_waitcnt vmcnt(3)
	v_lshlrev_b32_e32 v143, 16, v144
	v_mul_f32_e32 v143, 0xbfb8aa3b, v143
	v_exp_f32_e32 v143, v143
	s_nop 0
	v_add_f32_e32 v143, 1.0, v143
	v_rcp_f32_e32 v148, v143
	s_waitcnt vmcnt(2)
	v_lshlrev_b32_e32 v143, 16, v146
	v_mul_f32_e32 v143, 0xbfb8aa3b, v143
	v_exp_f32_e32 v150, v143
	v_and_b32_e32 v143, 0xffff0000, v144
	v_mul_f32_e32 v143, 0xbfb8aa3b, v143
	v_exp_f32_e32 v143, v143
	s_nop 0
	v_add_f32_e32 v143, 1.0, v143
	v_rcp_f32_e32 v149, v143
	v_and_b32_e32 v143, 0xffff0000, v146
	v_mul_f32_e32 v143, 0xbfb8aa3b, v143
	v_exp_f32_e32 v151, v143
	v_lshlrev_b32_e32 v143, 16, v145
	v_mul_f32_e32 v143, 0xbfb8aa3b, v143
	v_exp_f32_e32 v143, v143
	v_pk_add_f32 v[150:151], v[150:151], 1.0 op_sel_hi:[1,0]
	v_add_f32_e32 v143, 1.0, v143
	v_rcp_f32_e32 v144, v143
	v_lshlrev_b32_e32 v143, 16, v147
	v_mul_f32_e32 v143, 0xbfb8aa3b, v143
	v_exp_f32_e32 v146, v143
	v_and_b32_e32 v143, 0xffff0000, v145
	v_mul_f32_e32 v143, 0xbfb8aa3b, v143
	v_exp_f32_e32 v143, v143
	v_pk_mul_f32 v[148:149], v[148:149], v[150:151]
	v_add_f32_e32 v143, 1.0, v143
	v_rcp_f32_e32 v145, v143
	v_and_b32_e32 v143, 0xffff0000, v147
	v_mul_f32_e32 v143, 0xbfb8aa3b, v143
	v_exp_f32_e32 v147, v143
	s_waitcnt vmcnt(1)
	v_lshlrev_b32_e32 v143, 16, v138
	v_and_b32_e32 v138, 0xffff0000, v138
	v_mul_f32_e32 v138, 0xbfb8aa3b, v138
	v_exp_f32_e32 v138, v138
	v_pk_add_f32 v[146:147], v[146:147], 1.0 op_sel_hi:[1,0]
	v_mul_f32_e32 v143, 0xbfb8aa3b, v143
	v_pk_mul_f32 v[144:145], v[144:145], v[146:147]
	v_add_f32_e32 v138, 1.0, v138
	v_pk_mul_f32 v[60:61], v[60:61], v[144:145]
	v_rcp_f32_e32 v145, v138
	s_waitcnt vmcnt(0)
	v_and_b32_e32 v138, 0xffff0000, v140
	v_exp_f32_e32 v143, v143
	v_mul_f32_e32 v138, 0xbfb8aa3b, v138
	v_exp_f32_e32 v147, v138
	v_lshlrev_b32_e32 v138, 16, v139
	v_and_b32_e32 v139, 0xffff0000, v139
	v_mul_f32_e32 v138, 0xbfb8aa3b, v138
	v_mul_f32_e32 v139, 0xbfb8aa3b, v139
	v_exp_f32_e32 v138, v138
	v_exp_f32_e32 v139, v139
	v_add_f32_e32 v143, 1.0, v143
	v_rcp_f32_e32 v144, v143
	v_lshlrev_b32_e32 v143, 16, v140
	v_lshlrev_b32_e32 v140, 16, v141
	v_and_b32_e32 v141, 0xffff0000, v141
	v_mul_f32_e32 v140, 0xbfb8aa3b, v140
	v_mul_f32_e32 v141, 0xbfb8aa3b, v141
	v_add_f32_e32 v138, 1.0, v138
	v_exp_f32_e32 v140, v140
	v_add_f32_e32 v139, 1.0, v139
	v_exp_f32_e32 v141, v141
	v_rcp_f32_e32 v138, v138
	v_rcp_f32_e32 v139, v139
	v_mul_f32_e32 v143, 0xbfb8aa3b, v143
	v_pk_add_f32 v[140:141], v[140:141], 1.0 op_sel_hi:[1,0]
	v_exp_f32_e32 v146, v143
	v_pk_mul_f32 v[138:139], v[138:139], v[140:141]
	v_pk_mul_f32 v[58:59], v[58:59], v[148:149]
	v_pk_mul_f32 v[52:53], v[52:53], v[138:139]
	v_or_b32_e32 v138, 0x70, v142
	v_mad_i64_i32 v[138:139], s[26:27], v138, s35, v[136:137]
	v_lshl_add_u64 v[136:137], v[138:139], 0, s[30:31]
	v_lshl_add_u64 v[140:141], v[136:137], 0, v[0:1]
	global_load_dwordx2 v[140:141], v[140:141], off
	v_lshl_add_u64 v[138:139], v[138:139], 0, s[42:43]
	v_lshl_add_u64 v[142:143], v[138:139], 0, v[0:1]
	global_load_dwordx2 v[142:143], v[142:143], off
	v_pk_add_f32 v[146:147], v[146:147], 1.0 op_sel_hi:[1,0]
	s_waitcnt vmcnt(1)
; DI float bflo(unsigned u) { return __uint_as_float(u << 16); }
; DI float bfhi(unsigned u) { return __uint_as_float(u & 0xffff0000u); }
; DI float sigmoidf(float x) { return __builtin_amdgcn_rcpf(1.f + __expf(-x)); }
; DI float inv_sigmoidf(float x) { return 1.f + __expf(-x); }
; DI int TID8() { int t = threadIdx.x; asm volatile("" : "+v"(t)); return t; }
; template <class E>
; DI void gemm8_epi(f32x4 (&acc)[8][4], int m0, int n0, E e) {
;   const int tid = TID8(), lane = tid & 63, w = tid >> 6;
;   const int wm = w >> 2, wn = w & 3;
; #pragma unroll
;   for (int i = 0; i < 8; ++i)
; #pragma unroll
;     for (int j = 0; j < 4; ++j) {
;       const int m = m0 + wm * 128 + i * 16 + (lane & 15);
;       const int n = n0 + wn * 64 + j * 16 + (lane >> 4) * 4;
;       e(m, n, acc[i][j]);
;     }
; }
; __global__ void __launch_bounds__(512, 2) mega(Params p) {
;     ...
;       gemm8_epi(acc8, m0, n0, [&](int m, int n, f32x4& a) {
;         uint2 ua = *(const uint2*)(z + (size_t)m * ZS + C_MA + n);
;         uint2 ub = *(const uint2*)(z + (size_t)m * ZS + C_MB + n);
;         a[0] *= sigmoidf(bflo(ua.x)) * inv_sigmoidf(bflo(ub.x));
;         a[1] *= sigmoidf(bfhi(ua.x)) * inv_sigmoidf(bfhi(ub.x));
;         a[2] *= sigmoidf(bflo(ua.y)) * inv_sigmoidf(bflo(ub.y));
;         a[3] *= sigmoidf(bfhi(ua.y)) * inv_sigmoidf(bfhi(ub.y));
;       });
	v_lshlrev_b32_e32 v0, 16, v140
	v_mul_f32_e32 v0, 0xbfb8aa3b, v0
	v_exp_f32_e32 v0, v0
	v_pk_mul_f32 v[144:145], v[144:145], v[146:147]
	v_add_f32_e32 v0, 1.0, v0
	v_pk_mul_f32 v[50:51], v[50:51], v[144:145]
	v_rcp_f32_e32 v144, v0
	s_waitcnt vmcnt(0)
	v_lshlrev_b32_e32 v0, 16, v142
	v_mul_f32_e32 v0, 0xbfb8aa3b, v0
	v_exp_f32_e32 v146, v0
	v_and_b32_e32 v0, 0xffff0000, v140
	v_mul_f32_e32 v0, 0xbfb8aa3b, v0
	v_exp_f32_e32 v0, v0
	s_nop 0
	v_add_f32_e32 v0, 1.0, v0
	v_rcp_f32_e32 v145, v0
	v_and_b32_e32 v0, 0xffff0000, v142
	v_mul_f32_e32 v0, 0xbfb8aa3b, v0
	v_exp_f32_e32 v147, v0
	v_lshlrev_b32_e32 v0, 16, v141
	v_mul_f32_e32 v0, 0xbfb8aa3b, v0
	v_exp_f32_e32 v0, v0
	v_pk_add_f32 v[146:147], v[146:147], 1.0 op_sel_hi:[1,0]
	v_add_f32_e32 v0, 1.0, v0
	v_rcp_f32_e32 v140, v0
	v_lshlrev_b32_e32 v0, 16, v143
	v_mul_f32_e32 v0, 0xbfb8aa3b, v0
	v_exp_f32_e32 v142, v0
	v_and_b32_e32 v0, 0xffff0000, v141
	v_mul_f32_e32 v0, 0xbfb8aa3b, v0
	v_exp_f32_e32 v0, v0
	v_pk_mul_f32 v[144:145], v[144:145], v[146:147]
	v_add_f32_e32 v0, 1.0, v0
	v_rcp_f32_e32 v141, v0
	v_and_b32_e32 v0, 0xffff0000, v143
	v_mul_f32_e32 v0, 0xbfb8aa3b, v0
	v_exp_f32_e32 v143, v0
	v_pk_mul_f32 v[42:43], v[42:43], v[144:145]
	v_pk_add_f32 v[142:143], v[142:143], 1.0 op_sel_hi:[1,0]
	s_nop 0
	v_pk_mul_f32 v[140:141], v[140:141], v[142:143]
	s_nop 0
	v_pk_mul_f32 v[44:45], v[44:45], v[140:141]
	v_lshl_add_u64 v[140:141], v[136:137], 0, v[134:135]
	global_load_dwordx2 v[140:141], v[140:141], off
	v_lshl_add_u64 v[134:135], v[138:139], 0, v[134:135]
	global_load_dwordx2 v[134:135], v[134:135], off
	s_waitcnt vmcnt(1)
	v_lshlrev_b32_e32 v0, 16, v140
	v_mul_f32_e32 v0, 0xbfb8aa3b, v0
	v_exp_f32_e32 v0, v0
	s_nop 0
	v_add_f32_e32 v0, 1.0, v0
	v_rcp_f32_e32 v142, v0
	s_waitcnt vmcnt(0)
	v_lshlrev_b32_e32 v0, 16, v134
	v_mul_f32_e32 v0, 0xbfb8aa3b, v0
	v_exp_f32_e32 v144, v0
	v_and_b32_e32 v0, 0xffff0000, v140
	v_mul_f32_e32 v0, 0xbfb8aa3b, v0
	v_exp_f32_e32 v0, v0
	s_nop 0
	v_add_f32_e32 v0, 1.0, v0
	v_rcp_f32_e32 v143, v0
	v_and_b32_e32 v0, 0xffff0000, v134
	v_mul_f32_e32 v0, 0xbfb8aa3b, v0
	v_exp_f32_e32 v145, v0
	v_lshlrev_b32_e32 v0, 16, v141
	v_mul_f32_e32 v0, 0xbfb8aa3b, v0
	v_exp_f32_e32 v0, v0
	v_pk_add_f32 v[144:145], v[144:145], 1.0 op_sel_hi:[1,0]
	v_add_f32_e32 v0, 1.0, v0
	v_rcp_f32_e32 v140, v0
	v_lshlrev_b32_e32 v0, 16, v135
	v_mul_f32_e32 v0, 0xbfb8aa3b, v0
	v_exp_f32_e32 v134, v0
	v_and_b32_e32 v0, 0xffff0000, v141
	v_mul_f32_e32 v0, 0xbfb8aa3b, v0
	v_exp_f32_e32 v0, v0
	v_pk_mul_f32 v[142:143], v[142:143], v[144:145]
	v_mov_b32_e32 v145, v1
	v_pk_mul_f32 v[34:35], v[34:35], v[142:143]
	v_add_f32_e32 v0, 1.0, v0
	v_rcp_f32_e32 v141, v0
	v_and_b32_e32 v0, 0xffff0000, v135
	v_mul_f32_e32 v0, 0xbfb8aa3b, v0
	v_exp_f32_e32 v135, v0
	s_nop 0
	v_pk_add_f32 v[134:135], v[134:135], 1.0 op_sel_hi:[1,0]
	s_nop 0
	v_pk_mul_f32 v[134:135], v[140:141], v[134:135]
	s_nop 0
	v_pk_mul_f32 v[36:37], v[36:37], v[134:135]
	v_lshl_add_u64 v[134:135], v[136:137], 0, v[132:133]
	global_load_dwordx2 v[134:135], v[134:135], off
	v_lshl_add_u64 v[132:133], v[138:139], 0, v[132:133]
	global_load_dwordx2 v[132:133], v[132:133], off
	s_waitcnt vmcnt(1)
	v_lshlrev_b32_e32 v0, 16, v134
	v_mul_f32_e32 v0, 0xbfb8aa3b, v0
	v_exp_f32_e32 v0, v0
	s_nop 0
	v_add_f32_e32 v0, 1.0, v0
	v_rcp_f32_e32 v140, v0
	s_waitcnt vmcnt(0)
	v_lshlrev_b32_e32 v0, 16, v132
	v_mul_f32_e32 v0, 0xbfb8aa3b, v0
	v_exp_f32_e32 v142, v0
	v_and_b32_e32 v0, 0xffff0000, v134
	v_mul_f32_e32 v0, 0xbfb8aa3b, v0
	v_exp_f32_e32 v0, v0
	s_nop 0
	v_add_f32_e32 v0, 1.0, v0
	v_rcp_f32_e32 v141, v0
	v_and_b32_e32 v0, 0xffff0000, v132
	v_mul_f32_e32 v0, 0xbfb8aa3b, v0
	v_exp_f32_e32 v143, v0
	v_lshlrev_b32_e32 v0, 16, v135
	v_mul_f32_e32 v0, 0xbfb8aa3b, v0
	v_exp_f32_e32 v0, v0
	v_pk_add_f32 v[142:143], v[142:143], 1.0 op_sel_hi:[1,0]
	v_add_f32_e32 v0, 1.0, v0
	v_rcp_f32_e32 v134, v0
	v_lshlrev_b32_e32 v0, 16, v133
	v_mul_f32_e32 v0, 0xbfb8aa3b, v0
	v_exp_f32_e32 v132, v0
	v_and_b32_e32 v0, 0xffff0000, v135
	v_mul_f32_e32 v0, 0xbfb8aa3b, v0
	v_exp_f32_e32 v0, v0
	v_pk_mul_f32 v[140:141], v[140:141], v[142:143]
	v_mov_b32_e32 v143, v1
	v_pk_mul_f32 v[26:27], v[26:27], v[140:141]
	v_add_f32_e32 v0, 1.0, v0
	v_rcp_f32_e32 v135, v0
	v_and_b32_e32 v0, 0xffff0000, v133
	v_mul_f32_e32 v0, 0xbfb8aa3b, v0
	v_exp_f32_e32 v133, v0
	s_nop 0
	v_pk_add_f32 v[132:133], v[132:133], 1.0 op_sel_hi:[1,0]
	s_nop 0
	v_pk_mul_f32 v[132:133], v[134:135], v[132:133]
	s_nop 0
	v_pk_mul_f32 v[28:29], v[28:29], v[132:133]
	v_lshl_add_u64 v[132:133], v[136:137], 0, v[130:131]
	global_load_dwordx2 v[132:133], v[132:133], off
	v_lshl_add_u64 v[130:131], v[138:139], 0, v[130:131]
	global_load_dwordx2 v[130:131], v[130:131], off
	v_mov_b32_e32 v139, v1
	v_ashrrev_i32_e32 v173, 3, v172
	v_lshrrev_b32_e32 v140, 1, v173
	v_xor_b32_e32 v140, v140, v172
	v_lshlrev_b32_e32 v140, 3, v140
	v_and_b32_e32 v174, 56, v140
	v_lshrrev_b32_e32 v175, 1, v172
	v_bfe_u32 v176, v172, 1, 3
	v_lshlrev_b32_e32 v191, 1, v174
	v_lshlrev_b32_e32 v163, 6, v173
	s_waitcnt vmcnt(1)
; DI float bflo(unsigned u) { return __uint_as_float(u << 16); }
; DI float bfhi(unsigned u) { return __uint_as_float(u & 0xffff0000u); }
; DI float sigmoidf(float x) { return __builtin_amdgcn_rcpf(1.f + __expf(-x)); }
; DI float inv_sigmoidf(float x) { return 1.f + __expf(-x); }
; DI int TID8() { int t = threadIdx.x; asm volatile("" : "+v"(t)); return t; }
; DI void gemm8_accum(f32x4 (&acc)[8][4], const bf16_t* a, size_t lda, const bf16_t* b, size_t ldb, int nkb, bf16_t* L,
;                     const bool pre, const bf16_t* an, size_t ldan, const bf16_t* bn, size_t ldbn) {
;   const int tid = TID8(), lane = tid & 63, w = tid >> 6;
;   const int wm = w >> 2, wn = w & 3;
;   const int lrow = tid >> 3, lch = tid & 7;
;   u32x4 ra[4], rb[4];
;   unsigned offa[4], offb[4];
; #pragma unroll
;   for (int i = 0; i < 4; ++i) {
;     offa[i] = (unsigned)(lrow + 64 * i) * (unsigned)lda + (unsigned)(lch * 8);
;     offb[i] = (unsigned)(lrow + 64 * i) * (unsigned)ldb + (unsigned)(lch * 8);
;   }
;   if (!pre) {
;     g8_load1o(ra, a, offa);
;     g8_load1o(rb, b, offb);
;     __syncthreads();
;     g8_store(L, ra, rb, lrow, lch);
;   }
;   g8_load1o(ra, a + 64, offa);
;   g8_load1o(rb, b + 64, offb);
; __global__ void __launch_bounds__(512, 2) mega(Params p) {
;     ...
;       gemm8_epi(acc8, m0, n0, [&](int m, int n, f32x4& a) {
;         uint2 ua = *(const uint2*)(z + (size_t)m * ZS + C_MA + n);
;         uint2 ub = *(const uint2*)(z + (size_t)m * ZS + C_MB + n);
;         a[0] *= sigmoidf(bflo(ua.x)) * inv_sigmoidf(bflo(ub.x));
;         a[1] *= sigmoidf(bfhi(ua.x)) * inv_sigmoidf(bfhi(ub.x));
;         a[2] *= sigmoidf(bflo(ua.y)) * inv_sigmoidf(bflo(ub.y));
;         a[3] *= sigmoidf(bfhi(ua.y)) * inv_sigmoidf(bfhi(ub.y));
;       });
;       gemm8_accum(acc8, z + (size_t)m0 * ZS + C_RQ, ZS, wl + W_UPR + (size_t)n0 * 512, 512, 8, lds_all, true,
;                   (const bf16_t*)(p.ws + O_ONSA) + (size_t)mtn * 256 * 512, 512, wl + W_UPA + (size_t)ntilen * 256 * 512, 512);
	v_lshlrev_b32_e32 v0, 16, v132
	v_mul_f32_e32 v0, 0xbfb8aa3b, v0
	v_exp_f32_e32 v0, v0
	s_nop 0
	v_add_f32_e32 v0, 1.0, v0
	v_rcp_f32_e32 v134, v0
	s_waitcnt vmcnt(0)
	v_lshlrev_b32_e32 v0, 16, v130
	v_mul_f32_e32 v0, 0xbfb8aa3b, v0
	v_exp_f32_e32 v136, v0
	v_and_b32_e32 v0, 0xffff0000, v132
	v_mul_f32_e32 v0, 0xbfb8aa3b, v0
	v_exp_f32_e32 v0, v0
	s_nop 0
	v_add_f32_e32 v0, 1.0, v0
	v_rcp_f32_e32 v135, v0
	v_and_b32_e32 v0, 0xffff0000, v130
	v_mul_f32_e32 v0, 0xbfb8aa3b, v0
	v_exp_f32_e32 v137, v0
	v_lshlrev_b32_e32 v0, 16, v133
	v_mul_f32_e32 v0, 0xbfb8aa3b, v0
	v_exp_f32_e32 v0, v0
	v_pk_add_f32 v[136:137], v[136:137], 1.0 op_sel_hi:[1,0]
	v_add_f32_e32 v0, 1.0, v0
	v_rcp_f32_e32 v132, v0
	v_lshlrev_b32_e32 v0, 16, v131
	v_mul_f32_e32 v0, 0xbfb8aa3b, v0
	v_exp_f32_e32 v130, v0
	v_and_b32_e32 v0, 0xffff0000, v133
	v_mul_f32_e32 v0, 0xbfb8aa3b, v0
	v_exp_f32_e32 v0, v0
	v_pk_mul_f32 v[134:135], v[134:135], v[136:137]
	v_mov_b32_e32 v137, v1
	v_pk_mul_f32 v[18:19], v[18:19], v[134:135]
	v_add_f32_e32 v0, 1.0, v0
	v_rcp_f32_e32 v133, v0
	v_and_b32_e32 v0, 0xffff0000, v131
	v_mul_f32_e32 v0, 0xbfb8aa3b, v0
	v_exp_f32_e32 v131, v0
	v_lshlrev_b32_e32 v0, 3, v172
	v_and_b32_e32 v0, 56, v0
	v_mov_b32_e32 v135, v1
	v_pk_add_f32 v[130:131], v[130:131], 1.0 op_sel_hi:[1,0]
	s_nop 0
	v_pk_mul_f32 v[130:131], v[132:133], v[130:131]
	v_lshl_or_b32 v132, v173, 9, v0
	v_pk_mul_f32 v[20:21], v[20:21], v[130:131]
	v_mad_u64_u32 v[130:131], s[26:27], v173, s25, v[0:1]
	v_mov_b32_e32 v131, v1
	v_add_u32_e32 v144, 0x18000, v132
	v_add_u32_e32 v0, 0x54600, v130
	v_add_u32_e32 v142, 0x10000, v132
	v_lshlrev_b64 v[186:187], 1, v[130:131]
	v_lshlrev_b64 v[170:171], 1, v[144:145]
	v_add_u32_e32 v136, 0xa8c00, v130
	v_add_u32_e32 v138, 0xfd200, v130
	v_lshl_add_u64 v[130:131], s[2:3], 0, v[186:187]
	v_lshlrev_b64 v[184:185], 1, v[0:1]
	v_lshlrev_b64 v[168:169], 1, v[142:143]
	v_lshl_add_u64 v[142:143], s[6:7], 0, v[170:171]
	global_load_dwordx4 v[146:149], v[130:131], off offset:2736
	v_lshlrev_b64 v[182:183], 1, v[136:137]
	global_load_dwordx4 v[142:145], v[142:143], off offset:128
	v_lshl_add_u64 v[130:131], s[2:3], 0, v[184:185]
	v_add_u32_e32 v134, 0x8000, v132
	v_mov_b32_e32 v133, v1
	global_load_dwordx4 v[150:153], v[130:131], off offset:2736
	v_lshl_add_u64 v[130:131], s[2:3], 0, v[182:183]
	v_lshlrev_b64 v[180:181], 1, v[138:139]
	global_load_dwordx4 v[154:157], v[130:131], off offset:2736
	v_lshl_add_u64 v[130:131], s[2:3], 0, v[180:181]
	v_lshlrev_b64 v[164:165], 1, v[132:133]
	v_lshlrev_b64 v[166:167], 1, v[134:135]
	global_load_dwordx4 v[158:161], v[130:131], off offset:2736
	v_lshl_add_u64 v[130:131], s[6:7], 0, v[164:165]
	v_lshl_add_u64 v[134:135], s[6:7], 0, v[166:167]
	global_load_dwordx4 v[130:133], v[130:131], off offset:128
	v_bfe_u32 v0, v172, 4, 2
	global_load_dwordx4 v[138:141], v[134:135], off offset:128
	v_lshl_add_u64 v[134:135], s[6:7], 0, v[168:169]
	global_load_dwordx4 v[134:137], v[134:135], off offset:128
	v_bitop3_b32 v175, v175, v0, 7 bitop3:0x6c
	v_lshlrev_b32_e32 v192, 3, v175
	v_lshlrev_b32_e32 v175, 5, v172
	v_and_b32_e32 v175, 0xffffe000, v175
	v_lshlrev_b32_e32 v172, 6, v172
	v_and_or_b32 v188, v172, s1, v175
	v_readlane_b32 s1, v254, 20
	s_add_u32 s2, s1, s21
	v_readlane_b32 s1, v254, 21
	s_addc_u32 s3, s1, 0
	v_readlane_b32 s1, v254, 22
	v_bitop3_b32 v0, v0, v176, 4 bitop3:0x36
	s_add_u32 s0, s1, s0
	v_readlane_b32 s1, v254, 23
	v_and_b32_e32 v193, 0x33c0, v172
	v_lshlrev_b32_e32 v190, 3, v0
	v_lshlrev_b32_e32 v0, 7, v173
	s_addc_u32 s1, s1, 0
	v_add3_u32 v0, 0, v191, v0
	v_lshl_add_u64 v[172:173], s[2:3], 0, v[170:171]
	v_lshl_add_u64 v[174:175], s[2:3], 0, v[168:169]
	v_lshl_add_u64 v[176:177], s[2:3], 0, v[166:167]
	v_lshl_add_u64 v[178:179], s[2:3], 0, v[164:165]
	v_lshl_add_u64 v[180:181], s[0:1], 0, v[180:181]
	v_lshl_add_u64 v[182:183], s[0:1], 0, v[182:183]
	v_lshl_add_u64 v[184:185], s[0:1], 0, v[184:185]
	v_lshl_add_u64 v[186:187], s[0:1], 0, v[186:187]
	s_mov_b64 s[0:1], 0
	s_mov_b32 s2, 0
	v_lshlrev_b32_e32 v189, 1, v188
	v_lshlrev_b32_e32 v188, 1, v193
	v_readfirstlane_b32 s52, v186
	v_readfirstlane_b32 s53, v187
	s_sub_u32 s52, s52, 0x40000000
	s_subb_u32 s53, s53, 0
	v_readfirstlane_b32 s56, v178
	v_readfirstlane_b32 s57, v179
	s_sub_u32 s56, s56, 0x40000000
	s_subb_u32 s57, s57, 0
	v_subrev_u32_e32 v187, s52, v186
	v_subrev_u32_e32 v185, s52, v184
	v_subrev_u32_e32 v183, s52, v182
	v_subrev_u32_e32 v181, s52, v180
	v_subrev_u32_e32 v179, s56, v178
	v_subrev_u32_e32 v177, s56, v176
	v_subrev_u32_e32 v175, s56, v174
	v_subrev_u32_e32 v173, s56, v172

; DI void gemm8_accum(f32x4 (&acc)[8][4], const bf16_t* a, size_t lda, const bf16_t* b, size_t ldb, int nkb, bf16_t* L,
;                     const bool pre, const bf16_t* an, size_t ldan, const bf16_t* bn, size_t ldbn) {
;     ...
;   for (int kb = 0; kb + 2 < nkb; ++kb) {
;     __syncthreads();
;     g8_store1(L + ((kb + 1) & 1) * 32768, ra, lrow, lch);
;     g8_load1o(ra, a + (kb + 2) * 64, offa);
;     __builtin_amdgcn_sched_barrier(0);
;     g8_compute<0, 1>(acc, L + (kb & 1) * 32768, wm, wn, lane);
;     __builtin_amdgcn_sched_barrier(0);
;     g8_store1(L + ((kb + 1) & 1) * 32768 + 16384, rb, lrow, lch);
;     g8_load1o(rb, b + (kb + 2) * 64, offb);
;     __builtin_amdgcn_sched_barrier(0);
;     g8_compute<1, 2>(acc, L + (kb & 1) * 32768, wm, wn, lane);
.Lstg_780_a:
	s_waitcnt vmcnt(7)
	ds_write_b128 v193, v[146:149]
	s_waitcnt vmcnt(5)
	ds_write_b128 v193, v[150:153] offset:8192
	s_waitcnt vmcnt(4)
	ds_write_b128 v193, v[154:157] offset:16384
	s_waitcnt vmcnt(3)
	ds_write_b128 v193, v[158:161] offset:24576
	s_add_u32 s54, s52, s0
	s_addc_u32 s55, s53, s1
	global_load_dwordx4 v[146:149], v187, s[54:55]
	s_nop 0
	global_load_dwordx4 v[150:153], v185, s[54:55]
	s_nop 0
	global_load_dwordx4 v[154:157], v183, s[54:55]
	s_nop 0
	global_load_dwordx4 v[158:161], v181, s[54:55]
	s_and_b32 s2, s2, 0x8000
	s_lshl_b32 s2, s2, 1
	s_add_i32 s2, s2, 0
	v_lshl_add_u32 v194, v192, 1, s2
	v_add_u32_e32 v195, v194, v189
	ds_read_b128 v[198:201], v195
	ds_read_b128 v[206:209], v195 offset:2048
	ds_read_b128 v[210:213], v195 offset:4096
	ds_read_b128 v[214:217], v195 offset:6144
	ds_read_b128 v[218:221], v195 offset:8192
	ds_read_b128 v[222:225], v195 offset:10240
	ds_read_b128 v[226:229], v195 offset:12288
	ds_read_b128 v[230:233], v195 offset:14336
	v_add_u32_e32 v194, v194, v188
	ds_read_b128 v[234:237], v194 offset:32768
	ds_read_b128 v[238:241], v194 offset:34816
	ds_read_b128 v[242:245], v194 offset:36864
	ds_read_b128 v[246:249], v194 offset:38912
	s_setprio 1
	s_waitcnt lgkmcnt(3)
	v_mfma_f32_16x16x32_bf16 v[2:5], v[234:237], v[198:201], v[2:5]
	s_waitcnt lgkmcnt(2)
	v_mfma_f32_16x16x32_bf16 v[6:9], v[238:241], v[198:201], v[6:9]
	s_waitcnt lgkmcnt(1)
	v_mfma_f32_16x16x32_bf16 v[10:13], v[242:245], v[198:201], v[10:13]
	s_waitcnt lgkmcnt(0)
	v_mfma_f32_16x16x32_bf16 v[14:17], v[246:249], v[198:201], v[14:17]
	v_mfma_f32_16x16x32_bf16 v[22:25], v[234:237], v[206:209], v[22:25]
	v_mfma_f32_16x16x32_bf16 v[30:33], v[238:241], v[206:209], v[30:33]
	v_mfma_f32_16x16x32_bf16 v[38:41], v[242:245], v[206:209], v[38:41]
	v_mfma_f32_16x16x32_bf16 v[46:49], v[246:249], v[206:209], v[46:49]
	v_mfma_f32_16x16x32_bf16 v[54:57], v[234:237], v[210:213], v[54:57]
	v_mfma_f32_16x16x32_bf16 v[62:65], v[238:241], v[210:213], v[62:65]
	v_mfma_f32_16x16x32_bf16 v[70:73], v[242:245], v[210:213], v[70:73]
	v_mfma_f32_16x16x32_bf16 v[78:81], v[246:249], v[210:213], v[78:81]
	v_mfma_f32_16x16x32_bf16 v[86:89], v[234:237], v[214:217], v[86:89]
	v_mfma_f32_16x16x32_bf16 v[94:97], v[238:241], v[214:217], v[94:97]
	v_mfma_f32_16x16x32_bf16 v[102:105], v[242:245], v[214:217], v[102:105]
	v_mfma_f32_16x16x32_bf16 v[110:113], v[246:249], v[214:217], v[110:113]
	v_mfma_f32_16x16x32_bf16 v[118:121], v[234:237], v[218:221], v[118:121]
	v_mfma_f32_16x16x32_bf16 v[126:129], v[238:241], v[218:221], v[126:129]
	v_mfma_f32_16x16x32_bf16 v[122:125], v[242:245], v[218:221], v[122:125]
	v_mfma_f32_16x16x32_bf16 v[114:117], v[246:249], v[218:221], v[114:117]
	v_mfma_f32_16x16x32_bf16 v[106:109], v[234:237], v[222:225], v[106:109]
	v_mfma_f32_16x16x32_bf16 v[98:101], v[238:241], v[222:225], v[98:101]
	v_mfma_f32_16x16x32_bf16 v[90:93], v[242:245], v[222:225], v[90:93]
	v_mfma_f32_16x16x32_bf16 v[82:85], v[246:249], v[222:225], v[82:85]
	v_mfma_f32_16x16x32_bf16 v[74:77], v[234:237], v[226:229], v[74:77]
	v_mfma_f32_16x16x32_bf16 v[66:69], v[238:241], v[226:229], v[66:69]
	v_mfma_f32_16x16x32_bf16 v[58:61], v[242:245], v[226:229], v[58:61]
	v_mfma_f32_16x16x32_bf16 v[50:53], v[246:249], v[226:229], v[50:53]
	v_mfma_f32_16x16x32_bf16 v[42:45], v[234:237], v[230:233], v[42:45]
	v_mfma_f32_16x16x32_bf16 v[34:37], v[238:241], v[230:233], v[34:37]
	v_mfma_f32_16x16x32_bf16 v[26:29], v[242:245], v[230:233], v[26:29]
	v_mfma_f32_16x16x32_bf16 v[18:21], v[246:249], v[230:233], v[18:21]
	s_setprio 0
	s_waitcnt vmcnt(6)
	ds_write_b128 v193, v[130:133] offset:32768
	s_waitcnt vmcnt(5)
	ds_write_b128 v193, v[138:141] offset:40960
	s_waitcnt vmcnt(4)
	ds_write_b128 v193, v[134:137] offset:49152
	ds_write_b128 v193, v[142:145] offset:57344
	s_add_u32 s58, s56, s0
	s_addc_u32 s59, s57, s1
	global_load_dwordx4 v[130:133], v179, s[58:59]
	s_nop 0
	global_load_dwordx4 v[138:141], v177, s[58:59]
	global_load_dwordx4 v[134:137], v175, s[58:59]
	s_nop 0
	global_load_dwordx4 v[142:145], v173, s[58:59]
	v_lshl_add_u32 v193, v190, 1, s2
	v_add_u32_e32 v194, v193, v189
	ds_read_b128 v[198:201], v194
	ds_read_b128 v[206:209], v194 offset:2048
	ds_read_b128 v[210:213], v194 offset:4096
	ds_read_b128 v[214:217], v194 offset:6144
	ds_read_b128 v[218:221], v194 offset:8192
	ds_read_b128 v[222:225], v194 offset:10240
	ds_read_b128 v[226:229], v194 offset:12288
	ds_read_b128 v[230:233], v194 offset:14336
	v_add_u32_e32 v193, v193, v188
	ds_read_b128 v[234:237], v193 offset:32768
	ds_read_b128 v[238:241], v193 offset:34816
	ds_read_b128 v[242:245], v193 offset:36864
	ds_read_b128 v[246:249], v193 offset:38912
	s_cmp_lg_u32 s101, 0
	s_cbranch_scc1 .Lstg_780_b
; DI f32x4 mfma16(bf16x8 a, bf16x8 b, f32x4 c) { return __builtin_amdgcn_mfma_f32_16x16x32_bf16(a, b, c, 0, 0, 0); }
; #pragma unroll
;   for (int ks = KS0; ks < KS1; ++ks) {
;     bf16x8 af[8], bfr[4];
; #pragma unroll
;     for (int i = 0; i < 8; ++i) {
;       const int r = wm * 128 + i * 16 + (lane & 15);
;       af[i] = *(const bf16x8*)(S + r * 64 + (((ks * 4 + (lane >> 4)) ^ ((r >> 1) & 7)) << 3));
;     }
; #pragma unroll
;     for (int j = 0; j < 4; ++j) {
;       const int r = wn * 64 + j * 16 + (lane & 15);
;       bfr[j] = *(const bf16x8*)(S + 16384 + r * 64 + (((ks * 4 + (lane >> 4)) ^ ((r >> 1) & 7)) << 3));
;     }
;     __builtin_amdgcn_s_setprio(1);
; #pragma unroll
;     for (int i = 0; i < 8; ++i)
; #pragma unroll
;       for (int j = 0; j < 4; ++j) acc[i][j] = mfma16(bfr[j], af[i], acc[i][j]);
;     __builtin_amdgcn_s_setprio(0);
;   }
; }
	s_setprio 1
	s_waitcnt lgkmcnt(3)
	v_mfma_f32_16x16x32_bf16 v[2:5], v[234:237], v[198:201], v[2:5]
	s_waitcnt lgkmcnt(2)
	v_mfma_f32_16x16x32_bf16 v[6:9], v[238:241], v[198:201], v[6:9]
	s_waitcnt lgkmcnt(1)
	v_mfma_f32_16x16x32_bf16 v[10:13], v[242:245], v[198:201], v[10:13]
	s_waitcnt lgkmcnt(0)
	v_mfma_f32_16x16x32_bf16 v[14:17], v[246:249], v[198:201], v[14:17]
	v_mfma_f32_16x16x32_bf16 v[22:25], v[234:237], v[206:209], v[22:25]
	v_mfma_f32_16x16x32_bf16 v[30:33], v[238:241], v[206:209], v[30:33]
	v_mfma_f32_16x16x32_bf16 v[38:41], v[242:245], v[206:209], v[38:41]
	v_mfma_f32_16x16x32_bf16 v[46:49], v[246:249], v[206:209], v[46:49]
	v_mfma_f32_16x16x32_bf16 v[54:57], v[234:237], v[210:213], v[54:57]
	v_mfma_f32_16x16x32_bf16 v[62:65], v[238:241], v[210:213], v[62:65]
	v_mfma_f32_16x16x32_bf16 v[70:73], v[242:245], v[210:213], v[70:73]
	v_mfma_f32_16x16x32_bf16 v[78:81], v[246:249], v[210:213], v[78:81]
	v_mfma_f32_16x16x32_bf16 v[86:89], v[234:237], v[214:217], v[86:89]
	v_mfma_f32_16x16x32_bf16 v[94:97], v[238:241], v[214:217], v[94:97]
	v_mfma_f32_16x16x32_bf16 v[102:105], v[242:245], v[214:217], v[102:105]
	v_mfma_f32_16x16x32_bf16 v[110:113], v[246:249], v[214:217], v[110:113]
	v_mfma_f32_16x16x32_bf16 v[118:121], v[234:237], v[218:221], v[118:121]
	v_mfma_f32_16x16x32_bf16 v[126:129], v[238:241], v[218:221], v[126:129]
	v_mfma_f32_16x16x32_bf16 v[122:125], v[242:245], v[218:221], v[122:125]
	v_mfma_f32_16x16x32_bf16 v[114:117], v[246:249], v[218:221], v[114:117]
	v_mfma_f32_16x16x32_bf16 v[106:109], v[234:237], v[222:225], v[106:109]
	v_mfma_f32_16x16x32_bf16 v[98:101], v[238:241], v[222:225], v[98:101]
	v_mfma_f32_16x16x32_bf16 v[90:93], v[242:245], v[222:225], v[90:93]
	v_mfma_f32_16x16x32_bf16 v[82:85], v[246:249], v[222:225], v[82:85]
	v_mfma_f32_16x16x32_bf16 v[74:77], v[234:237], v[226:229], v[74:77]
	v_mfma_f32_16x16x32_bf16 v[66:69], v[238:241], v[226:229], v[66:69]
	v_mfma_f32_16x16x32_bf16 v[58:61], v[242:245], v[226:229], v[58:61]
	v_mfma_f32_16x16x32_bf16 v[50:53], v[246:249], v[226:229], v[50:53]
	v_mfma_f32_16x16x32_bf16 v[42:45], v[234:237], v[230:233], v[42:45]
	v_mfma_f32_16x16x32_bf16 v[34:37], v[238:241], v[230:233], v[34:37]
	v_mfma_f32_16x16x32_bf16 v[26:29], v[242:245], v[230:233], v[26:29]
	v_mfma_f32_16x16x32_bf16 v[18:21], v[246:249], v[230:233], v[18:21]
	s_setprio 0

; DI int TID8() { int t = threadIdx.x; asm volatile("" : "+v"(t)); return t; }
; DI void gemm8_accum(f32x4 (&acc)[8][4], const bf16_t* a, size_t lda, const bf16_t* b, size_t ldb, int nkb, bf16_t* L,
;                     const bool pre, const bf16_t* an, size_t ldan, const bf16_t* bn, size_t ldbn) {
;   const int tid = TID8(), lane = tid & 63, w = tid >> 6;
;   const int wm = w >> 2, wn = w & 3;
;   const int lrow = tid >> 3, lch = tid & 7;
;   u32x4 ra[4], rb[4];
;   unsigned offa[4], offb[4];
; #pragma unroll
;   for (int i = 0; i < 4; ++i) {
;     offa[i] = (unsigned)(lrow + 64 * i) * (unsigned)lda + (unsigned)(lch * 8);
;     offb[i] = (unsigned)(lrow + 64 * i) * (unsigned)ldb + (unsigned)(lch * 8);
;   }
;   if (!pre) {
;     g8_load1o(ra, a, offa);
;     g8_load1o(rb, b, offb);
;     __syncthreads();
;     g8_store(L, ra, rb, lrow, lch);
;   }
;   g8_load1o(ra, a + 64, offa);
;   g8_load1o(rb, b + 64, offb);
; DI void zero_acc8(f32x4 (&acc)[8][4]) {
; #pragma unroll
;   for (int i = 0; i < 8; ++i)
; #pragma unroll
;     for (int j = 0; j < 4; ++j) acc[i][j] = f32x4{0.f, 0.f, 0.f, 0.f};
; }
.LBB0_829:
	v_lshlrev_b64 v[38:39], 1, v[0:1]
	v_lshlrev_b64 v[40:41], 1, v[176:177]
	v_lshl_add_u64 v[2:3], s[2:3], 0, v[38:39]
	v_lshl_add_u64 v[4:5], s[2:3], 0, v[40:41]
	v_lshlrev_b64 v[42:43], 1, v[174:175]
	v_lshlrev_b64 v[44:45], 1, v[172:173]
	global_load_dwordx4 v[18:21], v[2:3], off offset:3760
	global_load_dwordx4 v[22:25], v[4:5], off offset:3760
	v_lshl_add_u64 v[2:3], s[2:3], 0, v[42:43]
	v_lshl_add_u64 v[4:5], s[2:3], 0, v[44:45]
	v_lshlrev_b64 v[46:47], 1, v[170:171]
	v_lshlrev_b64 v[48:49], 1, v[168:169]
	v_lshlrev_b64 v[50:51], 1, v[166:167]
	v_lshlrev_b64 v[52:53], 1, v[164:165]
	global_load_dwordx4 v[26:29], v[2:3], off offset:3760
	global_load_dwordx4 v[30:33], v[4:5], off offset:3760
	v_lshl_add_u64 v[2:3], s[0:1], 0, v[46:47]
	v_lshl_add_u64 v[4:5], s[0:1], 0, v[48:49]
	v_lshl_add_u64 v[6:7], s[0:1], 0, v[50:51]
	v_lshl_add_u64 v[10:11], s[0:1], 0, v[52:53]
	global_load_dwordx4 v[14:17], v[2:3], off offset:128
	s_nop 0
	global_load_dwordx4 v[2:5], v[4:5], off offset:128
	s_nop 0
	global_load_dwordx4 v[6:9], v[6:7], off offset:128
	s_nop 0
	global_load_dwordx4 v[10:13], v[10:11], off offset:128
	v_bfe_u32 v37, v34, 4, 2
	v_lshrrev_b32_e32 v54, 1, v34
	v_bitop3_b32 v54, v54, v37, 7 bitop3:0x6c
	s_lshr_b32 s7, s13, 2
	s_lshl_b32 s6, s12, 8
	s_and_b32 s12, s10, 0x60
	v_readlane_b32 s20, v252, 25
	v_lshlrev_b32_e32 v169, 3, v54
	v_lshlrev_b32_e32 v54, 5, v34
	s_and_b32 s7, s7, 3
	s_or_b32 s12, s20, s12
	s_and_b32 s20, s9, 3
	v_bfe_u32 v55, v34, 1, 3
	v_and_b32_e32 v54, 0xffffe000, v54
	v_lshlrev_b32_e32 v34, 6, v34
	s_movk_i32 s0, 0x3c0
	s_lshl_b32 s7, s7, 19
	s_add_i32 s12, s12, s20
	v_and_or_b32 v54, v34, s0, v54
	v_readlane_b32 s0, v254, 24
	s_add_u32 s0, s0, s7
	v_readlane_b32 s1, v254, 25
	s_addc_u32 s1, s1, 0
	s_mul_i32 s12, s12, 0x2a3000
	v_lshl_add_u64 v[178:179], s[0:1], 0, v[52:53]
	v_lshl_add_u64 v[180:181], s[0:1], 0, v[50:51]
	v_lshl_add_u64 v[182:183], s[0:1], 0, v[48:49]
	v_lshl_add_u64 v[184:185], s[0:1], 0, v[46:47]
	v_readlane_b32 s0, v254, 26
	v_and_b32_e32 v56, 0x33c0, v34
	v_bitop3_b32 v34, v37, v55, 4 bitop3:0x36
	s_add_u32 s0, s0, s12
	v_readlane_b32 s1, v254, 27
	v_lshlrev_b32_e32 v205, 3, v34
	v_lshlrev_b32_e32 v165, 1, v36
	v_lshlrev_b32_e32 v167, 1, v35
	s_addc_u32 s1, s1, 0
	v_mov_b32_e32 v34, 0
	v_add3_u32 v163, 0, v165, v167
	v_lshl_add_u64 v[186:187], s[0:1], 0, v[44:45]
	v_lshl_add_u64 v[188:189], s[0:1], 0, v[42:43]
	v_lshl_add_u64 v[190:191], s[0:1], 0, v[40:41]
	v_lshl_add_u64 v[192:193], s[0:1], 0, v[38:39]
	s_mov_b64 s[0:1], 0
	s_mov_b32 s2, 0
	v_lshlrev_b32_e32 v195, 1, v54
	v_lshlrev_b32_e32 v194, 1, v56
	v_mov_b32_e32 v35, v34
	v_mov_b32_e32 v36, v34
	v_mov_b32_e32 v37, v34
	v_mov_b32_e32 v38, v34
	v_mov_b32_e32 v39, v34
	v_mov_b32_e32 v40, v34
	v_mov_b32_e32 v41, v34
	v_mov_b32_e32 v42, v34
	v_mov_b32_e32 v43, v34
	v_mov_b32_e32 v44, v34
	v_mov_b32_e32 v45, v34
	v_mov_b32_e32 v46, v34
	v_mov_b32_e32 v47, v34
	v_mov_b32_e32 v48, v34
	v_mov_b32_e32 v49, v34
	v_mov_b32_e32 v50, v34
	v_mov_b32_e32 v51, v34
	v_mov_b32_e32 v52, v34
	v_mov_b32_e32 v53, v34
	v_mov_b32_e32 v54, v34
	v_mov_b32_e32 v55, v34
	v_mov_b32_e32 v56, v34
	v_mov_b32_e32 v57, v34
	v_mov_b32_e32 v58, v34
	v_mov_b32_e32 v59, v34
	v_mov_b32_e32 v60, v34
	v_mov_b32_e32 v61, v34
	v_mov_b32_e32 v62, v34
	v_mov_b32_e32 v63, v34
	v_mov_b32_e32 v64, v34
	v_mov_b32_e32 v65, v34
	v_mov_b32_e32 v66, v34
	v_mov_b32_e32 v67, v34
	v_mov_b32_e32 v68, v34
	v_mov_b32_e32 v69, v34
	v_mov_b32_e32 v70, v34
	v_mov_b32_e32 v71, v34
	v_mov_b32_e32 v72, v34
	v_mov_b32_e32 v73, v34
	v_mov_b32_e32 v74, v34
	v_mov_b32_e32 v75, v34
	v_mov_b32_e32 v76, v34
	v_mov_b32_e32 v77, v34
	v_mov_b32_e32 v78, v34
	v_mov_b32_e32 v79, v34
	v_mov_b32_e32 v80, v34
	v_mov_b32_e32 v81, v34
	v_mov_b32_e32 v82, v34
	v_mov_b32_e32 v83, v34
	v_mov_b32_e32 v84, v34
	v_mov_b32_e32 v85, v34
	v_mov_b32_e32 v86, v34
	v_mov_b32_e32 v87, v34
	v_mov_b32_e32 v88, v34
	v_mov_b32_e32 v89, v34
	v_mov_b32_e32 v90, v34
	v_mov_b32_e32 v91, v34
	v_mov_b32_e32 v92, v34
	v_mov_b32_e32 v93, v34
	v_mov_b32_e32 v94, v34
	v_mov_b32_e32 v95, v34
	v_mov_b32_e32 v96, v34
	v_mov_b32_e32 v97, v34
	v_mov_b32_e32 v98, v34
	v_mov_b32_e32 v99, v34
	v_mov_b32_e32 v100, v34
	v_mov_b32_e32 v101, v34
	v_mov_b32_e32 v102, v34
	v_mov_b32_e32 v103, v34
	v_mov_b32_e32 v104, v34
	v_mov_b32_e32 v105, v34
	v_mov_b32_e32 v106, v34
	v_mov_b32_e32 v107, v34
	v_mov_b32_e32 v108, v34
	v_mov_b32_e32 v109, v34
	v_mov_b32_e32 v110, v34
	v_mov_b32_e32 v111, v34
	v_mov_b32_e32 v112, v34
	v_mov_b32_e32 v113, v34
	v_mov_b32_e32 v114, v34
	v_mov_b32_e32 v115, v34
	v_mov_b32_e32 v116, v34
	v_mov_b32_e32 v117, v34
	v_mov_b32_e32 v118, v34
	v_mov_b32_e32 v119, v34
	v_mov_b32_e32 v120, v34
	v_mov_b32_e32 v121, v34
	v_mov_b32_e32 v122, v34
	v_mov_b32_e32 v123, v34
	v_mov_b32_e32 v124, v34
	v_mov_b32_e32 v125, v34
	v_mov_b32_e32 v126, v34
	v_mov_b32_e32 v127, v34
	v_mov_b32_e32 v128, v34
	v_mov_b32_e32 v129, v34
	v_mov_b32_e32 v130, v34
	v_mov_b32_e32 v131, v34
	v_mov_b32_e32 v132, v34
	v_mov_b32_e32 v133, v34
	v_mov_b32_e32 v134, v34
	v_mov_b32_e32 v135, v34
	v_mov_b32_e32 v136, v34
	v_mov_b32_e32 v137, v34
	v_mov_b32_e32 v138, v34
	v_mov_b32_e32 v139, v34
	v_mov_b32_e32 v140, v34
	v_mov_b32_e32 v141, v34
	v_mov_b32_e32 v142, v34
	v_mov_b32_e32 v143, v34
	v_mov_b32_e32 v144, v34
	v_mov_b32_e32 v145, v34
	v_mov_b32_e32 v146, v34
	v_mov_b32_e32 v147, v34
	v_mov_b32_e32 v148, v34
	v_mov_b32_e32 v149, v34
	v_mov_b32_e32 v150, v34
	v_mov_b32_e32 v151, v34
	v_mov_b32_e32 v152, v34
	v_mov_b32_e32 v153, v34
	v_mov_b32_e32 v154, v34
	v_mov_b32_e32 v155, v34
	v_mov_b32_e32 v156, v34
	v_mov_b32_e32 v157, v34
	v_mov_b32_e32 v158, v34
	v_mov_b32_e32 v159, v34
	v_mov_b32_e32 v160, v34
	v_mov_b32_e32 v161, v34
	v_readfirstlane_b32 s52, v192
	v_readfirstlane_b32 s53, v193
	s_sub_u32 s52, s52, 0x40000000
	s_subb_u32 s53, s53, 0
	v_readfirstlane_b32 s56, v184
	v_readfirstlane_b32 s57, v185
	s_sub_u32 s56, s56, 0x40000000
	s_subb_u32 s57, s57, 0
	v_subrev_u32_e32 v193, s52, v192
	v_subrev_u32_e32 v191, s52, v190
	v_subrev_u32_e32 v189, s52, v188
	v_subrev_u32_e32 v187, s52, v186
	v_subrev_u32_e32 v185, s56, v184
	v_subrev_u32_e32 v183, s56, v182
	v_subrev_u32_e32 v181, s56, v180
	v_subrev_u32_e32 v179, s56, v178

; DI f32x4 mfma16(bf16x8 a, bf16x8 b, f32x4 c) { return __builtin_amdgcn_mfma_f32_16x16x32_bf16(a, b, c, 0, 0, 0); }
; #pragma unroll
;   for (int ks = KS0; ks < KS1; ++ks) {
;     bf16x8 af[8], bfr[4];
; #pragma unroll
;     for (int i = 0; i < 8; ++i) {
;       const int r = wm * 128 + i * 16 + (lane & 15);
;       af[i] = *(const bf16x8*)(S + r * 64 + (((ks * 4 + (lane >> 4)) ^ ((r >> 1) & 7)) << 3));
;     }
; #pragma unroll
;     for (int j = 0; j < 4; ++j) {
;       const int r = wn * 64 + j * 16 + (lane & 15);
;       bfr[j] = *(const bf16x8*)(S + 16384 + r * 64 + (((ks * 4 + (lane >> 4)) ^ ((r >> 1) & 7)) << 3));
;     }
;     __builtin_amdgcn_s_setprio(1);
; #pragma unroll
;     for (int i = 0; i < 8; ++i)
; #pragma unroll
;       for (int j = 0; j < 4; ++j) acc[i][j] = mfma16(bfr[j], af[i], acc[i][j]);
;     __builtin_amdgcn_s_setprio(0);
;   }
; }
; DI void gemm8_accum(f32x4 (&acc)[8][4], const bf16_t* a, size_t lda, const bf16_t* b, size_t ldb, int nkb, bf16_t* L,
;                     const bool pre, const bf16_t* an, size_t ldan, const bf16_t* bn, size_t ldbn) {
;     ...
;   for (int kb = 0; kb + 2 < nkb; ++kb) {
;     __syncthreads();
;     g8_store1(L + ((kb + 1) & 1) * 32768, ra, lrow, lch);
;     g8_load1o(ra, a + (kb + 2) * 64, offa);
;     __builtin_amdgcn_sched_barrier(0);
;     g8_compute<0, 1>(acc, L + (kb & 1) * 32768, wm, wn, lane);
;     __builtin_amdgcn_sched_barrier(0);
;     g8_store1(L + ((kb + 1) & 1) * 32768 + 16384, rb, lrow, lch);
;     g8_load1o(rb, b + (kb + 2) * 64, offb);
;     __builtin_amdgcn_sched_barrier(0);
;     g8_compute<1, 2>(acc, L + (kb & 1) * 32768, wm, wn, lane);
;   }
.Lstg_830_a:
	s_waitcnt vmcnt(7)
	ds_write_b128 v171, v[18:21]
	s_waitcnt vmcnt(6)
	ds_write_b128 v171, v[22:25] offset:8192
	s_waitcnt vmcnt(5)
	ds_write_b128 v171, v[26:29] offset:16384
	s_waitcnt vmcnt(4)
	ds_write_b128 v171, v[30:33] offset:24576
	s_add_u32 s54, s52, s0
	s_addc_u32 s55, s53, s1
	global_load_dwordx4 v[18:21], v193, s[54:55]
	s_nop 0
	global_load_dwordx4 v[22:25], v191, s[54:55]
	s_nop 0
	global_load_dwordx4 v[26:29], v189, s[54:55]
	s_nop 0
	global_load_dwordx4 v[30:33], v187, s[54:55]
	s_and_b32 s2, s2, 0x8000
	s_lshl_b32 s2, s2, 1
	s_add_i32 s2, s2, 0
	v_lshl_add_u32 v173, v169, 1, s2
	v_add_u32_e32 v175, v173, v195
	ds_read_b128 v[198:201], v175
	ds_read_b128 v[206:209], v175 offset:2048
	ds_read_b128 v[210:213], v175 offset:4096
	ds_read_b128 v[214:217], v175 offset:6144
	ds_read_b128 v[218:221], v175 offset:8192
	ds_read_b128 v[222:225], v175 offset:10240
	ds_read_b128 v[226:229], v175 offset:12288
	ds_read_b128 v[230:233], v175 offset:14336
	v_add_u32_e32 v173, v173, v194
	ds_read_b128 v[234:237], v173 offset:32768
	ds_read_b128 v[238:241], v173 offset:34816
	ds_read_b128 v[242:245], v173 offset:36864
	ds_read_b128 v[246:249], v173 offset:38912
	s_setprio 1
	s_waitcnt lgkmcnt(3)
	v_mfma_f32_16x16x32_bf16 v[158:161], v[234:237], v[198:201], v[158:161]
	s_waitcnt lgkmcnt(2)
	v_mfma_f32_16x16x32_bf16 v[154:157], v[238:241], v[198:201], v[154:157]
	s_waitcnt lgkmcnt(1)
	v_mfma_f32_16x16x32_bf16 v[150:153], v[242:245], v[198:201], v[150:153]
	s_waitcnt lgkmcnt(0)
	v_mfma_f32_16x16x32_bf16 v[146:149], v[246:249], v[198:201], v[146:149]
	v_mfma_f32_16x16x32_bf16 v[142:145], v[234:237], v[206:209], v[142:145]
	v_mfma_f32_16x16x32_bf16 v[138:141], v[238:241], v[206:209], v[138:141]
	v_mfma_f32_16x16x32_bf16 v[134:137], v[242:245], v[206:209], v[134:137]
	v_mfma_f32_16x16x32_bf16 v[130:133], v[246:249], v[206:209], v[130:133]
	v_mfma_f32_16x16x32_bf16 v[126:129], v[234:237], v[210:213], v[126:129]
	v_mfma_f32_16x16x32_bf16 v[122:125], v[238:241], v[210:213], v[122:125]
	v_mfma_f32_16x16x32_bf16 v[118:121], v[242:245], v[210:213], v[118:121]
	v_mfma_f32_16x16x32_bf16 v[114:117], v[246:249], v[210:213], v[114:117]
	v_mfma_f32_16x16x32_bf16 v[110:113], v[234:237], v[214:217], v[110:113]
	v_mfma_f32_16x16x32_bf16 v[106:109], v[238:241], v[214:217], v[106:109]
	v_mfma_f32_16x16x32_bf16 v[102:105], v[242:245], v[214:217], v[102:105]
	v_mfma_f32_16x16x32_bf16 v[98:101], v[246:249], v[214:217], v[98:101]
	v_mfma_f32_16x16x32_bf16 v[94:97], v[234:237], v[218:221], v[94:97]
	v_mfma_f32_16x16x32_bf16 v[90:93], v[238:241], v[218:221], v[90:93]
	v_mfma_f32_16x16x32_bf16 v[86:89], v[242:245], v[218:221], v[86:89]
	v_mfma_f32_16x16x32_bf16 v[82:85], v[246:249], v[218:221], v[82:85]
	v_mfma_f32_16x16x32_bf16 v[78:81], v[234:237], v[222:225], v[78:81]
	v_mfma_f32_16x16x32_bf16 v[74:77], v[238:241], v[222:225], v[74:77]
	v_mfma_f32_16x16x32_bf16 v[70:73], v[242:245], v[222:225], v[70:73]
	v_mfma_f32_16x16x32_bf16 v[66:69], v[246:249], v[222:225], v[66:69]
	v_mfma_f32_16x16x32_bf16 v[62:65], v[234:237], v[226:229], v[62:65]
	v_mfma_f32_16x16x32_bf16 v[58:61], v[238:241], v[226:229], v[58:61]
	v_mfma_f32_16x16x32_bf16 v[54:57], v[242:245], v[226:229], v[54:57]
	v_mfma_f32_16x16x32_bf16 v[50:53], v[246:249], v[226:229], v[50:53]
	v_mfma_f32_16x16x32_bf16 v[46:49], v[234:237], v[230:233], v[46:49]
	v_mfma_f32_16x16x32_bf16 v[42:45], v[238:241], v[230:233], v[42:45]
	v_mfma_f32_16x16x32_bf16 v[38:41], v[242:245], v[230:233], v[38:41]
	v_mfma_f32_16x16x32_bf16 v[34:37], v[246:249], v[230:233], v[34:37]
	s_setprio 0
	s_waitcnt vmcnt(7)
	ds_write_b128 v171, v[14:17] offset:32768
	s_waitcnt vmcnt(6)
	ds_write_b128 v171, v[2:5] offset:40960
	s_waitcnt vmcnt(5)
	ds_write_b128 v171, v[6:9] offset:49152
	s_waitcnt vmcnt(4)
	ds_write_b128 v171, v[10:13] offset:57344
	s_add_u32 s58, s56, s0
	s_addc_u32 s59, s57, s1
	global_load_dwordx4 v[14:17], v185, s[58:59]
	s_nop 0
	global_load_dwordx4 v[2:5], v183, s[58:59]
	s_nop 0
	global_load_dwordx4 v[6:9], v181, s[58:59]
	s_nop 0
	global_load_dwordx4 v[10:13], v179, s[58:59]
	v_lshl_add_u32 v171, v205, 1, s2
	v_add_u32_e32 v173, v171, v195
	ds_read_b128 v[198:201], v173
	ds_read_b128 v[206:209], v173 offset:2048
	ds_read_b128 v[210:213], v173 offset:4096
	ds_read_b128 v[214:217], v173 offset:6144
	ds_read_b128 v[218:221], v173 offset:8192
	ds_read_b128 v[222:225], v173 offset:10240
	ds_read_b128 v[226:229], v173 offset:12288
	ds_read_b128 v[230:233], v173 offset:14336
	v_add_u32_e32 v171, v171, v194
	ds_read_b128 v[234:237], v171 offset:32768
	ds_read_b128 v[238:241], v171 offset:34816
	ds_read_b128 v[242:245], v171 offset:36864
	ds_read_b128 v[246:249], v171 offset:38912
	s_cmp_lg_u32 s101, 0
	s_cbranch_scc1 .Lstg_830_b
; DI f32x4 mfma16(bf16x8 a, bf16x8 b, f32x4 c) { return __builtin_amdgcn_mfma_f32_16x16x32_bf16(a, b, c, 0, 0, 0); }
;     ...
; #pragma unroll
;     for (int j = 0; j < 4; ++j) {
;       const int r = wn * 64 + j * 16 + (lane & 15);
;       bfr[j] = *(const bf16x8*)(S + 16384 + r * 64 + (((ks * 4 + (lane >> 4)) ^ ((r >> 1) & 7)) << 3));
;     }
;     __builtin_amdgcn_s_setprio(1);
; #pragma unroll
;     for (int i = 0; i < 8; ++i)
; #pragma unroll
;       for (int j = 0; j < 4; ++j) acc[i][j] = mfma16(bfr[j], af[i], acc[i][j]);
;     __builtin_amdgcn_s_setprio(0);
	s_setprio 1
	s_waitcnt lgkmcnt(3)
	v_mfma_f32_16x16x32_bf16 v[158:161], v[234:237], v[198:201], v[158:161]
	s_waitcnt lgkmcnt(2)
	v_mfma_f32_16x16x32_bf16 v[154:157], v[238:241], v[198:201], v[154:157]
	s_waitcnt lgkmcnt(1)
	v_mfma_f32_16x16x32_bf16 v[150:153], v[242:245], v[198:201], v[150:153]
	s_waitcnt lgkmcnt(0)
	v_mfma_f32_16x16x32_bf16 v[146:149], v[246:249], v[198:201], v[146:149]
	v_mfma_f32_16x16x32_bf16 v[142:145], v[234:237], v[206:209], v[142:145]
	v_mfma_f32_16x16x32_bf16 v[138:141], v[238:241], v[206:209], v[138:141]
	v_mfma_f32_16x16x32_bf16 v[134:137], v[242:245], v[206:209], v[134:137]
	v_mfma_f32_16x16x32_bf16 v[130:133], v[246:249], v[206:209], v[130:133]
	v_mfma_f32_16x16x32_bf16 v[126:129], v[234:237], v[210:213], v[126:129]
	v_mfma_f32_16x16x32_bf16 v[122:125], v[238:241], v[210:213], v[122:125]
	v_mfma_f32_16x16x32_bf16 v[118:121], v[242:245], v[210:213], v[118:121]
	v_mfma_f32_16x16x32_bf16 v[114:117], v[246:249], v[210:213], v[114:117]
	v_mfma_f32_16x16x32_bf16 v[110:113], v[234:237], v[214:217], v[110:113]
	v_mfma_f32_16x16x32_bf16 v[106:109], v[238:241], v[214:217], v[106:109]
	v_mfma_f32_16x16x32_bf16 v[102:105], v[242:245], v[214:217], v[102:105]
	v_mfma_f32_16x16x32_bf16 v[98:101], v[246:249], v[214:217], v[98:101]
	v_mfma_f32_16x16x32_bf16 v[94:97], v[234:237], v[218:221], v[94:97]
	v_mfma_f32_16x16x32_bf16 v[90:93], v[238:241], v[218:221], v[90:93]
	v_mfma_f32_16x16x32_bf16 v[86:89], v[242:245], v[218:221], v[86:89]
	v_mfma_f32_16x16x32_bf16 v[82:85], v[246:249], v[218:221], v[82:85]
	v_mfma_f32_16x16x32_bf16 v[78:81], v[234:237], v[222:225], v[78:81]
	v_mfma_f32_16x16x32_bf16 v[74:77], v[238:241], v[222:225], v[74:77]
	v_mfma_f32_16x16x32_bf16 v[70:73], v[242:245], v[222:225], v[70:73]
	v_mfma_f32_16x16x32_bf16 v[66:69], v[246:249], v[222:225], v[66:69]
	v_mfma_f32_16x16x32_bf16 v[62:65], v[234:237], v[226:229], v[62:65]
	v_mfma_f32_16x16x32_bf16 v[58:61], v[238:241], v[226:229], v[58:61]
	v_mfma_f32_16x16x32_bf16 v[54:57], v[242:245], v[226:229], v[54:57]
	v_mfma_f32_16x16x32_bf16 v[50:53], v[246:249], v[226:229], v[50:53]
	v_mfma_f32_16x16x32_bf16 v[46:49], v[234:237], v[230:233], v[46:49]
	v_mfma_f32_16x16x32_bf16 v[42:45], v[238:241], v[230:233], v[42:45]
	v_mfma_f32_16x16x32_bf16 v[38:41], v[242:245], v[230:233], v[38:41]
	v_mfma_f32_16x16x32_bf16 v[34:37], v[246:249], v[230:233], v[34:37]
	s_setprio 0

; DI int TID8() { int t = threadIdx.x; asm volatile("" : "+v"(t)); return t; }
; DI void gemm8_accum(f32x4 (&acc)[8][4], const bf16_t* a, size_t lda, const bf16_t* b, size_t ldb, int nkb, bf16_t* L,
;                     const bool pre, const bf16_t* an, size_t ldan, const bf16_t* bn, size_t ldbn) {
;   const int tid = TID8(), lane = tid & 63, w = tid >> 6;
;   const int wm = w >> 2, wn = w & 3;
;   const int lrow = tid >> 3, lch = tid & 7;
;   u32x4 ra[4], rb[4];
;   unsigned offa[4], offb[4];
; #pragma unroll
;   for (int i = 0; i < 4; ++i) {
;     offa[i] = (unsigned)(lrow + 64 * i) * (unsigned)lda + (unsigned)(lch * 8);
;     offb[i] = (unsigned)(lrow + 64 * i) * (unsigned)ldb + (unsigned)(lch * 8);
;   }
;   if (!pre) {
;     g8_load1o(ra, a, offa);
;     g8_load1o(rb, b, offb);
;     __syncthreads();
;     g8_store(L, ra, rb, lrow, lch);
;   }
;   g8_load1o(ra, a + 64, offa);
;   g8_load1o(rb, b + 64, offb);
; DI void zero_acc8(f32x4 (&acc)[8][4]) {
; #pragma unroll
;   for (int i = 0; i < 8; ++i)
; #pragma unroll
;     for (int j = 0; j < 4; ++j) acc[i][j] = f32x4{0.f, 0.f, 0.f, 0.f};
; }
.LBB0_891:
	v_lshlrev_b64 v[40:41], 1, v[168:169]
	v_lshl_add_u64 v[6:7], s[2:3], 0, v[40:41]
	v_lshlrev_b64 v[42:43], 1, v[166:167]
	v_lshlrev_b64 v[44:45], 1, v[0:1]
	v_lshl_add_u64 v[8:9], s[2:3], 0, v[42:43]
	global_load_dwordx4 v[18:21], v[6:7], off offset:128
	global_load_dwordx4 v[26:29], v[8:9], off offset:128
	v_lshl_add_u64 v[6:7], s[2:3], 0, v[44:45]
	global_load_dwordx4 v[22:25], v[4:5], off offset:128
	global_load_dwordx4 v[30:33], v[6:7], off offset:128
	global_load_dwordx4 v[14:17], v[2:3], off offset:128
	v_lshl_add_u64 v[2:3], s[0:1], 0, v[40:41]
	s_nop 1
	global_load_dwordx4 v[2:5], v[2:3], off offset:128
	v_lshl_add_u64 v[6:7], s[0:1], 0, v[42:43]
	v_lshl_add_u64 v[10:11], s[0:1], 0, v[44:45]
	global_load_dwordx4 v[6:9], v[6:7], off offset:128
	s_nop 0
	global_load_dwordx4 v[10:13], v[10:11], off offset:128
	v_bfe_u32 v39, v36, 4, 2
	v_lshrrev_b32_e32 v46, 1, v36
	v_readlane_b32 s7, v252, 25
	v_bitop3_b32 v46, v46, v39, 7 bitop3:0x6c
	s_or_b32 s7, s7, s12
	s_and_b32 s12, s9, 3
	v_lshlrev_b32_e32 v191, 3, v46
	v_lshlrev_b32_e32 v46, 5, v36
	s_lshl_b32 s6, s10, 11
	s_add_i32 s7, s7, s12
	v_bfe_u32 v47, v36, 1, 3
	v_and_b32_e32 v46, 0xffffe000, v46
	v_lshlrev_b32_e32 v36, 6, v36
	s_movk_i32 s0, 0x3c0
	s_and_b32 s6, s6, 0x780000
	s_lshl_b32 s7, s7, 19
	v_and_or_b32 v46, v36, s0, v46
	v_readlane_b32 s0, v254, 28
	s_add_u32 s0, s0, s6
	v_readlane_b32 s1, v254, 29
	v_add_u32_e32 v34, v35, v34
	v_mov_b32_e32 v35, v1
	s_addc_u32 s1, s1, 0
	v_lshlrev_b64 v[34:35], 1, v[34:35]
	v_lshl_add_u64 v[170:171], s[0:1], 0, v[44:45]
	v_lshl_add_u64 v[172:173], s[0:1], 0, v[42:43]
	v_lshl_add_u64 v[174:175], s[0:1], 0, v[40:41]
	v_lshl_add_u64 v[176:177], s[0:1], 0, v[34:35]
	v_readlane_b32 s0, v253, 57
	s_add_u32 s0, s0, s7
	v_readlane_b32 s1, v253, 58
	s_addc_u32 s1, s1, 0
	v_and_b32_e32 v36, 0x33c0, v36
	v_bitop3_b32 v39, v39, v47, 4 bitop3:0x36
	v_lshlrev_b32_e32 v189, 1, v38
	v_lshlrev_b32_e32 v190, 1, v37
	v_lshl_add_u64 v[184:185], s[0:1], 0, v[34:35]
	v_mov_b32_e32 v34, 0
	v_lshlrev_b32_e32 v188, 3, v39
	v_add3_u32 v163, 0, v189, v190
	v_lshl_add_u64 v[178:179], s[0:1], 0, v[44:45]
	v_lshl_add_u64 v[180:181], s[0:1], 0, v[42:43]
	v_lshl_add_u64 v[182:183], s[0:1], 0, v[40:41]
	s_mov_b64 s[0:1], 0
	s_mov_b32 s2, 0
	v_lshlrev_b32_e32 v187, 1, v46
	v_lshlrev_b32_e32 v186, 1, v36
	v_mov_b32_e32 v35, v34
	v_mov_b32_e32 v36, v34
	v_mov_b32_e32 v37, v34
	v_mov_b32_e32 v38, v34
	v_mov_b32_e32 v39, v34
	v_mov_b32_e32 v40, v34
	v_mov_b32_e32 v41, v34
	v_mov_b32_e32 v42, v34
	v_mov_b32_e32 v43, v34
	v_mov_b32_e32 v44, v34
	v_mov_b32_e32 v45, v34
	v_mov_b32_e32 v46, v34
	v_mov_b32_e32 v47, v34
	v_mov_b32_e32 v48, v34
	v_mov_b32_e32 v49, v34
	v_mov_b32_e32 v50, v34
	v_mov_b32_e32 v51, v34
	v_mov_b32_e32 v52, v34
	v_mov_b32_e32 v53, v34
	v_mov_b32_e32 v54, v34
	v_mov_b32_e32 v55, v34
	v_mov_b32_e32 v56, v34
	v_mov_b32_e32 v57, v34
	v_mov_b32_e32 v58, v34
	v_mov_b32_e32 v59, v34
	v_mov_b32_e32 v60, v34
	v_mov_b32_e32 v61, v34
	v_mov_b32_e32 v62, v34
	v_mov_b32_e32 v63, v34
	v_mov_b32_e32 v64, v34
	v_mov_b32_e32 v65, v34
	v_mov_b32_e32 v66, v34
	v_mov_b32_e32 v67, v34
	v_mov_b32_e32 v68, v34
	v_mov_b32_e32 v69, v34
	v_mov_b32_e32 v70, v34
	v_mov_b32_e32 v71, v34
	v_mov_b32_e32 v72, v34
	v_mov_b32_e32 v73, v34
	v_mov_b32_e32 v74, v34
	v_mov_b32_e32 v75, v34
	v_mov_b32_e32 v76, v34
	v_mov_b32_e32 v77, v34
	v_mov_b32_e32 v78, v34
	v_mov_b32_e32 v79, v34
	v_mov_b32_e32 v80, v34
	v_mov_b32_e32 v81, v34
	v_mov_b32_e32 v82, v34
	v_mov_b32_e32 v83, v34
	v_mov_b32_e32 v84, v34
	v_mov_b32_e32 v85, v34
	v_mov_b32_e32 v86, v34
	v_mov_b32_e32 v87, v34
	v_mov_b32_e32 v88, v34
	v_mov_b32_e32 v89, v34
	v_mov_b32_e32 v90, v34
	v_mov_b32_e32 v91, v34
	v_mov_b32_e32 v92, v34
	v_mov_b32_e32 v93, v34
	v_mov_b32_e32 v94, v34
	v_mov_b32_e32 v95, v34
	v_mov_b32_e32 v96, v34
	v_mov_b32_e32 v97, v34
	v_mov_b32_e32 v98, v34
	v_mov_b32_e32 v99, v34
	v_mov_b32_e32 v100, v34
	v_mov_b32_e32 v101, v34
	v_mov_b32_e32 v102, v34
	v_mov_b32_e32 v103, v34
	v_mov_b32_e32 v104, v34
	v_mov_b32_e32 v105, v34
	v_mov_b32_e32 v106, v34
	v_mov_b32_e32 v107, v34
	v_mov_b32_e32 v108, v34
	v_mov_b32_e32 v109, v34
	v_mov_b32_e32 v110, v34
	v_mov_b32_e32 v111, v34
	v_mov_b32_e32 v112, v34
	v_mov_b32_e32 v113, v34
	v_mov_b32_e32 v114, v34
	v_mov_b32_e32 v115, v34
	v_mov_b32_e32 v116, v34
	v_mov_b32_e32 v117, v34
	v_mov_b32_e32 v118, v34
	v_mov_b32_e32 v119, v34
	v_mov_b32_e32 v120, v34
	v_mov_b32_e32 v121, v34
	v_mov_b32_e32 v122, v34
	v_mov_b32_e32 v123, v34
	v_mov_b32_e32 v124, v34
	v_mov_b32_e32 v125, v34
	v_mov_b32_e32 v126, v34
	v_mov_b32_e32 v127, v34
	v_mov_b32_e32 v128, v34
	v_mov_b32_e32 v129, v34
	v_mov_b32_e32 v130, v34
	v_mov_b32_e32 v131, v34
	v_mov_b32_e32 v132, v34
	v_mov_b32_e32 v133, v34
	v_mov_b32_e32 v134, v34
	v_mov_b32_e32 v135, v34
	v_mov_b32_e32 v136, v34
	v_mov_b32_e32 v137, v34
	v_mov_b32_e32 v138, v34
	v_mov_b32_e32 v139, v34
	v_mov_b32_e32 v140, v34
	v_mov_b32_e32 v141, v34
	v_mov_b32_e32 v142, v34
	v_mov_b32_e32 v143, v34
	v_mov_b32_e32 v144, v34
	v_mov_b32_e32 v145, v34
	v_mov_b32_e32 v146, v34
	v_mov_b32_e32 v147, v34
	v_mov_b32_e32 v148, v34
	v_mov_b32_e32 v149, v34
	v_mov_b32_e32 v150, v34
	v_mov_b32_e32 v151, v34
	v_mov_b32_e32 v152, v34
	v_mov_b32_e32 v153, v34
	v_mov_b32_e32 v154, v34
	v_mov_b32_e32 v155, v34
	v_mov_b32_e32 v156, v34
	v_mov_b32_e32 v157, v34
	v_mov_b32_e32 v158, v34
	v_mov_b32_e32 v159, v34
	v_mov_b32_e32 v160, v34
	v_mov_b32_e32 v161, v34
	v_readfirstlane_b32 s52, v184
	v_readfirstlane_b32 s53, v185
	s_sub_u32 s52, s52, 0x40000000
	s_subb_u32 s53, s53, 0
	v_readfirstlane_b32 s56, v176
	v_readfirstlane_b32 s57, v177
	s_sub_u32 s56, s56, 0x40000000
	s_subb_u32 s57, s57, 0
	v_subrev_u32_e32 v185, s52, v184
	v_subrev_u32_e32 v181, s52, v180
	v_subrev_u32_e32 v179, s52, v178
	v_subrev_u32_e32 v183, s52, v182
	v_subrev_u32_e32 v177, s56, v176
	v_subrev_u32_e32 v175, s56, v174
	v_subrev_u32_e32 v173, s56, v172
	v_subrev_u32_e32 v171, s56, v170

; DI f32x4 mfma16(bf16x8 a, bf16x8 b, f32x4 c) { return __builtin_amdgcn_mfma_f32_16x16x32_bf16(a, b, c, 0, 0, 0); }
; #pragma unroll
;   for (int ks = KS0; ks < KS1; ++ks) {
;     bf16x8 af[8], bfr[4];
; #pragma unroll
;     for (int i = 0; i < 8; ++i) {
;       const int r = wm * 128 + i * 16 + (lane & 15);
;       af[i] = *(const bf16x8*)(S + r * 64 + (((ks * 4 + (lane >> 4)) ^ ((r >> 1) & 7)) << 3));
;     }
; #pragma unroll
;     for (int j = 0; j < 4; ++j) {
;       const int r = wn * 64 + j * 16 + (lane & 15);
;       bfr[j] = *(const bf16x8*)(S + 16384 + r * 64 + (((ks * 4 + (lane >> 4)) ^ ((r >> 1) & 7)) << 3));
;     }
;     __builtin_amdgcn_s_setprio(1);
; #pragma unroll
;     for (int i = 0; i < 8; ++i)
; #pragma unroll
;       for (int j = 0; j < 4; ++j) acc[i][j] = mfma16(bfr[j], af[i], acc[i][j]);
;     __builtin_amdgcn_s_setprio(0);
;   }
; }
; DI void gemm8_accum(f32x4 (&acc)[8][4], const bf16_t* a, size_t lda, const bf16_t* b, size_t ldb, int nkb, bf16_t* L,
;                     const bool pre, const bf16_t* an, size_t ldan, const bf16_t* bn, size_t ldbn) {
;     ...
;   for (int kb = 0; kb + 2 < nkb; ++kb) {
;     __syncthreads();
;     g8_store1(L + ((kb + 1) & 1) * 32768, ra, lrow, lch);
;     g8_load1o(ra, a + (kb + 2) * 64, offa);
;     __builtin_amdgcn_sched_barrier(0);
;     g8_compute<0, 1>(acc, L + (kb & 1) * 32768, wm, wn, lane);
;     __builtin_amdgcn_sched_barrier(0);
;     g8_store1(L + ((kb + 1) & 1) * 32768 + 16384, rb, lrow, lch);
;     g8_load1o(rb, b + (kb + 2) * 64, offb);
;     __builtin_amdgcn_sched_barrier(0);
;     g8_compute<1, 2>(acc, L + (kb & 1) * 32768, wm, wn, lane);
;   }
.Lstg_892_a:
	s_waitcnt vmcnt(5)
	ds_write_b128 v167, v[22:25]
	ds_write_b128 v167, v[18:21] offset:8192
	ds_write_b128 v167, v[26:29] offset:16384
	s_waitcnt vmcnt(4)
	ds_write_b128 v167, v[30:33] offset:24576
	s_add_u32 s54, s52, s0
	s_addc_u32 s55, s53, s1
	global_load_dwordx4 v[22:25], v185, s[54:55]
	global_load_dwordx4 v[26:29], v181, s[54:55]
	global_load_dwordx4 v[18:21], v183, s[54:55]
	s_nop 0
	global_load_dwordx4 v[30:33], v179, s[54:55]
	s_and_b32 s2, s2, 0x8000
	s_lshl_b32 s2, s2, 1
	s_add_i32 s2, s2, 0
	v_lshl_add_u32 v169, v191, 1, s2
	v_add_u32_e32 v202, v169, v187
	ds_read_b128 v[192:195], v202
	ds_read_b128 v[198:201], v202 offset:2048
	ds_read_b128 v[206:209], v202 offset:4096
	ds_read_b128 v[210:213], v202 offset:6144
	ds_read_b128 v[214:217], v202 offset:8192
	ds_read_b128 v[218:221], v202 offset:10240
	ds_read_b128 v[222:225], v202 offset:12288
	ds_read_b128 v[226:229], v202 offset:14336
	v_add_u32_e32 v169, v169, v186
	ds_read_b128 v[230:233], v169 offset:32768
	ds_read_b128 v[234:237], v169 offset:34816
	ds_read_b128 v[238:241], v169 offset:36864
	ds_read_b128 v[242:245], v169 offset:38912
	s_setprio 1
	s_waitcnt lgkmcnt(3)
	v_mfma_f32_16x16x32_bf16 v[158:161], v[230:233], v[192:195], v[158:161]
	s_waitcnt lgkmcnt(2)
	v_mfma_f32_16x16x32_bf16 v[154:157], v[234:237], v[192:195], v[154:157]
	s_waitcnt lgkmcnt(1)
	v_mfma_f32_16x16x32_bf16 v[150:153], v[238:241], v[192:195], v[150:153]
	s_waitcnt lgkmcnt(0)
	v_mfma_f32_16x16x32_bf16 v[146:149], v[242:245], v[192:195], v[146:149]
	v_mfma_f32_16x16x32_bf16 v[142:145], v[230:233], v[198:201], v[142:145]
	v_mfma_f32_16x16x32_bf16 v[138:141], v[234:237], v[198:201], v[138:141]
	v_mfma_f32_16x16x32_bf16 v[134:137], v[238:241], v[198:201], v[134:137]
	v_mfma_f32_16x16x32_bf16 v[130:133], v[242:245], v[198:201], v[130:133]
	v_mfma_f32_16x16x32_bf16 v[126:129], v[230:233], v[206:209], v[126:129]
	v_mfma_f32_16x16x32_bf16 v[122:125], v[234:237], v[206:209], v[122:125]
	v_mfma_f32_16x16x32_bf16 v[118:121], v[238:241], v[206:209], v[118:121]
	v_mfma_f32_16x16x32_bf16 v[114:117], v[242:245], v[206:209], v[114:117]
	v_mfma_f32_16x16x32_bf16 v[110:113], v[230:233], v[210:213], v[110:113]
	v_mfma_f32_16x16x32_bf16 v[106:109], v[234:237], v[210:213], v[106:109]
	v_mfma_f32_16x16x32_bf16 v[102:105], v[238:241], v[210:213], v[102:105]
	v_mfma_f32_16x16x32_bf16 v[98:101], v[242:245], v[210:213], v[98:101]
	v_mfma_f32_16x16x32_bf16 v[94:97], v[230:233], v[214:217], v[94:97]
	v_mfma_f32_16x16x32_bf16 v[90:93], v[234:237], v[214:217], v[90:93]
	v_mfma_f32_16x16x32_bf16 v[86:89], v[238:241], v[214:217], v[86:89]
	v_mfma_f32_16x16x32_bf16 v[82:85], v[242:245], v[214:217], v[82:85]
	v_mfma_f32_16x16x32_bf16 v[78:81], v[230:233], v[218:221], v[78:81]
	v_mfma_f32_16x16x32_bf16 v[74:77], v[234:237], v[218:221], v[74:77]
	v_mfma_f32_16x16x32_bf16 v[70:73], v[238:241], v[218:221], v[70:73]
	v_mfma_f32_16x16x32_bf16 v[66:69], v[242:245], v[218:221], v[66:69]
	v_mfma_f32_16x16x32_bf16 v[62:65], v[230:233], v[222:225], v[62:65]
	v_mfma_f32_16x16x32_bf16 v[58:61], v[234:237], v[222:225], v[58:61]
	v_mfma_f32_16x16x32_bf16 v[54:57], v[238:241], v[222:225], v[54:57]
	v_mfma_f32_16x16x32_bf16 v[50:53], v[242:245], v[222:225], v[50:53]
	v_mfma_f32_16x16x32_bf16 v[46:49], v[230:233], v[226:229], v[46:49]
	v_mfma_f32_16x16x32_bf16 v[42:45], v[234:237], v[226:229], v[42:45]
	v_mfma_f32_16x16x32_bf16 v[38:41], v[238:241], v[226:229], v[38:41]
	v_mfma_f32_16x16x32_bf16 v[34:37], v[242:245], v[226:229], v[34:37]
	s_setprio 0
	s_waitcnt vmcnt(7)
	ds_write_b128 v167, v[14:17] offset:32768
	s_waitcnt vmcnt(6)
	ds_write_b128 v167, v[2:5] offset:40960
	s_waitcnt vmcnt(5)
	ds_write_b128 v167, v[6:9] offset:49152
	s_waitcnt vmcnt(4)
	ds_write_b128 v167, v[10:13] offset:57344
	s_add_u32 s58, s56, s0
	s_addc_u32 s59, s57, s1
	global_load_dwordx4 v[14:17], v177, s[58:59]
	s_nop 0
	global_load_dwordx4 v[2:5], v175, s[58:59]
	s_nop 0
	global_load_dwordx4 v[6:9], v173, s[58:59]
	s_nop 0
	global_load_dwordx4 v[10:13], v171, s[58:59]
	v_lshl_add_u32 v167, v188, 1, s2
	v_add_u32_e32 v169, v167, v187
	ds_read_b128 v[192:195], v169
	ds_read_b128 v[198:201], v169 offset:2048
	ds_read_b128 v[206:209], v169 offset:4096
	ds_read_b128 v[210:213], v169 offset:6144
	ds_read_b128 v[214:217], v169 offset:8192
	ds_read_b128 v[218:221], v169 offset:10240
	ds_read_b128 v[222:225], v169 offset:12288
	ds_read_b128 v[226:229], v169 offset:14336
	v_add_u32_e32 v167, v167, v186
	ds_read_b128 v[230:233], v167 offset:32768
	ds_read_b128 v[234:237], v167 offset:34816
	ds_read_b128 v[238:241], v167 offset:36864
	ds_read_b128 v[242:245], v167 offset:38912
	s_cmp_lg_u32 s101, 0
	s_cbranch_scc1 .Lstg_892_b
; DI f32x4 mfma16(bf16x8 a, bf16x8 b, f32x4 c) { return __builtin_amdgcn_mfma_f32_16x16x32_bf16(a, b, c, 0, 0, 0); }
;     ...
; #pragma unroll
;     for (int j = 0; j < 4; ++j) {
;       const int r = wn * 64 + j * 16 + (lane & 15);
;       bfr[j] = *(const bf16x8*)(S + 16384 + r * 64 + (((ks * 4 + (lane >> 4)) ^ ((r >> 1) & 7)) << 3));
;     }
;     __builtin_amdgcn_s_setprio(1);
; #pragma unroll
;     for (int i = 0; i < 8; ++i)
; #pragma unroll
;       for (int j = 0; j < 4; ++j) acc[i][j] = mfma16(bfr[j], af[i], acc[i][j]);
;     __builtin_amdgcn_s_setprio(0);
	s_setprio 1
	s_waitcnt lgkmcnt(3)
	v_mfma_f32_16x16x32_bf16 v[158:161], v[230:233], v[192:195], v[158:161]
	s_waitcnt lgkmcnt(2)
	v_mfma_f32_16x16x32_bf16 v[154:157], v[234:237], v[192:195], v[154:157]
	s_waitcnt lgkmcnt(1)
	v_mfma_f32_16x16x32_bf16 v[150:153], v[238:241], v[192:195], v[150:153]
	s_waitcnt lgkmcnt(0)
	v_mfma_f32_16x16x32_bf16 v[146:149], v[242:245], v[192:195], v[146:149]
	v_mfma_f32_16x16x32_bf16 v[142:145], v[230:233], v[198:201], v[142:145]
	v_mfma_f32_16x16x32_bf16 v[138:141], v[234:237], v[198:201], v[138:141]
	v_mfma_f32_16x16x32_bf16 v[134:137], v[238:241], v[198:201], v[134:137]
	v_mfma_f32_16x16x32_bf16 v[130:133], v[242:245], v[198:201], v[130:133]
	v_mfma_f32_16x16x32_bf16 v[126:129], v[230:233], v[206:209], v[126:129]
	v_mfma_f32_16x16x32_bf16 v[122:125], v[234:237], v[206:209], v[122:125]
	v_mfma_f32_16x16x32_bf16 v[118:121], v[238:241], v[206:209], v[118:121]
	v_mfma_f32_16x16x32_bf16 v[114:117], v[242:245], v[206:209], v[114:117]
	v_mfma_f32_16x16x32_bf16 v[110:113], v[230:233], v[210:213], v[110:113]
	v_mfma_f32_16x16x32_bf16 v[106:109], v[234:237], v[210:213], v[106:109]
	v_mfma_f32_16x16x32_bf16 v[102:105], v[238:241], v[210:213], v[102:105]
	v_mfma_f32_16x16x32_bf16 v[98:101], v[242:245], v[210:213], v[98:101]
	v_mfma_f32_16x16x32_bf16 v[94:97], v[230:233], v[214:217], v[94:97]
	v_mfma_f32_16x16x32_bf16 v[90:93], v[234:237], v[214:217], v[90:93]
	v_mfma_f32_16x16x32_bf16 v[86:89], v[238:241], v[214:217], v[86:89]
	v_mfma_f32_16x16x32_bf16 v[82:85], v[242:245], v[214:217], v[82:85]
	v_mfma_f32_16x16x32_bf16 v[78:81], v[230:233], v[218:221], v[78:81]
	v_mfma_f32_16x16x32_bf16 v[74:77], v[234:237], v[218:221], v[74:77]
	v_mfma_f32_16x16x32_bf16 v[70:73], v[238:241], v[218:221], v[70:73]
	v_mfma_f32_16x16x32_bf16 v[66:69], v[242:245], v[218:221], v[66:69]
	v_mfma_f32_16x16x32_bf16 v[62:65], v[230:233], v[222:225], v[62:65]
	v_mfma_f32_16x16x32_bf16 v[58:61], v[234:237], v[222:225], v[58:61]
	v_mfma_f32_16x16x32_bf16 v[54:57], v[238:241], v[222:225], v[54:57]
	v_mfma_f32_16x16x32_bf16 v[50:53], v[242:245], v[222:225], v[50:53]
	v_mfma_f32_16x16x32_bf16 v[46:49], v[230:233], v[226:229], v[46:49]
	v_mfma_f32_16x16x32_bf16 v[42:45], v[234:237], v[226:229], v[42:45]
	v_mfma_f32_16x16x32_bf16 v[38:41], v[238:241], v[226:229], v[38:41]
	v_mfma_f32_16x16x32_bf16 v[34:37], v[242:245], v[226:229], v[34:37]
	s_setprio 0

; DI int TID8() { int t = threadIdx.x; asm volatile("" : "+v"(t)); return t; }
; DI void gemm8_accum(f32x4 (&acc)[8][4], const bf16_t* a, size_t lda, const bf16_t* b, size_t ldb, int nkb, bf16_t* L,
;                     const bool pre, const bf16_t* an, size_t ldan, const bf16_t* bn, size_t ldbn) {
;   const int tid = TID8(), lane = tid & 63, w = tid >> 6;
;   const int wm = w >> 2, wn = w & 3;
;   const int lrow = tid >> 3, lch = tid & 7;
;   u32x4 ra[4], rb[4];
;   unsigned offa[4], offb[4];
; #pragma unroll
;   for (int i = 0; i < 4; ++i) {
;     offa[i] = (unsigned)(lrow + 64 * i) * (unsigned)lda + (unsigned)(lch * 8);
;     offb[i] = (unsigned)(lrow + 64 * i) * (unsigned)ldb + (unsigned)(lch * 8);
;   }
;   if (!pre) {
;     g8_load1o(ra, a, offa);
;     g8_load1o(rb, b, offb);
;     __syncthreads();
;     g8_store(L, ra, rb, lrow, lch);
;   }
;   g8_load1o(ra, a + 64, offa);
;   g8_load1o(rb, b + 64, offb);
; DI void zero_acc8(f32x4 (&acc)[8][4]) {
; #pragma unroll
;   for (int i = 0; i < 8; ++i)
; #pragma unroll
;     for (int j = 0; j < 4; ++j) acc[i][j] = f32x4{0.f, 0.f, 0.f, 0.f};
; }
.LBB0_941:
	v_lshlrev_b64 v[40:41], 1, v[168:169]
	v_lshl_add_u64 v[6:7], s[2:3], 0, v[40:41]
	v_lshlrev_b64 v[42:43], 1, v[166:167]
	v_lshlrev_b64 v[44:45], 1, v[0:1]
	v_lshl_add_u64 v[8:9], s[2:3], 0, v[42:43]
	global_load_dwordx4 v[18:21], v[6:7], off offset:128
	global_load_dwordx4 v[26:29], v[8:9], off offset:128
	v_lshl_add_u64 v[6:7], s[2:3], 0, v[44:45]
	global_load_dwordx4 v[22:25], v[4:5], off offset:128
	global_load_dwordx4 v[30:33], v[6:7], off offset:128
	global_load_dwordx4 v[14:17], v[2:3], off offset:128
	v_lshl_add_u64 v[2:3], s[0:1], 0, v[40:41]
	s_nop 1
	global_load_dwordx4 v[2:5], v[2:3], off offset:128
	v_lshl_add_u64 v[6:7], s[0:1], 0, v[42:43]
	v_lshl_add_u64 v[10:11], s[0:1], 0, v[44:45]
	global_load_dwordx4 v[6:9], v[6:7], off offset:128
	s_nop 0
	global_load_dwordx4 v[10:13], v[10:11], off offset:128
	v_bfe_u32 v39, v36, 4, 2
	v_lshrrev_b32_e32 v46, 1, v36
	s_lshl_b32 s6, s12, 8
	s_and_b32 s12, s10, 0x60
	v_readlane_b32 s20, v252, 25
	v_bitop3_b32 v46, v46, v39, 7 bitop3:0x6c
	s_lshr_b32 s7, s13, 2
	s_or_b32 s12, s20, s12
	s_and_b32 s20, s9, 3
	v_lshlrev_b32_e32 v191, 3, v46
	v_lshlrev_b32_e32 v46, 5, v36
	s_and_b32 s7, s7, 3
	s_add_i32 s12, s12, s20
	v_bfe_u32 v47, v36, 1, 3
	v_and_b32_e32 v46, 0xffffe000, v46
	v_lshlrev_b32_e32 v36, 6, v36
	s_movk_i32 s0, 0x3c0
	s_lshl_b32 s7, s7, 21
	s_lshl_b32 s12, s12, 21
	v_and_or_b32 v46, v36, s0, v46
	v_readlane_b32 s0, v254, 30
	s_add_u32 s0, s0, s7
	v_readlane_b32 s1, v254, 31
	v_add_u32_e32 v34, v35, v34
	v_mov_b32_e32 v35, v1
	s_addc_u32 s1, s1, 0
	v_lshlrev_b64 v[34:35], 1, v[34:35]
	v_lshl_add_u64 v[170:171], s[0:1], 0, v[44:45]
	v_lshl_add_u64 v[172:173], s[0:1], 0, v[42:43]
	v_lshl_add_u64 v[174:175], s[0:1], 0, v[40:41]
	v_lshl_add_u64 v[176:177], s[0:1], 0, v[34:35]
	v_readlane_b32 s0, v254, 32
	s_add_u32 s0, s0, s12
	v_readlane_b32 s1, v254, 33
	s_addc_u32 s1, s1, 0
	v_and_b32_e32 v36, 0x33c0, v36
	v_bitop3_b32 v39, v39, v47, 4 bitop3:0x36
	v_lshlrev_b32_e32 v189, 1, v38
	v_lshlrev_b32_e32 v190, 1, v37
	v_lshl_add_u64 v[184:185], s[0:1], 0, v[34:35]
	v_mov_b32_e32 v34, 0
	v_lshlrev_b32_e32 v188, 3, v39
	v_add3_u32 v163, 0, v189, v190
	v_lshl_add_u64 v[178:179], s[0:1], 0, v[44:45]
	v_lshl_add_u64 v[180:181], s[0:1], 0, v[42:43]
	v_lshl_add_u64 v[182:183], s[0:1], 0, v[40:41]
	s_mov_b64 s[0:1], 0
	s_mov_b32 s2, 0
	v_lshlrev_b32_e32 v187, 1, v46
	v_lshlrev_b32_e32 v186, 1, v36
	v_mov_b32_e32 v35, v34
	v_mov_b32_e32 v36, v34
	v_mov_b32_e32 v37, v34
	v_mov_b32_e32 v38, v34
	v_mov_b32_e32 v39, v34
	v_mov_b32_e32 v40, v34
	v_mov_b32_e32 v41, v34
	v_mov_b32_e32 v42, v34
	v_mov_b32_e32 v43, v34
	v_mov_b32_e32 v44, v34
	v_mov_b32_e32 v45, v34
	v_mov_b32_e32 v46, v34
	v_mov_b32_e32 v47, v34
	v_mov_b32_e32 v48, v34
	v_mov_b32_e32 v49, v34
	v_mov_b32_e32 v50, v34
	v_mov_b32_e32 v51, v34
	v_mov_b32_e32 v52, v34
	v_mov_b32_e32 v53, v34
	v_mov_b32_e32 v54, v34
	v_mov_b32_e32 v55, v34
	v_mov_b32_e32 v56, v34
	v_mov_b32_e32 v57, v34
	v_mov_b32_e32 v58, v34
	v_mov_b32_e32 v59, v34
	v_mov_b32_e32 v60, v34
	v_mov_b32_e32 v61, v34
	v_mov_b32_e32 v62, v34
	v_mov_b32_e32 v63, v34
	v_mov_b32_e32 v64, v34
	v_mov_b32_e32 v65, v34
	v_mov_b32_e32 v66, v34
	v_mov_b32_e32 v67, v34
	v_mov_b32_e32 v68, v34
	v_mov_b32_e32 v69, v34
	v_mov_b32_e32 v70, v34
	v_mov_b32_e32 v71, v34
	v_mov_b32_e32 v72, v34
	v_mov_b32_e32 v73, v34
	v_mov_b32_e32 v74, v34
	v_mov_b32_e32 v75, v34
	v_mov_b32_e32 v76, v34
	v_mov_b32_e32 v77, v34
	v_mov_b32_e32 v78, v34
	v_mov_b32_e32 v79, v34
	v_mov_b32_e32 v80, v34
	v_mov_b32_e32 v81, v34
	v_mov_b32_e32 v82, v34
	v_mov_b32_e32 v83, v34
	v_mov_b32_e32 v84, v34
	v_mov_b32_e32 v85, v34
	v_mov_b32_e32 v86, v34
	v_mov_b32_e32 v87, v34
	v_mov_b32_e32 v88, v34
	v_mov_b32_e32 v89, v34
	v_mov_b32_e32 v90, v34
	v_mov_b32_e32 v91, v34
	v_mov_b32_e32 v92, v34
	v_mov_b32_e32 v93, v34
	v_mov_b32_e32 v94, v34
	v_mov_b32_e32 v95, v34
	v_mov_b32_e32 v96, v34
	v_mov_b32_e32 v97, v34
	v_mov_b32_e32 v98, v34
	v_mov_b32_e32 v99, v34
	v_mov_b32_e32 v100, v34
	v_mov_b32_e32 v101, v34
	v_mov_b32_e32 v102, v34
	v_mov_b32_e32 v103, v34
	v_mov_b32_e32 v104, v34
	v_mov_b32_e32 v105, v34
	v_mov_b32_e32 v106, v34
	v_mov_b32_e32 v107, v34
	v_mov_b32_e32 v108, v34
	v_mov_b32_e32 v109, v34
	v_mov_b32_e32 v110, v34
	v_mov_b32_e32 v111, v34
	v_mov_b32_e32 v112, v34
	v_mov_b32_e32 v113, v34
	v_mov_b32_e32 v114, v34
	v_mov_b32_e32 v115, v34
	v_mov_b32_e32 v116, v34
	v_mov_b32_e32 v117, v34
	v_mov_b32_e32 v118, v34
	v_mov_b32_e32 v119, v34
	v_mov_b32_e32 v120, v34
	v_mov_b32_e32 v121, v34
	v_mov_b32_e32 v122, v34
	v_mov_b32_e32 v123, v34
	v_mov_b32_e32 v124, v34
	v_mov_b32_e32 v125, v34
	v_mov_b32_e32 v126, v34
	v_mov_b32_e32 v127, v34
	v_mov_b32_e32 v128, v34
	v_mov_b32_e32 v129, v34
	v_mov_b32_e32 v130, v34
	v_mov_b32_e32 v131, v34
	v_mov_b32_e32 v132, v34
	v_mov_b32_e32 v133, v34
	v_mov_b32_e32 v134, v34
	v_mov_b32_e32 v135, v34
	v_mov_b32_e32 v136, v34
	v_mov_b32_e32 v137, v34
	v_mov_b32_e32 v138, v34
	v_mov_b32_e32 v139, v34
	v_mov_b32_e32 v140, v34
	v_mov_b32_e32 v141, v34
	v_mov_b32_e32 v142, v34
	v_mov_b32_e32 v143, v34
	v_mov_b32_e32 v144, v34
	v_mov_b32_e32 v145, v34
	v_mov_b32_e32 v146, v34
	v_mov_b32_e32 v147, v34
	v_mov_b32_e32 v148, v34
	v_mov_b32_e32 v149, v34
	v_mov_b32_e32 v150, v34
	v_mov_b32_e32 v151, v34
	v_mov_b32_e32 v152, v34
	v_mov_b32_e32 v153, v34
	v_mov_b32_e32 v154, v34
	v_mov_b32_e32 v155, v34
	v_mov_b32_e32 v156, v34
	v_mov_b32_e32 v157, v34
	v_mov_b32_e32 v158, v34
	v_mov_b32_e32 v159, v34
	v_mov_b32_e32 v160, v34
	v_mov_b32_e32 v161, v34
	v_readfirstlane_b32 s52, v184
	v_readfirstlane_b32 s53, v185
	s_sub_u32 s52, s52, 0x40000000
	s_subb_u32 s53, s53, 0
	v_readfirstlane_b32 s56, v176
	v_readfirstlane_b32 s57, v177
	s_sub_u32 s56, s56, 0x40000000
	s_subb_u32 s57, s57, 0
	v_subrev_u32_e32 v185, s52, v184
	v_subrev_u32_e32 v181, s52, v180
	v_subrev_u32_e32 v179, s52, v178
	v_subrev_u32_e32 v183, s52, v182
	v_subrev_u32_e32 v177, s56, v176
	v_subrev_u32_e32 v175, s56, v174
	v_subrev_u32_e32 v173, s56, v172
	v_subrev_u32_e32 v171, s56, v170

; DI f32x4 mfma16(bf16x8 a, bf16x8 b, f32x4 c) { return __builtin_amdgcn_mfma_f32_16x16x32_bf16(a, b, c, 0, 0, 0); }
; #pragma unroll
;   for (int ks = KS0; ks < KS1; ++ks) {
;     bf16x8 af[8], bfr[4];
; #pragma unroll
;     for (int i = 0; i < 8; ++i) {
;       const int r = wm * 128 + i * 16 + (lane & 15);
;       af[i] = *(const bf16x8*)(S + r * 64 + (((ks * 4 + (lane >> 4)) ^ ((r >> 1) & 7)) << 3));
;     }
; #pragma unroll
;     for (int j = 0; j < 4; ++j) {
;       const int r = wn * 64 + j * 16 + (lane & 15);
;       bfr[j] = *(const bf16x8*)(S + 16384 + r * 64 + (((ks * 4 + (lane >> 4)) ^ ((r >> 1) & 7)) << 3));
;     }
;     __builtin_amdgcn_s_setprio(1);
; #pragma unroll
;     for (int i = 0; i < 8; ++i)
; #pragma unroll
;       for (int j = 0; j < 4; ++j) acc[i][j] = mfma16(bfr[j], af[i], acc[i][j]);
;     __builtin_amdgcn_s_setprio(0);
;   }
; }
; DI void gemm8_accum(f32x4 (&acc)[8][4], const bf16_t* a, size_t lda, const bf16_t* b, size_t ldb, int nkb, bf16_t* L,
;                     const bool pre, const bf16_t* an, size_t ldan, const bf16_t* bn, size_t ldbn) {
;     ...
;   for (int kb = 0; kb + 2 < nkb; ++kb) {
;     __syncthreads();
;     g8_store1(L + ((kb + 1) & 1) * 32768, ra, lrow, lch);
;     g8_load1o(ra, a + (kb + 2) * 64, offa);
;     __builtin_amdgcn_sched_barrier(0);
;     g8_compute<0, 1>(acc, L + (kb & 1) * 32768, wm, wn, lane);
;     __builtin_amdgcn_sched_barrier(0);
;     g8_store1(L + ((kb + 1) & 1) * 32768 + 16384, rb, lrow, lch);
;     g8_load1o(rb, b + (kb + 2) * 64, offb);
;     __builtin_amdgcn_sched_barrier(0);
;     g8_compute<1, 2>(acc, L + (kb & 1) * 32768, wm, wn, lane);
;   }
.Lstg_942_a:
	s_waitcnt vmcnt(5)
	ds_write_b128 v167, v[22:25]
	ds_write_b128 v167, v[18:21] offset:8192
	ds_write_b128 v167, v[26:29] offset:16384
	s_waitcnt vmcnt(4)
	ds_write_b128 v167, v[30:33] offset:24576
	s_add_u32 s54, s52, s0
	s_addc_u32 s55, s53, s1
	global_load_dwordx4 v[22:25], v185, s[54:55]
	global_load_dwordx4 v[26:29], v181, s[54:55]
	global_load_dwordx4 v[18:21], v183, s[54:55]
	s_nop 0
	global_load_dwordx4 v[30:33], v179, s[54:55]
	s_and_b32 s2, s2, 0x8000
	s_lshl_b32 s2, s2, 1
	s_add_i32 s2, s2, 0
	v_lshl_add_u32 v169, v191, 1, s2
	v_add_u32_e32 v222, v169, v187
	ds_read_b128 v[192:195], v222
	ds_read_b128 v[198:201], v222 offset:2048
	ds_read_b128 v[202:205], v222 offset:4096
	ds_read_b128 v[206:209], v222 offset:6144
	ds_read_b128 v[210:213], v222 offset:8192
	ds_read_b128 v[214:217], v222 offset:10240
	ds_read_b128 v[218:221], v222 offset:12288
	ds_read_b128 v[222:225], v222 offset:14336
	v_add_u32_e32 v169, v169, v186
	ds_read_b128 v[226:229], v169 offset:32768
	ds_read_b128 v[230:233], v169 offset:34816
	ds_read_b128 v[234:237], v169 offset:36864
	ds_read_b128 v[238:241], v169 offset:38912
	s_setprio 1
	s_waitcnt lgkmcnt(3)
	v_mfma_f32_16x16x32_bf16 v[158:161], v[226:229], v[192:195], v[158:161]
	s_waitcnt lgkmcnt(2)
	v_mfma_f32_16x16x32_bf16 v[154:157], v[230:233], v[192:195], v[154:157]
	s_waitcnt lgkmcnt(1)
	v_mfma_f32_16x16x32_bf16 v[150:153], v[234:237], v[192:195], v[150:153]
	s_waitcnt lgkmcnt(0)
	v_mfma_f32_16x16x32_bf16 v[146:149], v[238:241], v[192:195], v[146:149]
	v_mfma_f32_16x16x32_bf16 v[142:145], v[226:229], v[198:201], v[142:145]
	v_mfma_f32_16x16x32_bf16 v[138:141], v[230:233], v[198:201], v[138:141]
	v_mfma_f32_16x16x32_bf16 v[134:137], v[234:237], v[198:201], v[134:137]
	v_mfma_f32_16x16x32_bf16 v[130:133], v[238:241], v[198:201], v[130:133]
	v_mfma_f32_16x16x32_bf16 v[126:129], v[226:229], v[202:205], v[126:129]
	v_mfma_f32_16x16x32_bf16 v[122:125], v[230:233], v[202:205], v[122:125]
	v_mfma_f32_16x16x32_bf16 v[118:121], v[234:237], v[202:205], v[118:121]
	v_mfma_f32_16x16x32_bf16 v[114:117], v[238:241], v[202:205], v[114:117]
	v_mfma_f32_16x16x32_bf16 v[110:113], v[226:229], v[206:209], v[110:113]
	v_mfma_f32_16x16x32_bf16 v[106:109], v[230:233], v[206:209], v[106:109]
	v_mfma_f32_16x16x32_bf16 v[102:105], v[234:237], v[206:209], v[102:105]
	v_mfma_f32_16x16x32_bf16 v[98:101], v[238:241], v[206:209], v[98:101]
	v_mfma_f32_16x16x32_bf16 v[94:97], v[226:229], v[210:213], v[94:97]
	v_mfma_f32_16x16x32_bf16 v[90:93], v[230:233], v[210:213], v[90:93]
	v_mfma_f32_16x16x32_bf16 v[86:89], v[234:237], v[210:213], v[86:89]
	v_mfma_f32_16x16x32_bf16 v[82:85], v[238:241], v[210:213], v[82:85]
	v_mfma_f32_16x16x32_bf16 v[78:81], v[226:229], v[214:217], v[78:81]
	v_mfma_f32_16x16x32_bf16 v[74:77], v[230:233], v[214:217], v[74:77]
	v_mfma_f32_16x16x32_bf16 v[70:73], v[234:237], v[214:217], v[70:73]
	v_mfma_f32_16x16x32_bf16 v[66:69], v[238:241], v[214:217], v[66:69]
	v_mfma_f32_16x16x32_bf16 v[62:65], v[226:229], v[218:221], v[62:65]
	v_mfma_f32_16x16x32_bf16 v[58:61], v[230:233], v[218:221], v[58:61]
	v_mfma_f32_16x16x32_bf16 v[54:57], v[234:237], v[218:221], v[54:57]
	v_mfma_f32_16x16x32_bf16 v[50:53], v[238:241], v[218:221], v[50:53]
	v_mfma_f32_16x16x32_bf16 v[46:49], v[226:229], v[222:225], v[46:49]
	v_mfma_f32_16x16x32_bf16 v[42:45], v[230:233], v[222:225], v[42:45]
	v_mfma_f32_16x16x32_bf16 v[38:41], v[234:237], v[222:225], v[38:41]
	v_mfma_f32_16x16x32_bf16 v[34:37], v[238:241], v[222:225], v[34:37]
	s_setprio 0
	s_waitcnt vmcnt(7)
	ds_write_b128 v167, v[14:17] offset:32768
	s_waitcnt vmcnt(6)
	ds_write_b128 v167, v[2:5] offset:40960
	s_waitcnt vmcnt(5)
	ds_write_b128 v167, v[6:9] offset:49152
	s_waitcnt vmcnt(4)
	ds_write_b128 v167, v[10:13] offset:57344
	s_add_u32 s58, s56, s0
	s_addc_u32 s59, s57, s1
	global_load_dwordx4 v[14:17], v177, s[58:59]
	s_nop 0
	global_load_dwordx4 v[2:5], v175, s[58:59]
	s_nop 0
	global_load_dwordx4 v[6:9], v173, s[58:59]
	s_nop 0
	global_load_dwordx4 v[10:13], v171, s[58:59]
	v_lshl_add_u32 v167, v188, 1, s2
	v_add_u32_e32 v169, v167, v187
	ds_read_b128 v[192:195], v169
	ds_read_b128 v[198:201], v169 offset:2048
	ds_read_b128 v[202:205], v169 offset:4096
	ds_read_b128 v[206:209], v169 offset:6144
	ds_read_b128 v[210:213], v169 offset:8192
	ds_read_b128 v[214:217], v169 offset:10240
	ds_read_b128 v[218:221], v169 offset:12288
	ds_read_b128 v[222:225], v169 offset:14336
	v_add_u32_e32 v167, v167, v186
	ds_read_b128 v[226:229], v167 offset:32768
	ds_read_b128 v[230:233], v167 offset:34816
	ds_read_b128 v[234:237], v167 offset:36864
	ds_read_b128 v[238:241], v167 offset:38912
	s_cmp_lg_u32 s101, 0
	s_cbranch_scc1 .Lstg_942_b
; DI f32x4 mfma16(bf16x8 a, bf16x8 b, f32x4 c) { return __builtin_amdgcn_mfma_f32_16x16x32_bf16(a, b, c, 0, 0, 0); }
;     ...
; #pragma unroll
;     for (int j = 0; j < 4; ++j) {
;       const int r = wn * 64 + j * 16 + (lane & 15);
;       bfr[j] = *(const bf16x8*)(S + 16384 + r * 64 + (((ks * 4 + (lane >> 4)) ^ ((r >> 1) & 7)) << 3));
;     }
;     __builtin_amdgcn_s_setprio(1);
; #pragma unroll
;     for (int i = 0; i < 8; ++i)
; #pragma unroll
;       for (int j = 0; j < 4; ++j) acc[i][j] = mfma16(bfr[j], af[i], acc[i][j]);
;     __builtin_amdgcn_s_setprio(0);
	s_setprio 1
	s_waitcnt lgkmcnt(3)
	v_mfma_f32_16x16x32_bf16 v[158:161], v[226:229], v[192:195], v[158:161]
	s_waitcnt lgkmcnt(2)
	v_mfma_f32_16x16x32_bf16 v[154:157], v[230:233], v[192:195], v[154:157]
	s_waitcnt lgkmcnt(1)
	v_mfma_f32_16x16x32_bf16 v[150:153], v[234:237], v[192:195], v[150:153]
	s_waitcnt lgkmcnt(0)
	v_mfma_f32_16x16x32_bf16 v[146:149], v[238:241], v[192:195], v[146:149]
	v_mfma_f32_16x16x32_bf16 v[142:145], v[226:229], v[198:201], v[142:145]
	v_mfma_f32_16x16x32_bf16 v[138:141], v[230:233], v[198:201], v[138:141]
	v_mfma_f32_16x16x32_bf16 v[134:137], v[234:237], v[198:201], v[134:137]
	v_mfma_f32_16x16x32_bf16 v[130:133], v[238:241], v[198:201], v[130:133]
	v_mfma_f32_16x16x32_bf16 v[126:129], v[226:229], v[202:205], v[126:129]
	v_mfma_f32_16x16x32_bf16 v[122:125], v[230:233], v[202:205], v[122:125]
	v_mfma_f32_16x16x32_bf16 v[118:121], v[234:237], v[202:205], v[118:121]
	v_mfma_f32_16x16x32_bf16 v[114:117], v[238:241], v[202:205], v[114:117]
	v_mfma_f32_16x16x32_bf16 v[110:113], v[226:229], v[206:209], v[110:113]
	v_mfma_f32_16x16x32_bf16 v[106:109], v[230:233], v[206:209], v[106:109]
	v_mfma_f32_16x16x32_bf16 v[102:105], v[234:237], v[206:209], v[102:105]
	v_mfma_f32_16x16x32_bf16 v[98:101], v[238:241], v[206:209], v[98:101]
	v_mfma_f32_16x16x32_bf16 v[94:97], v[226:229], v[210:213], v[94:97]
	v_mfma_f32_16x16x32_bf16 v[90:93], v[230:233], v[210:213], v[90:93]
	v_mfma_f32_16x16x32_bf16 v[86:89], v[234:237], v[210:213], v[86:89]
	v_mfma_f32_16x16x32_bf16 v[82:85], v[238:241], v[210:213], v[82:85]
	v_mfma_f32_16x16x32_bf16 v[78:81], v[226:229], v[214:217], v[78:81]
	v_mfma_f32_16x16x32_bf16 v[74:77], v[230:233], v[214:217], v[74:77]
	v_mfma_f32_16x16x32_bf16 v[70:73], v[234:237], v[214:217], v[70:73]
	v_mfma_f32_16x16x32_bf16 v[66:69], v[238:241], v[214:217], v[66:69]
	v_mfma_f32_16x16x32_bf16 v[62:65], v[226:229], v[218:221], v[62:65]
	v_mfma_f32_16x16x32_bf16 v[58:61], v[230:233], v[218:221], v[58:61]
	v_mfma_f32_16x16x32_bf16 v[54:57], v[234:237], v[218:221], v[54:57]
	v_mfma_f32_16x16x32_bf16 v[50:53], v[238:241], v[218:221], v[50:53]
	v_mfma_f32_16x16x32_bf16 v[46:49], v[226:229], v[222:225], v[46:49]
	v_mfma_f32_16x16x32_bf16 v[42:45], v[230:233], v[222:225], v[42:45]
	v_mfma_f32_16x16x32_bf16 v[38:41], v[234:237], v[222:225], v[38:41]
	v_mfma_f32_16x16x32_bf16 v[34:37], v[238:241], v[222:225], v[34:37]
	s_setprio 0

; template <class F>
; DI void gemm8_epi_staged(f32x4 (&acc)[8][4], int m0, int n0, bf16_t* L0, F f, bf16_t* dst, size_t ld, int nmax) {
;     ...
; #pragma unroll
;     for (int it = 0; it < 8; ++it) {
;       const int idx = tid + 512 * it;
;       const int row = idx >> 5, ch = idx & 31;
;       const u32x4 v = *(const u32x4*)(L + row * 264 + ch * 8);
;       const int n = n0 + ch * 8;
;       if (n < nmax) *(u32x4*)(dst + (size_t)(m0 + half * 128 + row) * ld + n) = v;
;     }
;     __syncthreads();
.LBB0_1006:
	s_or_b64 exec, exec, s[4:5]
	s_and_b32 s5, s10, 0x60
	v_readlane_b32 s6, v252, 25
	s_or_b32 s5, s6, s5
	s_and_b32 s6, s9, 3
	s_add_i32 s5, s5, s6
	s_waitcnt lgkmcnt(0)
	s_barrier
	s_or_b32 s6, s13, 0x80
	ds_read_b128 v[2:5], v77
	v_add_u32_e32 v6, s6, v0
	v_ashrrev_i32_e32 v7, 31, v6
	v_lshlrev_b64 v[6:7], 11, v[6:7]
	v_lshl_add_u64 v[10:11], v[66:67], 0, v[6:7]
	ds_read_b128 v[6:9], v79
	s_waitcnt lgkmcnt(1)
	global_store_dwordx4 v[10:11], v[2:5], off
	v_mov_b32_e32 v26, v196
	s_lshl_b32 s4, s11, 11
	v_add_u32_e32 v2, s6, v78
	v_ashrrev_i32_e32 v3, 31, v2
	v_lshlrev_b64 v[2:3], 11, v[2:3]
	v_lshl_add_u64 v[2:3], v[66:67], 0, v[2:3]
	s_waitcnt lgkmcnt(0)
	global_store_dwordx4 v[2:3], v[6:9], off
	ds_read_b128 v[2:5], v81
	s_and_b32 s4, s4, 0x180000
	v_add_u32_e32 v6, s6, v80
	v_ashrrev_i32_e32 v7, 31, v6
	v_lshlrev_b64 v[6:7], 11, v[6:7]
	v_lshl_add_u64 v[10:11], v[66:67], 0, v[6:7]
	ds_read_b128 v[6:9], v83
	s_waitcnt lgkmcnt(1)
	global_store_dwordx4 v[10:11], v[2:5], off
	s_lshl_b32 s5, s5, 19
	s_nop 0
	v_add_u32_e32 v2, s6, v82
	v_ashrrev_i32_e32 v3, 31, v2
	v_lshlrev_b64 v[2:3], 11, v[2:3]
	v_lshl_add_u64 v[2:3], v[66:67], 0, v[2:3]
	s_waitcnt lgkmcnt(0)
	global_store_dwordx4 v[2:3], v[6:9], off
	ds_read_b128 v[2:5], v85
	s_nop 0
	v_add_u32_e32 v6, s6, v84
	v_ashrrev_i32_e32 v7, 31, v6
	v_lshlrev_b64 v[6:7], 11, v[6:7]
	v_lshl_add_u64 v[10:11], v[66:67], 0, v[6:7]
	ds_read_b128 v[6:9], v87
	s_waitcnt lgkmcnt(1)
	global_store_dwordx4 v[10:11], v[2:5], off
	s_nop 1
	v_add_u32_e32 v2, s6, v86
	v_ashrrev_i32_e32 v3, 31, v2
	v_lshlrev_b64 v[2:3], 11, v[2:3]
	v_lshl_add_u64 v[2:3], v[66:67], 0, v[2:3]
	s_waitcnt lgkmcnt(0)
	global_store_dwordx4 v[2:3], v[6:9], off
	ds_read_b128 v[2:5], v89
	s_nop 0
	v_add_u32_e32 v6, s6, v88
	v_ashrrev_i32_e32 v7, 31, v6
	v_lshlrev_b64 v[6:7], 11, v[6:7]
	v_lshl_add_u64 v[10:11], v[66:67], 0, v[6:7]
	ds_read_b128 v[6:9], v91
	s_waitcnt lgkmcnt(1)
	global_store_dwordx4 v[10:11], v[2:5], off
	s_nop 1
	v_add_u32_e32 v2, s6, v90
	v_ashrrev_i32_e32 v3, 31, v2
	v_lshlrev_b64 v[2:3], 11, v[2:3]
	v_lshl_add_u64 v[2:3], v[66:67], 0, v[2:3]
	s_waitcnt lgkmcnt(0)
	global_store_dwordx4 v[2:3], v[6:9], off
	s_barrier
; DI int TID8() { int t = threadIdx.x; asm volatile("" : "+v"(t)); return t; }
; DI void gemm8_accum(f32x4 (&acc)[8][4], const bf16_t* a, size_t lda, const bf16_t* b, size_t ldb, int nkb, bf16_t* L,
;                     const bool pre, const bf16_t* an, size_t ldan, const bf16_t* bn, size_t ldbn) {
;   const int tid = TID8(), lane = tid & 63, w = tid >> 6;
;   const int wm = w >> 2, wn = w & 3;
;   const int lrow = tid >> 3, lch = tid & 7;
;   u32x4 ra[4], rb[4];
;   unsigned offa[4], offb[4];
; #pragma unroll
;   for (int i = 0; i < 4; ++i) {
;     offa[i] = (unsigned)(lrow + 64 * i) * (unsigned)lda + (unsigned)(lch * 8);
;     offb[i] = (unsigned)(lrow + 64 * i) * (unsigned)ldb + (unsigned)(lch * 8);
;   }
;   if (!pre) {
;     g8_load1o(ra, a, offa);
;     g8_load1o(rb, b, offb);
;     __syncthreads();
;     g8_store(L, ra, rb, lrow, lch);
;   }
;   g8_load1o(ra, a + 64, offa);
;   g8_load1o(rb, b + 64, offb);
; DI void zero_acc8(f32x4 (&acc)[8][4]) {
; #pragma unroll
;   for (int i = 0; i < 8; ++i)
; #pragma unroll
;     for (int j = 0; j < 4; ++j) acc[i][j] = f32x4{0.f, 0.f, 0.f, 0.f};
; }
	v_mov_b32_e32 v3, v1
	v_ashrrev_i32_e32 v189, 3, v26
	v_lshlrev_b32_e32 v0, 3, v26
	v_and_b32_e32 v184, 56, v0
	v_add_u32_e32 v188, 64, v189
	v_lshrrev_b32_e32 v8, 1, v189
	v_lshl_or_b32 v0, v189, 10, v184
	v_lshl_or_b32 v2, v188, 10, v184
	v_add_u32_e32 v187, 0x80, v189
	v_add_u32_e32 v185, 0xc0, v189
	v_xor_b32_e32 v8, v8, v26
	v_lshl_or_b32 v4, v187, 10, v184
	v_lshl_or_b32 v6, v185, 10, v184
	v_mov_b32_e32 v5, v1
	v_mov_b32_e32 v7, v1
	v_lshlrev_b32_e32 v8, 3, v8
	v_lshlrev_b64 v[18:19], 1, v[0:1]
	v_lshlrev_b64 v[20:21], 1, v[2:3]
	v_and_b32_e32 v27, 56, v8
	v_lshl_add_u64 v[8:9], s[2:3], 0, v[18:19]
	v_lshl_add_u64 v[2:3], s[2:3], 0, v[20:21]
	v_lshlrev_b64 v[22:23], 1, v[4:5]
	v_lshlrev_b64 v[24:25], 1, v[6:7]
	global_load_dwordx4 v[34:37], v[8:9], off offset:128
	global_load_dwordx4 v[42:45], v[2:3], off offset:128
	v_lshl_add_u64 v[2:3], s[2:3], 0, v[22:23]
	v_lshl_add_u64 v[4:5], s[2:3], 0, v[24:25]
	global_load_dwordx4 v[54:57], v[2:3], off offset:128
	global_load_dwordx4 v[94:97], v[4:5], off offset:128
	v_lshl_add_u64 v[2:3], s[0:1], 0, v[18:19]
	v_lshl_add_u64 v[4:5], s[0:1], 0, v[20:21]
	v_lshl_add_u64 v[6:7], s[0:1], 0, v[22:23]
	v_lshl_add_u64 v[10:11], s[0:1], 0, v[24:25]
	global_load_dwordx4 v[14:17], v[2:3], off offset:128
	s_nop 0
	global_load_dwordx4 v[2:5], v[4:5], off offset:128
	s_nop 0
	global_load_dwordx4 v[6:9], v[6:7], off offset:128
	s_nop 0
	global_load_dwordx4 v[10:13], v[10:11], off offset:128
	v_bfe_u32 v0, v26, 4, 2
	v_lshrrev_b32_e32 v28, 1, v26
	v_bitop3_b32 v28, v28, v0, 7 bitop3:0x6c
	v_lshlrev_b32_e32 v186, 3, v28
	v_lshlrev_b32_e32 v28, 5, v26
	v_bfe_u32 v29, v26, 1, 3
	v_and_b32_e32 v28, 0xffffe000, v28
	v_lshlrev_b32_e32 v26, 6, v26
	s_movk_i32 s0, 0x3c0
	v_and_or_b32 v28, v26, s0, v28
	v_readlane_b32 s0, v254, 34
	s_add_u32 s0, s0, s4
	v_readlane_b32 s1, v254, 35
	s_addc_u32 s1, s1, 0
	v_bitop3_b32 v0, v0, v29, 4 bitop3:0x36
	v_lshl_add_u64 v[164:165], s[0:1], 0, v[24:25]
	v_lshl_add_u64 v[166:167], s[0:1], 0, v[22:23]
	v_lshl_add_u64 v[168:169], s[0:1], 0, v[20:21]
	v_lshl_add_u64 v[170:171], s[0:1], 0, v[18:19]
	v_readlane_b32 s0, v253, 57
	s_add_u32 s0, s0, s5
	v_readlane_b32 s1, v253, 58
	s_addc_u32 s1, s1, 0
	v_and_b32_e32 v26, 0x33c0, v26
	v_lshlrev_b32_e32 v182, 3, v0
	v_lshlrev_b32_e32 v183, 1, v27
	v_lshlrev_b32_e32 v0, 7, v189
	v_lshl_add_u64 v[178:179], s[0:1], 0, v[18:19]
	v_mov_b32_e32 v18, 0
	v_lshlrev_b32_e32 v190, 6, v189
	v_add3_u32 v163, 0, v183, v0
	v_lshl_add_u64 v[172:173], s[0:1], 0, v[24:25]
	v_lshl_add_u64 v[174:175], s[0:1], 0, v[22:23]
	v_lshl_add_u64 v[176:177], s[0:1], 0, v[20:21]
	s_mov_b64 s[0:1], 0
	s_mov_b32 s2, 0
	v_lshlrev_b32_e32 v181, 1, v28
	v_lshlrev_b32_e32 v180, 1, v26
	v_mov_b32_e32 v19, v18
	v_mov_b32_e32 v20, v18
	v_mov_b32_e32 v21, v18
	v_mov_b32_e32 v22, v18
	v_mov_b32_e32 v23, v18
	v_mov_b32_e32 v24, v18
	v_mov_b32_e32 v25, v18
	v_mov_b32_e32 v26, v18
	v_mov_b32_e32 v27, v18
	v_mov_b32_e32 v28, v18
	v_mov_b32_e32 v29, v18
	v_mov_b32_e32 v30, v18
	v_mov_b32_e32 v31, v18
	v_mov_b32_e32 v32, v18
	v_mov_b32_e32 v33, v18
	v_mov_b32_e32 v38, v18
	v_mov_b32_e32 v39, v18
	v_mov_b32_e32 v40, v18
	v_mov_b32_e32 v41, v18
	v_mov_b32_e32 v46, v18
	v_mov_b32_e32 v47, v18
	v_mov_b32_e32 v48, v18
	v_mov_b32_e32 v49, v18
	v_mov_b32_e32 v50, v18
	v_mov_b32_e32 v51, v18
	v_mov_b32_e32 v52, v18
	v_mov_b32_e32 v53, v18
	v_mov_b32_e32 v58, v18
	v_mov_b32_e32 v59, v18
	v_mov_b32_e32 v60, v18
	v_mov_b32_e32 v61, v18
	v_mov_b32_e32 v62, v18
	v_mov_b32_e32 v63, v18
	v_mov_b32_e32 v64, v18
	v_mov_b32_e32 v65, v18
	v_mov_b32_e32 v66, v18
	v_mov_b32_e32 v67, v18
	v_mov_b32_e32 v68, v18
	v_mov_b32_e32 v69, v18
	v_mov_b32_e32 v70, v18
	v_mov_b32_e32 v71, v18
	v_mov_b32_e32 v72, v18
	v_mov_b32_e32 v73, v18
	v_mov_b32_e32 v74, v18
	v_mov_b32_e32 v75, v18
	v_mov_b32_e32 v76, v18
	v_mov_b32_e32 v77, v18
	v_mov_b32_e32 v78, v18
	v_mov_b32_e32 v79, v18
	v_mov_b32_e32 v80, v18
	v_mov_b32_e32 v81, v18
	v_mov_b32_e32 v82, v18
	v_mov_b32_e32 v83, v18
	v_mov_b32_e32 v84, v18
	v_mov_b32_e32 v85, v18
	v_mov_b32_e32 v86, v18
	v_mov_b32_e32 v87, v18
	v_mov_b32_e32 v88, v18
	v_mov_b32_e32 v89, v18
	v_mov_b32_e32 v90, v18
	v_mov_b32_e32 v91, v18
	v_mov_b32_e32 v92, v18
	v_mov_b32_e32 v93, v18
	v_mov_b32_e32 v98, v18
	v_mov_b32_e32 v99, v18
	v_mov_b32_e32 v100, v18
	v_mov_b32_e32 v101, v18
	v_mov_b32_e32 v102, v18
	v_mov_b32_e32 v103, v18
	v_mov_b32_e32 v104, v18
	v_mov_b32_e32 v105, v18
	v_mov_b32_e32 v106, v18
	v_mov_b32_e32 v107, v18
	v_mov_b32_e32 v108, v18
	v_mov_b32_e32 v109, v18
	v_mov_b32_e32 v110, v18
	v_mov_b32_e32 v111, v18
	v_mov_b32_e32 v112, v18
	v_mov_b32_e32 v113, v18
	v_mov_b32_e32 v114, v18
	v_mov_b32_e32 v115, v18
	v_mov_b32_e32 v116, v18
	v_mov_b32_e32 v117, v18
	v_mov_b32_e32 v118, v18
	v_mov_b32_e32 v119, v18
	v_mov_b32_e32 v120, v18
	v_mov_b32_e32 v121, v18
	v_mov_b32_e32 v122, v18
	v_mov_b32_e32 v123, v18
	v_mov_b32_e32 v124, v18
	v_mov_b32_e32 v125, v18
	v_mov_b32_e32 v126, v18
	v_mov_b32_e32 v127, v18
	v_mov_b32_e32 v128, v18
	v_mov_b32_e32 v129, v18
	v_mov_b32_e32 v130, v18
	v_mov_b32_e32 v131, v18
	v_mov_b32_e32 v132, v18
	v_mov_b32_e32 v133, v18
	v_mov_b32_e32 v134, v18
	v_mov_b32_e32 v135, v18
	v_mov_b32_e32 v136, v18
	v_mov_b32_e32 v137, v18
	v_mov_b32_e32 v138, v18
	v_mov_b32_e32 v139, v18
	v_mov_b32_e32 v140, v18
	v_mov_b32_e32 v141, v18
	v_mov_b32_e32 v142, v18
	v_mov_b32_e32 v143, v18
	v_mov_b32_e32 v144, v18
	v_mov_b32_e32 v145, v18
	v_mov_b32_e32 v146, v18
	v_mov_b32_e32 v147, v18
	v_mov_b32_e32 v148, v18
	v_mov_b32_e32 v149, v18
	v_mov_b32_e32 v150, v18
	v_mov_b32_e32 v151, v18
	v_mov_b32_e32 v152, v18
	v_mov_b32_e32 v153, v18
	v_mov_b32_e32 v154, v18
	v_mov_b32_e32 v155, v18
	v_mov_b32_e32 v156, v18
	v_mov_b32_e32 v157, v18
	v_mov_b32_e32 v158, v18
	v_mov_b32_e32 v159, v18
	v_mov_b32_e32 v160, v18
	v_mov_b32_e32 v161, v18
	v_readfirstlane_b32 s52, v178
	v_readfirstlane_b32 s53, v179
	s_sub_u32 s52, s52, 0x40000000
	s_subb_u32 s53, s53, 0
	v_readfirstlane_b32 s56, v170
	v_readfirstlane_b32 s57, v171
	s_sub_u32 s56, s56, 0x40000000
	s_subb_u32 s57, s57, 0
	v_subrev_u32_e32 v179, s52, v178
	v_subrev_u32_e32 v177, s52, v176
	v_subrev_u32_e32 v175, s52, v174
	v_subrev_u32_e32 v173, s52, v172
	v_subrev_u32_e32 v171, s56, v170
	v_subrev_u32_e32 v169, s56, v168
	v_subrev_u32_e32 v167, s56, v166
	v_subrev_u32_e32 v165, s56, v164

; DI f32x4 mfma16(bf16x8 a, bf16x8 b, f32x4 c) { return __builtin_amdgcn_mfma_f32_16x16x32_bf16(a, b, c, 0, 0, 0); }
; #pragma unroll
;   for (int ks = KS0; ks < KS1; ++ks) {
;     bf16x8 af[8], bfr[4];
; #pragma unroll
;     for (int i = 0; i < 8; ++i) {
;       const int r = wm * 128 + i * 16 + (lane & 15);
;       af[i] = *(const bf16x8*)(S + r * 64 + (((ks * 4 + (lane >> 4)) ^ ((r >> 1) & 7)) << 3));
;     }
; #pragma unroll
;     for (int j = 0; j < 4; ++j) {
;       const int r = wn * 64 + j * 16 + (lane & 15);
;       bfr[j] = *(const bf16x8*)(S + 16384 + r * 64 + (((ks * 4 + (lane >> 4)) ^ ((r >> 1) & 7)) << 3));
;     }
;     __builtin_amdgcn_s_setprio(1);
; #pragma unroll
;     for (int i = 0; i < 8; ++i)
; #pragma unroll
;       for (int j = 0; j < 4; ++j) acc[i][j] = mfma16(bfr[j], af[i], acc[i][j]);
;     __builtin_amdgcn_s_setprio(0);
;   }
; }
; DI void gemm8_accum(f32x4 (&acc)[8][4], const bf16_t* a, size_t lda, const bf16_t* b, size_t ldb, int nkb, bf16_t* L,
;                     const bool pre, const bf16_t* an, size_t ldan, const bf16_t* bn, size_t ldbn) {
;     ...
;   for (int kb = 0; kb + 2 < nkb; ++kb) {
;     __syncthreads();
;     g8_store1(L + ((kb + 1) & 1) * 32768, ra, lrow, lch);
;     g8_load1o(ra, a + (kb + 2) * 64, offa);
;     __builtin_amdgcn_sched_barrier(0);
;     g8_compute<0, 1>(acc, L + (kb & 1) * 32768, wm, wn, lane);
;     __builtin_amdgcn_sched_barrier(0);
;     g8_store1(L + ((kb + 1) & 1) * 32768 + 16384, rb, lrow, lch);
;     g8_load1o(rb, b + (kb + 2) * 64, offb);
;     __builtin_amdgcn_sched_barrier(0);
;     g8_compute<1, 2>(acc, L + (kb & 1) * 32768, wm, wn, lane);
;   }
.Lstg_1007_a:
	s_waitcnt vmcnt(7)
	ds_write_b128 v0, v[34:37]
	s_waitcnt vmcnt(6)
	ds_write_b128 v0, v[42:45] offset:8192
	s_waitcnt vmcnt(5)
	ds_write_b128 v0, v[54:57] offset:16384
	s_waitcnt vmcnt(4)
	ds_write_b128 v0, v[94:97] offset:24576
	s_add_u32 s54, s52, s0
	s_addc_u32 s55, s53, s1
	global_load_dwordx4 v[34:37], v179, s[54:55]
	s_nop 0
	global_load_dwordx4 v[42:45], v177, s[54:55]
	s_nop 0
	global_load_dwordx4 v[54:57], v175, s[54:55]
	s_nop 0
	global_load_dwordx4 v[94:97], v173, s[54:55]
	s_and_b32 s2, s2, 0x8000
	s_lshl_b32 s2, s2, 1
	s_add_i32 s2, s2, 0
	v_lshl_add_u32 v191, v186, 1, s2
	v_add_u32_e32 v222, v191, v181
	ds_read_b128 v[192:195], v222
	ds_read_b128 v[198:201], v222 offset:2048
	ds_read_b128 v[202:205], v222 offset:4096
	ds_read_b128 v[206:209], v222 offset:6144
	ds_read_b128 v[210:213], v222 offset:8192
	ds_read_b128 v[214:217], v222 offset:10240
	ds_read_b128 v[218:221], v222 offset:12288
	ds_read_b128 v[222:225], v222 offset:14336
	v_add_u32_e32 v191, v191, v180
	ds_read_b128 v[226:229], v191 offset:32768
	ds_read_b128 v[230:233], v191 offset:34816
	ds_read_b128 v[234:237], v191 offset:36864
	ds_read_b128 v[238:241], v191 offset:38912
	s_setprio 1
	s_waitcnt lgkmcnt(3)
	v_mfma_f32_16x16x32_bf16 v[158:161], v[226:229], v[192:195], v[158:161]
	s_waitcnt lgkmcnt(2)
	v_mfma_f32_16x16x32_bf16 v[154:157], v[230:233], v[192:195], v[154:157]
	s_waitcnt lgkmcnt(1)
	v_mfma_f32_16x16x32_bf16 v[150:153], v[234:237], v[192:195], v[150:153]
	s_waitcnt lgkmcnt(0)
	v_mfma_f32_16x16x32_bf16 v[146:149], v[238:241], v[192:195], v[146:149]
	v_mfma_f32_16x16x32_bf16 v[142:145], v[226:229], v[198:201], v[142:145]
	v_mfma_f32_16x16x32_bf16 v[138:141], v[230:233], v[198:201], v[138:141]
	v_mfma_f32_16x16x32_bf16 v[134:137], v[234:237], v[198:201], v[134:137]
	v_mfma_f32_16x16x32_bf16 v[130:133], v[238:241], v[198:201], v[130:133]
	v_mfma_f32_16x16x32_bf16 v[126:129], v[226:229], v[202:205], v[126:129]
	v_mfma_f32_16x16x32_bf16 v[122:125], v[230:233], v[202:205], v[122:125]
	v_mfma_f32_16x16x32_bf16 v[118:121], v[234:237], v[202:205], v[118:121]
	v_mfma_f32_16x16x32_bf16 v[114:117], v[238:241], v[202:205], v[114:117]
	v_mfma_f32_16x16x32_bf16 v[110:113], v[226:229], v[206:209], v[110:113]
	v_mfma_f32_16x16x32_bf16 v[106:109], v[230:233], v[206:209], v[106:109]
	v_mfma_f32_16x16x32_bf16 v[102:105], v[234:237], v[206:209], v[102:105]
	v_mfma_f32_16x16x32_bf16 v[98:101], v[238:241], v[206:209], v[98:101]
	v_mfma_f32_16x16x32_bf16 v[90:93], v[226:229], v[210:213], v[90:93]
	v_mfma_f32_16x16x32_bf16 v[86:89], v[230:233], v[210:213], v[86:89]
	v_mfma_f32_16x16x32_bf16 v[82:85], v[234:237], v[210:213], v[82:85]
	v_mfma_f32_16x16x32_bf16 v[78:81], v[238:241], v[210:213], v[78:81]
	v_mfma_f32_16x16x32_bf16 v[74:77], v[226:229], v[214:217], v[74:77]
	v_mfma_f32_16x16x32_bf16 v[70:73], v[230:233], v[214:217], v[70:73]
	v_mfma_f32_16x16x32_bf16 v[66:69], v[234:237], v[214:217], v[66:69]
	v_mfma_f32_16x16x32_bf16 v[62:65], v[238:241], v[214:217], v[62:65]
	v_mfma_f32_16x16x32_bf16 v[58:61], v[226:229], v[218:221], v[58:61]
	v_mfma_f32_16x16x32_bf16 v[50:53], v[230:233], v[218:221], v[50:53]
	v_mfma_f32_16x16x32_bf16 v[46:49], v[234:237], v[218:221], v[46:49]
	v_mfma_f32_16x16x32_bf16 v[38:41], v[238:241], v[218:221], v[38:41]
	v_mfma_f32_16x16x32_bf16 v[30:33], v[226:229], v[222:225], v[30:33]
	v_mfma_f32_16x16x32_bf16 v[26:29], v[230:233], v[222:225], v[26:29]
	v_mfma_f32_16x16x32_bf16 v[22:25], v[234:237], v[222:225], v[22:25]
	v_mfma_f32_16x16x32_bf16 v[18:21], v[238:241], v[222:225], v[18:21]
	s_setprio 0
	s_waitcnt vmcnt(7)
	ds_write_b128 v0, v[14:17] offset:32768
	s_waitcnt vmcnt(6)
	ds_write_b128 v0, v[2:5] offset:40960
	s_waitcnt vmcnt(5)
	ds_write_b128 v0, v[6:9] offset:49152
	s_waitcnt vmcnt(4)
	ds_write_b128 v0, v[10:13] offset:57344
	s_add_u32 s58, s56, s0
	s_addc_u32 s59, s57, s1
	global_load_dwordx4 v[14:17], v171, s[58:59]
	s_nop 0
	global_load_dwordx4 v[2:5], v169, s[58:59]
	s_nop 0
	global_load_dwordx4 v[6:9], v167, s[58:59]
	s_nop 0
	global_load_dwordx4 v[10:13], v165, s[58:59]
	v_lshl_add_u32 v0, v182, 1, s2
	v_add_u32_e32 v191, v0, v181
	ds_read_b128 v[192:195], v191
	ds_read_b128 v[198:201], v191 offset:2048
	ds_read_b128 v[202:205], v191 offset:4096
	ds_read_b128 v[206:209], v191 offset:6144
	ds_read_b128 v[210:213], v191 offset:8192
	ds_read_b128 v[214:217], v191 offset:10240
	ds_read_b128 v[218:221], v191 offset:12288
	ds_read_b128 v[222:225], v191 offset:14336
	v_add_u32_e32 v0, v0, v180
	ds_read_b128 v[226:229], v0 offset:32768
	ds_read_b128 v[230:233], v0 offset:34816
	ds_read_b128 v[234:237], v0 offset:36864
	ds_read_b128 v[238:241], v0 offset:38912
	s_cmp_lg_u32 s101, 0
	s_cbranch_scc1 .Lstg_1007_b
; DI f32x4 mfma16(bf16x8 a, bf16x8 b, f32x4 c) { return __builtin_amdgcn_mfma_f32_16x16x32_bf16(a, b, c, 0, 0, 0); }
;     ...
; #pragma unroll
;     for (int j = 0; j < 4; ++j) {
;       const int r = wn * 64 + j * 16 + (lane & 15);
;       bfr[j] = *(const bf16x8*)(S + 16384 + r * 64 + (((ks * 4 + (lane >> 4)) ^ ((r >> 1) & 7)) << 3));
;     }
;     __builtin_amdgcn_s_setprio(1);
; #pragma unroll
;     for (int i = 0; i < 8; ++i)
; #pragma unroll
;       for (int j = 0; j < 4; ++j) acc[i][j] = mfma16(bfr[j], af[i], acc[i][j]);
;     __builtin_amdgcn_s_setprio(0);
	s_setprio 1
	s_waitcnt lgkmcnt(3)
	v_mfma_f32_16x16x32_bf16 v[158:161], v[226:229], v[192:195], v[158:161]
	s_waitcnt lgkmcnt(2)
	v_mfma_f32_16x16x32_bf16 v[154:157], v[230:233], v[192:195], v[154:157]
	s_waitcnt lgkmcnt(1)
	v_mfma_f32_16x16x32_bf16 v[150:153], v[234:237], v[192:195], v[150:153]
	s_waitcnt lgkmcnt(0)
	v_mfma_f32_16x16x32_bf16 v[146:149], v[238:241], v[192:195], v[146:149]
	v_mfma_f32_16x16x32_bf16 v[142:145], v[226:229], v[198:201], v[142:145]
	v_mfma_f32_16x16x32_bf16 v[138:141], v[230:233], v[198:201], v[138:141]
	v_mfma_f32_16x16x32_bf16 v[134:137], v[234:237], v[198:201], v[134:137]
	v_mfma_f32_16x16x32_bf16 v[130:133], v[238:241], v[198:201], v[130:133]
	v_mfma_f32_16x16x32_bf16 v[126:129], v[226:229], v[202:205], v[126:129]
	v_mfma_f32_16x16x32_bf16 v[122:125], v[230:233], v[202:205], v[122:125]
	v_mfma_f32_16x16x32_bf16 v[118:121], v[234:237], v[202:205], v[118:121]
	v_mfma_f32_16x16x32_bf16 v[114:117], v[238:241], v[202:205], v[114:117]
	v_mfma_f32_16x16x32_bf16 v[110:113], v[226:229], v[206:209], v[110:113]
	v_mfma_f32_16x16x32_bf16 v[106:109], v[230:233], v[206:209], v[106:109]
	v_mfma_f32_16x16x32_bf16 v[102:105], v[234:237], v[206:209], v[102:105]
	v_mfma_f32_16x16x32_bf16 v[98:101], v[238:241], v[206:209], v[98:101]
	v_mfma_f32_16x16x32_bf16 v[90:93], v[226:229], v[210:213], v[90:93]
	v_mfma_f32_16x16x32_bf16 v[86:89], v[230:233], v[210:213], v[86:89]
	v_mfma_f32_16x16x32_bf16 v[82:85], v[234:237], v[210:213], v[82:85]
	v_mfma_f32_16x16x32_bf16 v[78:81], v[238:241], v[210:213], v[78:81]
	v_mfma_f32_16x16x32_bf16 v[74:77], v[226:229], v[214:217], v[74:77]
	v_mfma_f32_16x16x32_bf16 v[70:73], v[230:233], v[214:217], v[70:73]
	v_mfma_f32_16x16x32_bf16 v[66:69], v[234:237], v[214:217], v[66:69]
	v_mfma_f32_16x16x32_bf16 v[62:65], v[238:241], v[214:217], v[62:65]
	v_mfma_f32_16x16x32_bf16 v[58:61], v[226:229], v[218:221], v[58:61]
	v_mfma_f32_16x16x32_bf16 v[50:53], v[230:233], v[218:221], v[50:53]
	v_mfma_f32_16x16x32_bf16 v[46:49], v[234:237], v[218:221], v[46:49]
	v_mfma_f32_16x16x32_bf16 v[38:41], v[238:241], v[218:221], v[38:41]
	v_mfma_f32_16x16x32_bf16 v[30:33], v[226:229], v[222:225], v[30:33]
	v_mfma_f32_16x16x32_bf16 v[26:29], v[230:233], v[222:225], v[26:29]
	v_mfma_f32_16x16x32_bf16 v[22:25], v[234:237], v[222:225], v[22:25]
	v_mfma_f32_16x16x32_bf16 v[18:21], v[238:241], v[222:225], v[18:21]
	s_setprio 0
